# GEMM mainloops: redundant s_waitcnt lgkmcnt(0) after the segment barrier removed (waited before the barrier already)
# baseline (speedup 1.0000x reference)
; #define PG8_STAGE(bufoff, gbase, voff) do { _Pragma("unroll") for (int _i = 0; _i < 2; ++_i) \
;         __builtin_amdgcn_global_load_lds((const unsigned*)((const char*)(gbase) + (voff)[_i]), (PG8_LAS unsigned*)(lds + (bufoff) + ldsw + _i * 8192), 16, 0, 0); } while (0)
; #define PG8_LDA(dst, b, h) do { _Pragma("unroll") for (int m = 0; m < 4; ++m) _Pragma("unroll") for (int k = 0; k < 2; ++k) dst[m][k] = *(const PG8_LAS bf16x8*)(lds + PG8_SA(b, h) + aoff + m * 2048 + k * 1024); } while (0)
; #define PG8_LDB(dst, b, h) do { _Pragma("unroll") for (int n = 0; n < 2; ++n) _Pragma("unroll") for (int k = 0; k < 2; ++k) dst[n][k] = *(const PG8_LAS bf16x8*)(lds + PG8_SB(b, h) + boff + n * 2048 + k * 1024); } while (0)
; #define PG8_MMA(ai, bj, At, Bt) do { __builtin_amdgcn_s_setprio(1); _Pragma("unroll") for (int m = 0; m < 4; ++m) _Pragma("unroll") for (int n = 0; n < 2; ++n) _Pragma("unroll") for (int k = 0; k < 2; ++k) \
;         acc[ai][bj][m][n] = __builtin_amdgcn_mfma_f32_16x16x32_bf16(Bt[n][k], At[m][k], acc[ai][bj][m][n], 0, 0, 0); __builtin_amdgcn_s_setprio(0); } while (0)
; #define PG8_WAIT_V(n) asm volatile("s_waitcnt vmcnt(" #n ")" ::: "memory")
; #define PG8_WAIT_L(n) asm volatile("s_waitcnt lgkmcnt(" #n ")" ::: "memory")
; #define PG8_BAR __builtin_amdgcn_s_barrier()
; #define PG8_SCHED __builtin_amdgcn_sched_barrier(0)
; template <class Epi, class Sched, bool ALIGN_EPI = false, bool SP2 = false>
; __device__ __forceinline__ void gemm_phase(PG8_LAS unsigned char* lds, const Gemm g, const Sched& S, const Epi& E) {
;     ...
;             PG8_LDB(B0, 0, 0); PG8_LDB(B1, 0, 1); PG8_SCHED; PG8_LDA(At, 0, 0); PG8_STAGE(PG8_SA(1, 1), a1 + hstep, voffA);
;             PG8_WAIT_V(8); PG8_WAIT_L(0); PG8_BAR; PG8_MMA(0, 0, At, B0); PG8_MMA(0, 1, At, B1); PG8_BAR; PG8_SCHED;
;             PG8_LDA(At, 0, 1); PG8_STAGE(PG8_SB(0, 0), b2, voffB); PG8_STAGE(PG8_SB(0, 1), b2 + hstep, voffB); PG8_STAGE(PG8_SA(0, 0), a2, voffA);
;             PG8_WAIT_V(8); PG8_WAIT_L(0); PG8_BAR; PG8_MMA(1, 0, At, B0); PG8_MMA(1, 1, At, B1); PG8_BAR; PG8_SCHED;
.LBB0_212:
	ds_read_b128 v[144:147], v151
	ds_read_b128 v[154:157], v235
	ds_read_b128 v[158:161], v151 offset:2048
	ds_read_b128 v[162:165], v235 offset:2048
	ds_read_b128 v[166:169], v152
	ds_read_b128 v[170:173], v236
	ds_read_b128 v[174:177], v152 offset:2048
	ds_read_b128 v[178:181], v236 offset:2048
	s_add_u32 s0, s28, 0xfffc0080
	s_addc_u32 s1, s29, -1
	s_cmp_eq_u32 s64, 12
	s_cselect_b32 s35, s21, s1
	s_cselect_b32 s34, s60, s0
	s_cselect_b32 s31, s19, s63
	s_cselect_b32 s30, s61, s62
	v_lshl_add_u64 v[222:223], s[28:29], 0, v[136:137]
	s_add_i32 m0, s27, 0xc000
	ds_read_b128 v[190:193], v153
	ds_read_b128 v[194:197], v233
	ds_read_b128 v[198:201], v153 offset:2048
	ds_read_b128 v[202:205], v233 offset:2048
	ds_read_b128 v[206:209], v153 offset:4096
	ds_read_b128 v[210:213], v233 offset:4096
	ds_read_b128 v[214:217], v153 offset:6144
	ds_read_b128 v[218:221], v233 offset:6144
	global_load_lds_dwordx4 v[222:223], off
	v_lshl_add_u64 v[222:223], s[28:29], 0, v[138:139]
	s_add_i32 m0, s27, 0xe000
	s_nop 0
	global_load_lds_dwordx4 v[222:223], off
	s_waitcnt vmcnt(8)
	s_waitcnt lgkmcnt(0)
	s_barrier
	s_setprio 1
	v_mfma_f32_16x16x32_bf16 v[124:127], v[144:147], v[190:193], v[124:127]
	v_mfma_f32_16x16x32_bf16 v[120:123], v[158:161], v[190:193], v[120:123]
	v_mfma_f32_16x16x32_bf16 v[108:111], v[144:147], v[198:201], v[108:111]
	v_mfma_f32_16x16x32_bf16 v[104:107], v[158:161], v[198:201], v[104:107]
	v_mfma_f32_16x16x32_bf16 v[92:95], v[144:147], v[206:209], v[92:95]
	v_mfma_f32_16x16x32_bf16 v[88:91], v[158:161], v[206:209], v[88:91]
	v_mfma_f32_16x16x32_bf16 v[76:79], v[144:147], v[214:217], v[76:79]
	v_mfma_f32_16x16x32_bf16 v[72:75], v[158:161], v[214:217], v[72:75]
	v_mfma_f32_16x16x32_bf16 v[124:127], v[154:157], v[194:197], v[124:127]
	v_mfma_f32_16x16x32_bf16 v[120:123], v[162:165], v[194:197], v[120:123]
	v_mfma_f32_16x16x32_bf16 v[108:111], v[154:157], v[202:205], v[108:111]
	v_mfma_f32_16x16x32_bf16 v[104:107], v[162:165], v[202:205], v[104:107]
	v_mfma_f32_16x16x32_bf16 v[92:95], v[154:157], v[210:213], v[92:95]
	v_mfma_f32_16x16x32_bf16 v[88:91], v[162:165], v[210:213], v[88:91]
	v_mfma_f32_16x16x32_bf16 v[76:79], v[154:157], v[218:221], v[76:79]
	v_mfma_f32_16x16x32_bf16 v[72:75], v[162:165], v[218:221], v[72:75]
	s_setprio 0
	s_setprio 1
	v_mfma_f32_16x16x32_bf16 v[116:119], v[166:169], v[190:193], v[116:119]
	v_mfma_f32_16x16x32_bf16 v[112:115], v[174:177], v[190:193], v[112:115]
	v_mfma_f32_16x16x32_bf16 v[100:103], v[166:169], v[198:201], v[100:103]
	v_mfma_f32_16x16x32_bf16 v[96:99], v[174:177], v[198:201], v[96:99]
	v_mfma_f32_16x16x32_bf16 v[84:87], v[166:169], v[206:209], v[84:87]
	v_mfma_f32_16x16x32_bf16 v[80:83], v[174:177], v[206:209], v[80:83]
	v_mfma_f32_16x16x32_bf16 v[68:71], v[166:169], v[214:217], v[68:71]
	v_mfma_f32_16x16x32_bf16 v[64:67], v[174:177], v[214:217], v[64:67]
	v_mfma_f32_16x16x32_bf16 v[116:119], v[170:173], v[194:197], v[116:119]
	v_mfma_f32_16x16x32_bf16 v[112:115], v[178:181], v[194:197], v[112:115]
	v_mfma_f32_16x16x32_bf16 v[100:103], v[170:173], v[202:205], v[100:103]
	v_mfma_f32_16x16x32_bf16 v[96:99], v[178:181], v[202:205], v[96:99]
	v_mfma_f32_16x16x32_bf16 v[84:87], v[170:173], v[210:213], v[84:87]
	v_mfma_f32_16x16x32_bf16 v[80:83], v[178:181], v[210:213], v[80:83]
	v_mfma_f32_16x16x32_bf16 v[68:71], v[170:173], v[218:221], v[68:71]
	v_mfma_f32_16x16x32_bf16 v[64:67], v[178:181], v[218:221], v[64:67]
	s_setprio 0
	s_barrier
	s_add_i32 s0, s56, s40
	v_lshl_add_u64 v[222:223], s[30:31], 0, v[132:133]
	s_mov_b32 m0, s0
	ds_read_b128 v[190:193], v153 offset:16384
	ds_read_b128 v[194:197], v233 offset:16384
	ds_read_b128 v[198:201], v153 offset:18432
	ds_read_b128 v[202:205], v233 offset:18432
	ds_read_b128 v[206:209], v153 offset:20480
	ds_read_b128 v[210:213], v233 offset:20480
	ds_read_b128 v[214:217], v153 offset:22528
	ds_read_b128 v[218:221], v233 offset:22528
	global_load_lds_dwordx4 v[222:223], off
	s_add_i32 m0, s0, 0x2000
	s_add_u32 s0, s30, 0x40000
	v_lshl_add_u64 v[224:225], s[30:31], 0, v[128:129]
	s_addc_u32 s1, s31, 0
	s_add_i32 s2, s57, s40
	global_load_lds_dwordx4 v[224:225], off
	v_lshl_add_u64 v[226:227], s[0:1], 0, v[132:133]
	s_mov_b32 m0, s2
	v_lshl_add_u64 v[228:229], s[34:35], 0, v[130:131]
	global_load_lds_dwordx4 v[226:227], off
	v_lshl_add_u64 v[226:227], s[0:1], 0, v[128:129]
	s_add_i32 m0, s2, 0x2000
	s_nop 0
	global_load_lds_dwordx4 v[226:227], off
	v_lshl_add_u64 v[226:227], s[34:35], 0, v[134:135]
	s_mov_b32 m0, s27
	s_nop 0
	global_load_lds_dwordx4 v[226:227], off
	s_mov_b32 m0, s43
	s_nop 0
	global_load_lds_dwordx4 v[228:229], off
	s_waitcnt vmcnt(8)
	s_waitcnt lgkmcnt(0)
	s_barrier
; #define PG8_STAGE(bufoff, gbase, voff) do { _Pragma("unroll") for (int _i = 0; _i < 2; ++_i) \
;         __builtin_amdgcn_global_load_lds((const unsigned*)((const char*)(gbase) + (voff)[_i]), (PG8_LAS unsigned*)(lds + (bufoff) + ldsw + _i * 8192), 16, 0, 0); } while (0)
; #define PG8_LDA(dst, b, h) do { _Pragma("unroll") for (int m = 0; m < 4; ++m) _Pragma("unroll") for (int k = 0; k < 2; ++k) dst[m][k] = *(const PG8_LAS bf16x8*)(lds + PG8_SA(b, h) + aoff + m * 2048 + k * 1024); } while (0)
; #define PG8_LDB(dst, b, h) do { _Pragma("unroll") for (int n = 0; n < 2; ++n) _Pragma("unroll") for (int k = 0; k < 2; ++k) dst[n][k] = *(const PG8_LAS bf16x8*)(lds + PG8_SB(b, h) + boff + n * 2048 + k * 1024); } while (0)
; #define PG8_MMA(ai, bj, At, Bt) do { __builtin_amdgcn_s_setprio(1); _Pragma("unroll") for (int m = 0; m < 4; ++m) _Pragma("unroll") for (int n = 0; n < 2; ++n) _Pragma("unroll") for (int k = 0; k < 2; ++k) \
;         acc[ai][bj][m][n] = __builtin_amdgcn_mfma_f32_16x16x32_bf16(Bt[n][k], At[m][k], acc[ai][bj][m][n], 0, 0, 0); __builtin_amdgcn_s_setprio(0); } while (0)
; #define PG8_WAIT_V(n) asm volatile("s_waitcnt vmcnt(" #n ")" ::: "memory")
; #define PG8_WAIT_L(n) asm volatile("s_waitcnt lgkmcnt(" #n ")" ::: "memory")
; #define PG8_BAR __builtin_amdgcn_s_barrier()
; #define PG8_SCHED __builtin_amdgcn_sched_barrier(0)
; template <class Epi, class Sched, bool ALIGN_EPI = false, bool SP2 = false>
; __device__ __forceinline__ void gemm_phase(PG8_LAS unsigned char* lds, const Gemm g, const Sched& S, const Epi& E) {
;     ...
;             PG8_WAIT_V(8); PG8_WAIT_L(0); PG8_BAR; PG8_MMA(1, 0, At, B0); PG8_MMA(1, 1, At, B1); PG8_BAR; PG8_SCHED;
;             PG8_LDB(B0, 1, 0); PG8_LDB(B1, 1, 1); PG8_SCHED; PG8_LDA(At, 1, 0); PG8_STAGE(PG8_SA(0, 1), a2 + hstep, voffA);
;             PG8_WAIT_V(8); PG8_WAIT_L(0); PG8_BAR; PG8_MMA(0, 0, At, B0); PG8_MMA(0, 1, At, B1); PG8_BAR; PG8_SCHED;
	s_setprio 1
	v_mfma_f32_16x16x32_bf16 v[60:63], v[144:147], v[190:193], v[60:63]
	v_mfma_f32_16x16x32_bf16 v[56:59], v[158:161], v[190:193], v[56:59]
	v_mfma_f32_16x16x32_bf16 v[44:47], v[144:147], v[198:201], v[44:47]
	v_mfma_f32_16x16x32_bf16 v[40:43], v[158:161], v[198:201], v[40:43]
	v_mfma_f32_16x16x32_bf16 v[28:31], v[144:147], v[206:209], v[28:31]
	v_mfma_f32_16x16x32_bf16 v[24:27], v[158:161], v[206:209], v[24:27]
	v_mfma_f32_16x16x32_bf16 v[12:15], v[144:147], v[214:217], v[12:15]
	v_mfma_f32_16x16x32_bf16 v[8:11], v[158:161], v[214:217], v[8:11]
	v_mfma_f32_16x16x32_bf16 v[60:63], v[154:157], v[194:197], v[60:63]
	v_mfma_f32_16x16x32_bf16 v[56:59], v[162:165], v[194:197], v[56:59]
	v_mfma_f32_16x16x32_bf16 v[44:47], v[154:157], v[202:205], v[44:47]
	v_mfma_f32_16x16x32_bf16 v[40:43], v[162:165], v[202:205], v[40:43]
	v_mfma_f32_16x16x32_bf16 v[28:31], v[154:157], v[210:213], v[28:31]
	v_mfma_f32_16x16x32_bf16 v[24:27], v[162:165], v[210:213], v[24:27]
	v_mfma_f32_16x16x32_bf16 v[12:15], v[154:157], v[218:221], v[12:15]
	v_mfma_f32_16x16x32_bf16 v[8:11], v[162:165], v[218:221], v[8:11]
	s_setprio 0
	s_setprio 1
	v_mfma_f32_16x16x32_bf16 v[52:55], v[166:169], v[190:193], v[52:55]
	v_mfma_f32_16x16x32_bf16 v[48:51], v[174:177], v[190:193], v[48:51]
	v_mfma_f32_16x16x32_bf16 v[36:39], v[166:169], v[198:201], v[36:39]
	v_mfma_f32_16x16x32_bf16 v[32:35], v[174:177], v[198:201], v[32:35]
	v_mfma_f32_16x16x32_bf16 v[20:23], v[166:169], v[206:209], v[20:23]
	v_mfma_f32_16x16x32_bf16 v[16:19], v[174:177], v[206:209], v[16:19]
	v_mfma_f32_16x16x32_bf16 v[4:7], v[166:169], v[214:217], v[4:7]
	v_mfma_f32_16x16x32_bf16 v[0:3], v[174:177], v[214:217], v[0:3]
	v_mfma_f32_16x16x32_bf16 v[52:55], v[170:173], v[194:197], v[52:55]
	v_mfma_f32_16x16x32_bf16 v[48:51], v[178:181], v[194:197], v[48:51]
	v_mfma_f32_16x16x32_bf16 v[36:39], v[170:173], v[202:205], v[36:39]
	v_mfma_f32_16x16x32_bf16 v[32:35], v[178:181], v[202:205], v[32:35]
	v_mfma_f32_16x16x32_bf16 v[20:23], v[170:173], v[210:213], v[20:23]
	v_mfma_f32_16x16x32_bf16 v[16:19], v[178:181], v[210:213], v[16:19]
	v_mfma_f32_16x16x32_bf16 v[4:7], v[170:173], v[218:221], v[4:7]
	v_mfma_f32_16x16x32_bf16 v[0:3], v[178:181], v[218:221], v[0:3]
	s_setprio 0
	s_barrier
	s_add_i32 s2, 0, 0x18000
	s_add_i32 s3, 0, 0x1c000
	v_add_u32_e32 v162, s2, v149
	v_add_u32_e32 v237, s2, v234
	v_add_u32_e32 v178, s3, v149
	v_add_u32_e32 v238, s3, v234
	ds_read_b128 v[144:147], v162
	ds_read_b128 v[154:157], v237
	ds_read_b128 v[158:161], v162 offset:2048
	ds_read_b128 v[162:165], v237 offset:2048
	ds_read_b128 v[166:169], v178
	ds_read_b128 v[170:173], v238
	ds_read_b128 v[174:177], v178 offset:2048
	ds_read_b128 v[178:181], v238 offset:2048
	s_add_u32 s0, s34, 0x40000
	s_addc_u32 s1, s35, 0
	s_mov_b32 m0, s47
	v_lshl_add_u64 v[230:231], s[0:1], 0, v[134:135]
	ds_read_b128 v[190:193], v153 offset:32768
	ds_read_b128 v[194:197], v233 offset:32768
	ds_read_b128 v[198:201], v153 offset:34816
	ds_read_b128 v[202:205], v233 offset:34816
	ds_read_b128 v[206:209], v153 offset:36864
	ds_read_b128 v[210:213], v233 offset:36864
	ds_read_b128 v[214:217], v153 offset:38912
	ds_read_b128 v[218:221], v233 offset:38912
	global_load_lds_dwordx4 v[230:231], off
	v_lshl_add_u64 v[230:231], s[0:1], 0, v[130:131]
	s_mov_b32 m0, s50
	s_nop 0
	global_load_lds_dwordx4 v[230:231], off
	s_waitcnt vmcnt(8)
	s_waitcnt lgkmcnt(0)
	s_barrier
	s_setprio 1
	v_mfma_f32_16x16x32_bf16 v[124:127], v[144:147], v[190:193], v[124:127]
	v_mfma_f32_16x16x32_bf16 v[120:123], v[158:161], v[190:193], v[120:123]
	v_mfma_f32_16x16x32_bf16 v[108:111], v[144:147], v[198:201], v[108:111]
	v_mfma_f32_16x16x32_bf16 v[104:107], v[158:161], v[198:201], v[104:107]
	v_mfma_f32_16x16x32_bf16 v[92:95], v[144:147], v[206:209], v[92:95]
	v_mfma_f32_16x16x32_bf16 v[88:91], v[158:161], v[206:209], v[88:91]
	v_mfma_f32_16x16x32_bf16 v[76:79], v[144:147], v[214:217], v[76:79]
	v_mfma_f32_16x16x32_bf16 v[72:75], v[158:161], v[214:217], v[72:75]
	v_mfma_f32_16x16x32_bf16 v[124:127], v[154:157], v[194:197], v[124:127]
	v_mfma_f32_16x16x32_bf16 v[120:123], v[162:165], v[194:197], v[120:123]
	v_mfma_f32_16x16x32_bf16 v[108:111], v[154:157], v[202:205], v[108:111]
	v_mfma_f32_16x16x32_bf16 v[104:107], v[162:165], v[202:205], v[104:107]
	v_mfma_f32_16x16x32_bf16 v[92:95], v[154:157], v[210:213], v[92:95]
	v_mfma_f32_16x16x32_bf16 v[88:91], v[162:165], v[210:213], v[88:91]
	v_mfma_f32_16x16x32_bf16 v[76:79], v[154:157], v[218:221], v[76:79]
	v_mfma_f32_16x16x32_bf16 v[72:75], v[162:165], v[218:221], v[72:75]
	s_setprio 0
	s_setprio 1
	v_mfma_f32_16x16x32_bf16 v[116:119], v[166:169], v[190:193], v[116:119]
	v_mfma_f32_16x16x32_bf16 v[112:115], v[174:177], v[190:193], v[112:115]
	v_mfma_f32_16x16x32_bf16 v[100:103], v[166:169], v[198:201], v[100:103]
	v_mfma_f32_16x16x32_bf16 v[96:99], v[174:177], v[198:201], v[96:99]
	v_mfma_f32_16x16x32_bf16 v[84:87], v[166:169], v[206:209], v[84:87]
	v_mfma_f32_16x16x32_bf16 v[80:83], v[174:177], v[206:209], v[80:83]
	v_mfma_f32_16x16x32_bf16 v[68:71], v[166:169], v[214:217], v[68:71]
	v_mfma_f32_16x16x32_bf16 v[64:67], v[174:177], v[214:217], v[64:67]
	v_mfma_f32_16x16x32_bf16 v[116:119], v[170:173], v[194:197], v[116:119]
	v_mfma_f32_16x16x32_bf16 v[112:115], v[178:181], v[194:197], v[112:115]
	v_mfma_f32_16x16x32_bf16 v[100:103], v[170:173], v[202:205], v[100:103]
	v_mfma_f32_16x16x32_bf16 v[96:99], v[178:181], v[202:205], v[96:99]
	v_mfma_f32_16x16x32_bf16 v[84:87], v[170:173], v[210:213], v[84:87]
	v_mfma_f32_16x16x32_bf16 v[80:83], v[178:181], v[210:213], v[80:83]
	v_mfma_f32_16x16x32_bf16 v[68:71], v[170:173], v[218:221], v[68:71]
	v_mfma_f32_16x16x32_bf16 v[64:67], v[178:181], v[218:221], v[64:67]
	s_setprio 0
	s_barrier
; #define PG8_STAGE(bufoff, gbase, voff) do { _Pragma("unroll") for (int _i = 0; _i < 2; ++_i) \
;         __builtin_amdgcn_global_load_lds((const unsigned*)((const char*)(gbase) + (voff)[_i]), (PG8_LAS unsigned*)(lds + (bufoff) + ldsw + _i * 8192), 16, 0, 0); } while (0)
; #define PG8_LDA(dst, b, h) do { _Pragma("unroll") for (int m = 0; m < 4; ++m) _Pragma("unroll") for (int k = 0; k < 2; ++k) dst[m][k] = *(const PG8_LAS bf16x8*)(lds + PG8_SA(b, h) + aoff + m * 2048 + k * 1024); } while (0)
; #define PG8_MMA(ai, bj, At, Bt) do { __builtin_amdgcn_s_setprio(1); _Pragma("unroll") for (int m = 0; m < 4; ++m) _Pragma("unroll") for (int n = 0; n < 2; ++n) _Pragma("unroll") for (int k = 0; k < 2; ++k) \
;         acc[ai][bj][m][n] = __builtin_amdgcn_mfma_f32_16x16x32_bf16(Bt[n][k], At[m][k], acc[ai][bj][m][n], 0, 0, 0); __builtin_amdgcn_s_setprio(0); } while (0)
; #define PG8_WAIT_V(n) asm volatile("s_waitcnt vmcnt(" #n ")" ::: "memory")
; #define PG8_WAIT_L(n) asm volatile("s_waitcnt lgkmcnt(" #n ")" ::: "memory")
; #define PG8_BAR __builtin_amdgcn_s_barrier()
; #define PG8_SCHED __builtin_amdgcn_sched_barrier(0)
; template <class Epi, class Sched, bool ALIGN_EPI = false, bool SP2 = false>
; __device__ __forceinline__ void gemm_phase(PG8_LAS unsigned char* lds, const Gemm g, const Sched& S, const Epi& E) {
;     ...
;         for (int t = 0; t < nt; t += 2) {
;             const bool last = (t == nt - 2);
;     ...
;             PG8_LDA(At, 1, 1); PG8_STAGE(PG8_SB(1, 0), b3, voffB); PG8_STAGE(PG8_SB(1, 1), b3 + hstep, voffB); PG8_STAGE(PG8_SA(1, 0), a3, voffA);
;             PG8_WAIT_V(8); PG8_WAIT_L(0); PG8_BAR; PG8_MMA(1, 0, At, B0); PG8_MMA(1, 1, At, B1); PG8_BAR; PG8_SCHED;
	s_add_i32 s0, s2, s40
	v_lshl_add_u64 v[222:223], v[222:223], 0, s[14:15]
	s_mov_b32 m0, s0
	ds_read_b128 v[190:193], v153 offset:49152
	ds_read_b128 v[194:197], v233 offset:49152
	ds_read_b128 v[198:201], v153 offset:51200
	ds_read_b128 v[202:205], v233 offset:51200
	ds_read_b128 v[206:209], v153 offset:53248
	ds_read_b128 v[210:213], v233 offset:53248
	ds_read_b128 v[214:217], v153 offset:55296
	ds_read_b128 v[218:221], v233 offset:55296
	global_load_lds_dwordx4 v[222:223], off
	s_add_i32 m0, s0, 0x2000
	s_add_u32 s0, s30, 0x40080
	v_lshl_add_u64 v[222:223], v[224:225], 0, s[14:15]
	s_addc_u32 s1, s31, 0
	s_add_i32 s2, s3, s40
	global_load_lds_dwordx4 v[222:223], off
	v_lshl_add_u64 v[222:223], s[0:1], 0, v[132:133]
	s_mov_b32 m0, s2
	s_nop 0
	global_load_lds_dwordx4 v[222:223], off
	v_lshl_add_u64 v[222:223], s[0:1], 0, v[128:129]
	s_add_i32 m0, s2, 0x2000
	s_nop 0
	global_load_lds_dwordx4 v[222:223], off
	v_lshl_add_u64 v[222:223], v[226:227], 0, s[14:15]
	s_mov_b32 m0, s52
	s_nop 0
	global_load_lds_dwordx4 v[222:223], off
	v_lshl_add_u64 v[222:223], v[228:229], 0, s[14:15]
	s_mov_b32 m0, s53
	s_nop 0
	global_load_lds_dwordx4 v[222:223], off
	s_waitcnt vmcnt(8)
	s_waitcnt lgkmcnt(0)
	s_barrier
	s_setprio 1
	v_mfma_f32_16x16x32_bf16 v[60:63], v[144:147], v[190:193], v[60:63]
	v_mfma_f32_16x16x32_bf16 v[56:59], v[158:161], v[190:193], v[56:59]
	v_mfma_f32_16x16x32_bf16 v[44:47], v[144:147], v[198:201], v[44:47]
	v_mfma_f32_16x16x32_bf16 v[40:43], v[158:161], v[198:201], v[40:43]
	v_mfma_f32_16x16x32_bf16 v[28:31], v[144:147], v[206:209], v[28:31]
	v_mfma_f32_16x16x32_bf16 v[24:27], v[158:161], v[206:209], v[24:27]
	v_mfma_f32_16x16x32_bf16 v[12:15], v[144:147], v[214:217], v[12:15]
	v_mfma_f32_16x16x32_bf16 v[8:11], v[158:161], v[214:217], v[8:11]
	v_mfma_f32_16x16x32_bf16 v[60:63], v[154:157], v[194:197], v[60:63]
	v_mfma_f32_16x16x32_bf16 v[56:59], v[162:165], v[194:197], v[56:59]
	v_mfma_f32_16x16x32_bf16 v[44:47], v[154:157], v[202:205], v[44:47]
	v_mfma_f32_16x16x32_bf16 v[40:43], v[162:165], v[202:205], v[40:43]
	v_mfma_f32_16x16x32_bf16 v[28:31], v[154:157], v[210:213], v[28:31]
	v_mfma_f32_16x16x32_bf16 v[24:27], v[162:165], v[210:213], v[24:27]
	v_mfma_f32_16x16x32_bf16 v[12:15], v[154:157], v[218:221], v[12:15]
	v_mfma_f32_16x16x32_bf16 v[8:11], v[162:165], v[218:221], v[8:11]
	s_setprio 0
	s_setprio 1
	v_mfma_f32_16x16x32_bf16 v[52:55], v[166:169], v[190:193], v[52:55]
	v_mfma_f32_16x16x32_bf16 v[48:51], v[174:177], v[190:193], v[48:51]
	v_mfma_f32_16x16x32_bf16 v[36:39], v[166:169], v[198:201], v[36:39]
	v_mfma_f32_16x16x32_bf16 v[32:35], v[174:177], v[198:201], v[32:35]
	v_mfma_f32_16x16x32_bf16 v[20:23], v[166:169], v[206:209], v[20:23]
	v_mfma_f32_16x16x32_bf16 v[16:19], v[174:177], v[206:209], v[16:19]
	v_mfma_f32_16x16x32_bf16 v[4:7], v[166:169], v[214:217], v[4:7]
	v_mfma_f32_16x16x32_bf16 v[0:3], v[174:177], v[214:217], v[0:3]
	v_mfma_f32_16x16x32_bf16 v[52:55], v[170:173], v[194:197], v[52:55]
	v_mfma_f32_16x16x32_bf16 v[48:51], v[178:181], v[194:197], v[48:51]
	v_mfma_f32_16x16x32_bf16 v[36:39], v[170:173], v[202:205], v[36:39]
	v_mfma_f32_16x16x32_bf16 v[32:35], v[178:181], v[202:205], v[32:35]
	v_mfma_f32_16x16x32_bf16 v[20:23], v[170:173], v[210:213], v[20:23]
	v_mfma_f32_16x16x32_bf16 v[16:19], v[178:181], v[210:213], v[16:19]
	v_mfma_f32_16x16x32_bf16 v[4:7], v[170:173], v[218:221], v[4:7]
	v_mfma_f32_16x16x32_bf16 v[0:3], v[178:181], v[218:221], v[0:3]
	s_setprio 0
	s_barrier
	s_add_i32 s64, s64, 2
	s_add_u32 s28, s28, 0x100
	s_addc_u32 s29, s29, 0
	s_add_u32 s62, s62, 0x100
	s_addc_u32 s63, s63, 0
	s_cmp_gt_u32 s64, 13
	s_cbranch_scc0 .LBB0_212
	s_and_b64 vcc, exec, s[16:17]
	s_cbranch_vccz .LBB0_215
	s_barrier

; #define PG8_STAGE(bufoff, gbase, voff) do { _Pragma("unroll") for (int _i = 0; _i < 2; ++_i) \
;         __builtin_amdgcn_global_load_lds((const unsigned*)((const char*)(gbase) + (voff)[_i]), (PG8_LAS unsigned*)(lds + (bufoff) + ldsw + _i * 8192), 16, 0, 0); } while (0)
; #define PG8_LDA(dst, b, h) do { _Pragma("unroll") for (int m = 0; m < 4; ++m) _Pragma("unroll") for (int k = 0; k < 2; ++k) dst[m][k] = *(const PG8_LAS bf16x8*)(lds + PG8_SA(b, h) + aoff + m * 2048 + k * 1024); } while (0)
; #define PG8_LDB(dst, b, h) do { _Pragma("unroll") for (int n = 0; n < 2; ++n) _Pragma("unroll") for (int k = 0; k < 2; ++k) dst[n][k] = *(const PG8_LAS bf16x8*)(lds + PG8_SB(b, h) + boff + n * 2048 + k * 1024); } while (0)
; #define PG8_MMA(ai, bj, At, Bt) do { __builtin_amdgcn_s_setprio(1); _Pragma("unroll") for (int m = 0; m < 4; ++m) _Pragma("unroll") for (int n = 0; n < 2; ++n) _Pragma("unroll") for (int k = 0; k < 2; ++k) \
;         acc[ai][bj][m][n] = __builtin_amdgcn_mfma_f32_16x16x32_bf16(Bt[n][k], At[m][k], acc[ai][bj][m][n], 0, 0, 0); __builtin_amdgcn_s_setprio(0); } while (0)
; #define PG8_WAIT_V(n) asm volatile("s_waitcnt vmcnt(" #n ")" ::: "memory")
; #define PG8_WAIT_L(n) asm volatile("s_waitcnt lgkmcnt(" #n ")" ::: "memory")
; #define PG8_BAR __builtin_amdgcn_s_barrier()
; #define PG8_SCHED __builtin_amdgcn_sched_barrier(0)
; template <class Epi, class Sched, bool ALIGN_EPI = false, bool SP2 = false>
; __device__ __forceinline__ void gemm_phase(PG8_LAS unsigned char* lds, const Gemm g, const Sched& S, const Epi& E) {
;     ...
;             PG8_LDB(B0, 0, 0); PG8_LDB(B1, 0, 1); PG8_SCHED; PG8_LDA(At, 0, 0); PG8_STAGE(PG8_SA(1, 1), a1 + hstep, voffA);
;             PG8_WAIT_V(8); PG8_WAIT_L(0); PG8_BAR; PG8_MMA(0, 0, At, B0); PG8_MMA(0, 1, At, B1); PG8_BAR; PG8_SCHED;
;             PG8_LDA(At, 0, 1); PG8_STAGE(PG8_SB(0, 0), b2, voffB); PG8_STAGE(PG8_SB(0, 1), b2 + hstep, voffB); PG8_STAGE(PG8_SA(0, 0), a2, voffA);
;             PG8_WAIT_V(8); PG8_WAIT_L(0); PG8_BAR; PG8_MMA(1, 0, At, B0); PG8_MMA(1, 1, At, B1); PG8_BAR; PG8_SCHED;
.LBB0_303:
	ds_read_b128 v[150:153], v147
	ds_read_b128 v[154:157], v235
	ds_read_b128 v[158:161], v147 offset:2048
	ds_read_b128 v[162:165], v235 offset:2048
	ds_read_b128 v[166:169], v148
	ds_read_b128 v[170:173], v236
	ds_read_b128 v[174:177], v148 offset:2048
	ds_read_b128 v[178:181], v236 offset:2048
	s_add_u32 s34, s30, 0x100
	s_addc_u32 s35, s31, 0
	s_cmp_eq_u32 s74, 40
	s_cselect_b32 s39, s9, s35
	s_cselect_b32 s38, s8, s34
	s_cselect_b32 s37, s29, s73
	s_cselect_b32 s36, s28, s72
	v_lshl_add_u64 v[222:223], s[30:31], 0, v[136:137]
	s_add_i32 m0, s53, 0xc000
	ds_read_b128 v[190:193], v149
	ds_read_b128 v[194:197], v233
	ds_read_b128 v[198:201], v149 offset:2048
	ds_read_b128 v[202:205], v233 offset:2048
	ds_read_b128 v[206:209], v149 offset:4096
	ds_read_b128 v[210:213], v233 offset:4096
	ds_read_b128 v[214:217], v149 offset:6144
	ds_read_b128 v[218:221], v233 offset:6144
	global_load_lds_dwordx4 v[222:223], off
	v_lshl_add_u64 v[222:223], s[30:31], 0, v[138:139]
	s_add_i32 m0, s53, 0xe000
	s_nop 0
	global_load_lds_dwordx4 v[222:223], off
	s_waitcnt vmcnt(8)
	s_waitcnt lgkmcnt(0)
	s_barrier
	s_setprio 1
	v_mfma_f32_16x16x32_bf16 v[124:127], v[150:153], v[190:193], v[124:127]
	v_mfma_f32_16x16x32_bf16 v[120:123], v[158:161], v[190:193], v[120:123]
	v_mfma_f32_16x16x32_bf16 v[116:119], v[150:153], v[198:201], v[116:119]
	v_mfma_f32_16x16x32_bf16 v[112:115], v[158:161], v[198:201], v[112:115]
	v_mfma_f32_16x16x32_bf16 v[108:111], v[150:153], v[206:209], v[108:111]
	v_mfma_f32_16x16x32_bf16 v[104:107], v[158:161], v[206:209], v[104:107]
	v_mfma_f32_16x16x32_bf16 v[100:103], v[150:153], v[214:217], v[100:103]
	v_mfma_f32_16x16x32_bf16 v[96:99], v[158:161], v[214:217], v[96:99]
	v_mfma_f32_16x16x32_bf16 v[124:127], v[154:157], v[194:197], v[124:127]
	v_mfma_f32_16x16x32_bf16 v[120:123], v[162:165], v[194:197], v[120:123]
	v_mfma_f32_16x16x32_bf16 v[116:119], v[154:157], v[202:205], v[116:119]
	v_mfma_f32_16x16x32_bf16 v[112:115], v[162:165], v[202:205], v[112:115]
	v_mfma_f32_16x16x32_bf16 v[108:111], v[154:157], v[210:213], v[108:111]
	v_mfma_f32_16x16x32_bf16 v[104:107], v[162:165], v[210:213], v[104:107]
	v_mfma_f32_16x16x32_bf16 v[100:103], v[154:157], v[218:221], v[100:103]
	v_mfma_f32_16x16x32_bf16 v[96:99], v[162:165], v[218:221], v[96:99]
	s_setprio 0
	s_setprio 1
	v_mfma_f32_16x16x32_bf16 v[76:79], v[166:169], v[190:193], v[76:79]
	v_mfma_f32_16x16x32_bf16 v[68:71], v[174:177], v[190:193], v[68:71]
	v_mfma_f32_16x16x32_bf16 v[60:63], v[166:169], v[198:201], v[60:63]
	v_mfma_f32_16x16x32_bf16 v[52:55], v[174:177], v[198:201], v[52:55]
	v_mfma_f32_16x16x32_bf16 v[44:47], v[166:169], v[206:209], v[44:47]
	v_mfma_f32_16x16x32_bf16 v[40:43], v[174:177], v[206:209], v[40:43]
	v_mfma_f32_16x16x32_bf16 v[36:39], v[166:169], v[214:217], v[36:39]
	v_mfma_f32_16x16x32_bf16 v[32:35], v[174:177], v[214:217], v[32:35]
	v_mfma_f32_16x16x32_bf16 v[76:79], v[170:173], v[194:197], v[76:79]
	v_mfma_f32_16x16x32_bf16 v[68:71], v[178:181], v[194:197], v[68:71]
	v_mfma_f32_16x16x32_bf16 v[60:63], v[170:173], v[202:205], v[60:63]
	v_mfma_f32_16x16x32_bf16 v[52:55], v[178:181], v[202:205], v[52:55]
	v_mfma_f32_16x16x32_bf16 v[44:47], v[170:173], v[210:213], v[44:47]
	v_mfma_f32_16x16x32_bf16 v[40:43], v[178:181], v[210:213], v[40:43]
	v_mfma_f32_16x16x32_bf16 v[36:39], v[170:173], v[218:221], v[36:39]
	v_mfma_f32_16x16x32_bf16 v[32:35], v[178:181], v[218:221], v[32:35]
	s_setprio 0
	s_barrier
	s_add_i32 s3, s62, s52
	v_lshl_add_u64 v[222:223], s[36:37], 0, v[130:131]
	s_mov_b32 m0, s3
	ds_read_b128 v[190:193], v149 offset:16384
	ds_read_b128 v[194:197], v233 offset:16384
	ds_read_b128 v[198:201], v149 offset:18432
	ds_read_b128 v[202:205], v233 offset:18432
	ds_read_b128 v[206:209], v149 offset:20480
	ds_read_b128 v[210:213], v233 offset:20480
	ds_read_b128 v[214:217], v149 offset:22528
	ds_read_b128 v[218:221], v233 offset:22528
	global_load_lds_dwordx4 v[222:223], off
	s_add_i32 m0, s3, 0x2000
	s_add_u32 s10, s36, 0xb0000
	v_lshl_add_u64 v[224:225], s[36:37], 0, v[134:135]
	s_addc_u32 s11, s37, 0
	s_add_i32 s3, s63, s52
	global_load_lds_dwordx4 v[224:225], off
	v_lshl_add_u64 v[226:227], s[10:11], 0, v[130:131]
	s_mov_b32 m0, s3
	v_lshl_add_u64 v[228:229], s[38:39], 0, v[132:133]
	global_load_lds_dwordx4 v[226:227], off
	v_lshl_add_u64 v[226:227], s[10:11], 0, v[134:135]
	s_add_i32 m0, s3, 0x2000
	s_nop 0
	global_load_lds_dwordx4 v[226:227], off
	v_lshl_add_u64 v[226:227], s[38:39], 0, v[128:129]
	s_mov_b32 m0, s53
	s_nop 0
	global_load_lds_dwordx4 v[226:227], off
	s_mov_b32 m0, s54
	s_nop 0
	global_load_lds_dwordx4 v[228:229], off
	s_waitcnt vmcnt(8)
	s_waitcnt lgkmcnt(0)
	s_barrier
; #define PG8_STAGE(bufoff, gbase, voff) do { _Pragma("unroll") for (int _i = 0; _i < 2; ++_i) \
;         __builtin_amdgcn_global_load_lds((const unsigned*)((const char*)(gbase) + (voff)[_i]), (PG8_LAS unsigned*)(lds + (bufoff) + ldsw + _i * 8192), 16, 0, 0); } while (0)
; #define PG8_LDA(dst, b, h) do { _Pragma("unroll") for (int m = 0; m < 4; ++m) _Pragma("unroll") for (int k = 0; k < 2; ++k) dst[m][k] = *(const PG8_LAS bf16x8*)(lds + PG8_SA(b, h) + aoff + m * 2048 + k * 1024); } while (0)
; #define PG8_LDB(dst, b, h) do { _Pragma("unroll") for (int n = 0; n < 2; ++n) _Pragma("unroll") for (int k = 0; k < 2; ++k) dst[n][k] = *(const PG8_LAS bf16x8*)(lds + PG8_SB(b, h) + boff + n * 2048 + k * 1024); } while (0)
; #define PG8_MMA(ai, bj, At, Bt) do { __builtin_amdgcn_s_setprio(1); _Pragma("unroll") for (int m = 0; m < 4; ++m) _Pragma("unroll") for (int n = 0; n < 2; ++n) _Pragma("unroll") for (int k = 0; k < 2; ++k) \
;         acc[ai][bj][m][n] = __builtin_amdgcn_mfma_f32_16x16x32_bf16(Bt[n][k], At[m][k], acc[ai][bj][m][n], 0, 0, 0); __builtin_amdgcn_s_setprio(0); } while (0)
; #define PG8_WAIT_V(n) asm volatile("s_waitcnt vmcnt(" #n ")" ::: "memory")
; #define PG8_WAIT_L(n) asm volatile("s_waitcnt lgkmcnt(" #n ")" ::: "memory")
; #define PG8_BAR __builtin_amdgcn_s_barrier()
; #define PG8_SCHED __builtin_amdgcn_sched_barrier(0)
; template <class Epi, class Sched, bool ALIGN_EPI = false, bool SP2 = false>
; __device__ __forceinline__ void gemm_phase(PG8_LAS unsigned char* lds, const Gemm g, const Sched& S, const Epi& E) {
;     ...
;             PG8_WAIT_V(8); PG8_WAIT_L(0); PG8_BAR; PG8_MMA(1, 0, At, B0); PG8_MMA(1, 1, At, B1); PG8_BAR; PG8_SCHED;
;             PG8_LDB(B0, 1, 0); PG8_LDB(B1, 1, 1); PG8_SCHED; PG8_LDA(At, 1, 0); PG8_STAGE(PG8_SA(0, 1), a2 + hstep, voffA);
;             PG8_WAIT_V(8); PG8_WAIT_L(0); PG8_BAR; PG8_MMA(0, 0, At, B0); PG8_MMA(0, 1, At, B1); PG8_BAR; PG8_SCHED;
	s_setprio 1
	v_mfma_f32_16x16x32_bf16 v[92:95], v[150:153], v[190:193], v[92:95]
	v_mfma_f32_16x16x32_bf16 v[88:91], v[158:161], v[190:193], v[88:91]
	v_mfma_f32_16x16x32_bf16 v[84:87], v[150:153], v[198:201], v[84:87]
	v_mfma_f32_16x16x32_bf16 v[80:83], v[158:161], v[198:201], v[80:83]
	v_mfma_f32_16x16x32_bf16 v[72:75], v[150:153], v[206:209], v[72:75]
	v_mfma_f32_16x16x32_bf16 v[64:67], v[158:161], v[206:209], v[64:67]
	v_mfma_f32_16x16x32_bf16 v[56:59], v[150:153], v[214:217], v[56:59]
	v_mfma_f32_16x16x32_bf16 v[48:51], v[158:161], v[214:217], v[48:51]
	v_mfma_f32_16x16x32_bf16 v[92:95], v[154:157], v[194:197], v[92:95]
	v_mfma_f32_16x16x32_bf16 v[88:91], v[162:165], v[194:197], v[88:91]
	v_mfma_f32_16x16x32_bf16 v[84:87], v[154:157], v[202:205], v[84:87]
	v_mfma_f32_16x16x32_bf16 v[80:83], v[162:165], v[202:205], v[80:83]
	v_mfma_f32_16x16x32_bf16 v[72:75], v[154:157], v[210:213], v[72:75]
	v_mfma_f32_16x16x32_bf16 v[64:67], v[162:165], v[210:213], v[64:67]
	v_mfma_f32_16x16x32_bf16 v[56:59], v[154:157], v[218:221], v[56:59]
	v_mfma_f32_16x16x32_bf16 v[48:51], v[162:165], v[218:221], v[48:51]
	s_setprio 0
	s_setprio 1
	v_mfma_f32_16x16x32_bf16 v[28:31], v[166:169], v[190:193], v[28:31]
	v_mfma_f32_16x16x32_bf16 v[24:27], v[174:177], v[190:193], v[24:27]
	v_mfma_f32_16x16x32_bf16 v[20:23], v[166:169], v[198:201], v[20:23]
	v_mfma_f32_16x16x32_bf16 v[16:19], v[174:177], v[198:201], v[16:19]
	v_mfma_f32_16x16x32_bf16 v[12:15], v[166:169], v[206:209], v[12:15]
	v_mfma_f32_16x16x32_bf16 v[8:11], v[174:177], v[206:209], v[8:11]
	v_mfma_f32_16x16x32_bf16 v[4:7], v[166:169], v[214:217], v[4:7]
	v_mfma_f32_16x16x32_bf16 v[0:3], v[174:177], v[214:217], v[0:3]
	v_mfma_f32_16x16x32_bf16 v[28:31], v[170:173], v[194:197], v[28:31]
	v_mfma_f32_16x16x32_bf16 v[24:27], v[178:181], v[194:197], v[24:27]
	v_mfma_f32_16x16x32_bf16 v[20:23], v[170:173], v[202:205], v[20:23]
	v_mfma_f32_16x16x32_bf16 v[16:19], v[178:181], v[202:205], v[16:19]
	v_mfma_f32_16x16x32_bf16 v[12:15], v[170:173], v[210:213], v[12:15]
	v_mfma_f32_16x16x32_bf16 v[8:11], v[178:181], v[210:213], v[8:11]
	v_mfma_f32_16x16x32_bf16 v[4:7], v[170:173], v[218:221], v[4:7]
	v_mfma_f32_16x16x32_bf16 v[0:3], v[178:181], v[218:221], v[0:3]
	s_setprio 0
	s_barrier
	s_add_i32 s3, 0, 0x18000
	s_add_i32 s30, 0, 0x1c000
	v_add_u32_e32 v162, s3, v145
	v_add_u32_e32 v237, s3, v234
	v_add_u32_e32 v178, s30, v145
	v_add_u32_e32 v238, s30, v234
	ds_read_b128 v[150:153], v162
	ds_read_b128 v[154:157], v237
	ds_read_b128 v[158:161], v162 offset:2048
	ds_read_b128 v[162:165], v237 offset:2048
	ds_read_b128 v[166:169], v178
	ds_read_b128 v[170:173], v238
	ds_read_b128 v[174:177], v178 offset:2048
	ds_read_b128 v[178:181], v238 offset:2048
	s_add_u32 s10, s38, 0xb0000
	s_addc_u32 s11, s39, 0
	s_mov_b32 m0, s55
	v_lshl_add_u64 v[230:231], s[10:11], 0, v[128:129]
	ds_read_b128 v[190:193], v149 offset:32768
	ds_read_b128 v[194:197], v233 offset:32768
	ds_read_b128 v[198:201], v149 offset:34816
	ds_read_b128 v[202:205], v233 offset:34816
	ds_read_b128 v[206:209], v149 offset:36864
	ds_read_b128 v[210:213], v233 offset:36864
	ds_read_b128 v[214:217], v149 offset:38912
	ds_read_b128 v[218:221], v233 offset:38912
	global_load_lds_dwordx4 v[230:231], off
	v_lshl_add_u64 v[230:231], s[10:11], 0, v[132:133]
	s_mov_b32 m0, s56
	s_nop 0
	global_load_lds_dwordx4 v[230:231], off
	s_waitcnt vmcnt(8)
	s_waitcnt lgkmcnt(0)
	s_barrier
	s_setprio 1
	v_mfma_f32_16x16x32_bf16 v[124:127], v[150:153], v[190:193], v[124:127]
	v_mfma_f32_16x16x32_bf16 v[120:123], v[158:161], v[190:193], v[120:123]
	v_mfma_f32_16x16x32_bf16 v[116:119], v[150:153], v[198:201], v[116:119]
	v_mfma_f32_16x16x32_bf16 v[112:115], v[158:161], v[198:201], v[112:115]
	v_mfma_f32_16x16x32_bf16 v[108:111], v[150:153], v[206:209], v[108:111]
	v_mfma_f32_16x16x32_bf16 v[104:107], v[158:161], v[206:209], v[104:107]
	v_mfma_f32_16x16x32_bf16 v[100:103], v[150:153], v[214:217], v[100:103]
	v_mfma_f32_16x16x32_bf16 v[96:99], v[158:161], v[214:217], v[96:99]
	v_mfma_f32_16x16x32_bf16 v[124:127], v[154:157], v[194:197], v[124:127]
	v_mfma_f32_16x16x32_bf16 v[120:123], v[162:165], v[194:197], v[120:123]
	v_mfma_f32_16x16x32_bf16 v[116:119], v[154:157], v[202:205], v[116:119]
	v_mfma_f32_16x16x32_bf16 v[112:115], v[162:165], v[202:205], v[112:115]
	v_mfma_f32_16x16x32_bf16 v[108:111], v[154:157], v[210:213], v[108:111]
	v_mfma_f32_16x16x32_bf16 v[104:107], v[162:165], v[210:213], v[104:107]
	v_mfma_f32_16x16x32_bf16 v[100:103], v[154:157], v[218:221], v[100:103]
	v_mfma_f32_16x16x32_bf16 v[96:99], v[162:165], v[218:221], v[96:99]
	s_setprio 0
	s_setprio 1
	v_mfma_f32_16x16x32_bf16 v[76:79], v[166:169], v[190:193], v[76:79]
	v_mfma_f32_16x16x32_bf16 v[68:71], v[174:177], v[190:193], v[68:71]
	v_mfma_f32_16x16x32_bf16 v[60:63], v[166:169], v[198:201], v[60:63]
	v_mfma_f32_16x16x32_bf16 v[52:55], v[174:177], v[198:201], v[52:55]
	v_mfma_f32_16x16x32_bf16 v[44:47], v[166:169], v[206:209], v[44:47]
	v_mfma_f32_16x16x32_bf16 v[40:43], v[174:177], v[206:209], v[40:43]
	v_mfma_f32_16x16x32_bf16 v[36:39], v[166:169], v[214:217], v[36:39]
	v_mfma_f32_16x16x32_bf16 v[32:35], v[174:177], v[214:217], v[32:35]
	v_mfma_f32_16x16x32_bf16 v[76:79], v[170:173], v[194:197], v[76:79]
	v_mfma_f32_16x16x32_bf16 v[68:71], v[178:181], v[194:197], v[68:71]
	v_mfma_f32_16x16x32_bf16 v[60:63], v[170:173], v[202:205], v[60:63]
	v_mfma_f32_16x16x32_bf16 v[52:55], v[178:181], v[202:205], v[52:55]
	v_mfma_f32_16x16x32_bf16 v[44:47], v[170:173], v[210:213], v[44:47]
	v_mfma_f32_16x16x32_bf16 v[40:43], v[178:181], v[210:213], v[40:43]
	v_mfma_f32_16x16x32_bf16 v[36:39], v[170:173], v[218:221], v[36:39]
	v_mfma_f32_16x16x32_bf16 v[32:35], v[178:181], v[218:221], v[32:35]
	s_setprio 0
	s_barrier
; #define PG8_STAGE(bufoff, gbase, voff) do { _Pragma("unroll") for (int _i = 0; _i < 2; ++_i) \
;         __builtin_amdgcn_global_load_lds((const unsigned*)((const char*)(gbase) + (voff)[_i]), (PG8_LAS unsigned*)(lds + (bufoff) + ldsw + _i * 8192), 16, 0, 0); } while (0)
; #define PG8_LDA(dst, b, h) do { _Pragma("unroll") for (int m = 0; m < 4; ++m) _Pragma("unroll") for (int k = 0; k < 2; ++k) dst[m][k] = *(const PG8_LAS bf16x8*)(lds + PG8_SA(b, h) + aoff + m * 2048 + k * 1024); } while (0)
; #define PG8_MMA(ai, bj, At, Bt) do { __builtin_amdgcn_s_setprio(1); _Pragma("unroll") for (int m = 0; m < 4; ++m) _Pragma("unroll") for (int n = 0; n < 2; ++n) _Pragma("unroll") for (int k = 0; k < 2; ++k) \
;         acc[ai][bj][m][n] = __builtin_amdgcn_mfma_f32_16x16x32_bf16(Bt[n][k], At[m][k], acc[ai][bj][m][n], 0, 0, 0); __builtin_amdgcn_s_setprio(0); } while (0)
; #define PG8_WAIT_V(n) asm volatile("s_waitcnt vmcnt(" #n ")" ::: "memory")
; #define PG8_WAIT_L(n) asm volatile("s_waitcnt lgkmcnt(" #n ")" ::: "memory")
; #define PG8_BAR __builtin_amdgcn_s_barrier()
; #define PG8_SCHED __builtin_amdgcn_sched_barrier(0)
; template <class Epi, class Sched, bool ALIGN_EPI = false, bool SP2 = false>
; __device__ __forceinline__ void gemm_phase(PG8_LAS unsigned char* lds, const Gemm g, const Sched& S, const Epi& E) {
;     ...
;             PG8_LDA(At, 1, 1); PG8_STAGE(PG8_SB(1, 0), b3, voffB); PG8_STAGE(PG8_SB(1, 1), b3 + hstep, voffB); PG8_STAGE(PG8_SA(1, 0), a3, voffA);
;             PG8_WAIT_V(8); PG8_WAIT_L(0); PG8_BAR; PG8_MMA(1, 0, At, B0); PG8_MMA(1, 1, At, B1); PG8_BAR; PG8_SCHED;
;     ...
;         if constexpr (ALIGN_EPI) { if (wr == 0) PG8_BAR; }
	s_add_i32 s3, s3, s52
	v_lshl_add_u64 v[222:223], v[222:223], 0, s[16:17]
	s_mov_b32 m0, s3
	ds_read_b128 v[190:193], v149 offset:49152
	ds_read_b128 v[194:197], v233 offset:49152
	ds_read_b128 v[198:201], v149 offset:51200
	ds_read_b128 v[202:205], v233 offset:51200
	ds_read_b128 v[206:209], v149 offset:53248
	ds_read_b128 v[210:213], v233 offset:53248
	ds_read_b128 v[214:217], v149 offset:55296
	ds_read_b128 v[218:221], v233 offset:55296
	global_load_lds_dwordx4 v[222:223], off
	s_add_i32 m0, s3, 0x2000
	s_add_u32 s10, s36, 0xb0080
	v_lshl_add_u64 v[222:223], v[224:225], 0, s[16:17]
	s_addc_u32 s11, s37, 0
	s_add_i32 s3, s30, s52
	global_load_lds_dwordx4 v[222:223], off
	v_lshl_add_u64 v[222:223], s[10:11], 0, v[130:131]
	s_mov_b32 m0, s3
	s_nop 0
	global_load_lds_dwordx4 v[222:223], off
	v_lshl_add_u64 v[222:223], s[10:11], 0, v[134:135]
	s_add_i32 m0, s3, 0x2000
	s_nop 0
	global_load_lds_dwordx4 v[222:223], off
	v_lshl_add_u64 v[222:223], v[226:227], 0, s[16:17]
	s_mov_b32 m0, s58
	s_nop 0
	global_load_lds_dwordx4 v[222:223], off
	v_lshl_add_u64 v[222:223], v[228:229], 0, s[16:17]
	s_mov_b32 m0, s59
	s_nop 0
	global_load_lds_dwordx4 v[222:223], off
	s_waitcnt vmcnt(8)
	s_waitcnt lgkmcnt(0)
	s_barrier
	s_setprio 1
	v_mfma_f32_16x16x32_bf16 v[92:95], v[150:153], v[190:193], v[92:95]
	v_mfma_f32_16x16x32_bf16 v[88:91], v[158:161], v[190:193], v[88:91]
	v_mfma_f32_16x16x32_bf16 v[84:87], v[150:153], v[198:201], v[84:87]
	v_mfma_f32_16x16x32_bf16 v[80:83], v[158:161], v[198:201], v[80:83]
	v_mfma_f32_16x16x32_bf16 v[72:75], v[150:153], v[206:209], v[72:75]
	v_mfma_f32_16x16x32_bf16 v[64:67], v[158:161], v[206:209], v[64:67]
	v_mfma_f32_16x16x32_bf16 v[56:59], v[150:153], v[214:217], v[56:59]
	v_mfma_f32_16x16x32_bf16 v[48:51], v[158:161], v[214:217], v[48:51]
	v_mfma_f32_16x16x32_bf16 v[92:95], v[154:157], v[194:197], v[92:95]
	v_mfma_f32_16x16x32_bf16 v[88:91], v[162:165], v[194:197], v[88:91]
	v_mfma_f32_16x16x32_bf16 v[84:87], v[154:157], v[202:205], v[84:87]
	v_mfma_f32_16x16x32_bf16 v[80:83], v[162:165], v[202:205], v[80:83]
	v_mfma_f32_16x16x32_bf16 v[72:75], v[154:157], v[210:213], v[72:75]
	v_mfma_f32_16x16x32_bf16 v[64:67], v[162:165], v[210:213], v[64:67]
	v_mfma_f32_16x16x32_bf16 v[56:59], v[154:157], v[218:221], v[56:59]
	v_mfma_f32_16x16x32_bf16 v[48:51], v[162:165], v[218:221], v[48:51]
	s_setprio 0
	s_setprio 1
	v_mfma_f32_16x16x32_bf16 v[28:31], v[166:169], v[190:193], v[28:31]
	v_mfma_f32_16x16x32_bf16 v[24:27], v[174:177], v[190:193], v[24:27]
	v_mfma_f32_16x16x32_bf16 v[20:23], v[166:169], v[198:201], v[20:23]
	v_mfma_f32_16x16x32_bf16 v[16:19], v[174:177], v[198:201], v[16:19]
	v_mfma_f32_16x16x32_bf16 v[12:15], v[166:169], v[206:209], v[12:15]
	v_mfma_f32_16x16x32_bf16 v[8:11], v[174:177], v[206:209], v[8:11]
	v_mfma_f32_16x16x32_bf16 v[4:7], v[166:169], v[214:217], v[4:7]
	v_mfma_f32_16x16x32_bf16 v[0:3], v[174:177], v[214:217], v[0:3]
	v_mfma_f32_16x16x32_bf16 v[28:31], v[170:173], v[194:197], v[28:31]
	v_mfma_f32_16x16x32_bf16 v[24:27], v[178:181], v[194:197], v[24:27]
	v_mfma_f32_16x16x32_bf16 v[20:23], v[170:173], v[202:205], v[20:23]
	v_mfma_f32_16x16x32_bf16 v[16:19], v[178:181], v[202:205], v[16:19]
	v_mfma_f32_16x16x32_bf16 v[12:15], v[170:173], v[210:213], v[12:15]
	v_mfma_f32_16x16x32_bf16 v[8:11], v[178:181], v[210:213], v[8:11]
	v_mfma_f32_16x16x32_bf16 v[4:7], v[170:173], v[218:221], v[4:7]
	v_mfma_f32_16x16x32_bf16 v[0:3], v[178:181], v[218:221], v[0:3]
	s_setprio 0
	s_barrier
	s_add_i32 s74, s74, 2
	s_add_u32 s72, s72, 0x100
	s_addc_u32 s73, s73, 0
	s_cmp_gt_u32 s74, 41
	s_mov_b64 s[30:31], s[34:35]
	s_cbranch_scc0 .LBB0_303
	s_and_b64 vcc, exec, s[18:19]
	s_cbranch_vccz .LBB0_306
	s_barrier

; #define PG8_STAGE(bufoff, gbase, voff) do { _Pragma("unroll") for (int _i = 0; _i < 2; ++_i) \
;         __builtin_amdgcn_global_load_lds((const unsigned*)((const char*)(gbase) + (voff)[_i]), (PG8_LAS unsigned*)(lds + (bufoff) + ldsw + _i * 8192), 16, 0, 0); } while (0)
; #define PG8_LDA(dst, b, h) do { _Pragma("unroll") for (int m = 0; m < 4; ++m) _Pragma("unroll") for (int k = 0; k < 2; ++k) dst[m][k] = *(const PG8_LAS bf16x8*)(lds + PG8_SA(b, h) + aoff + m * 2048 + k * 1024); } while (0)
; #define PG8_LDB(dst, b, h) do { _Pragma("unroll") for (int n = 0; n < 2; ++n) _Pragma("unroll") for (int k = 0; k < 2; ++k) dst[n][k] = *(const PG8_LAS bf16x8*)(lds + PG8_SB(b, h) + boff + n * 2048 + k * 1024); } while (0)
; #define PG8_MMA(ai, bj, At, Bt) do { __builtin_amdgcn_s_setprio(1); _Pragma("unroll") for (int m = 0; m < 4; ++m) _Pragma("unroll") for (int n = 0; n < 2; ++n) _Pragma("unroll") for (int k = 0; k < 2; ++k) \
;         acc[ai][bj][m][n] = __builtin_amdgcn_mfma_f32_16x16x32_bf16(Bt[n][k], At[m][k], acc[ai][bj][m][n], 0, 0, 0); __builtin_amdgcn_s_setprio(0); } while (0)
; #define PG8_WAIT_V(n) asm volatile("s_waitcnt vmcnt(" #n ")" ::: "memory")
; template <class Epi, class Sched, bool ALIGN_EPI = false, bool SP2 = false>
; __device__ __forceinline__ void gemm_phase(PG8_LAS unsigned char* lds, const Gemm g, const Sched& S, const Epi& E) {
;     ...
;         const char* nA = has_next ? (const char*)g.A + (size_t)nxt.pm * tstep : cA; const char* nB = has_next ? (const char*)g.Bt + (size_t)nxt.pn * tstep : cB;
;         for (int t = 0; t < nt; t += 2) {
;             const bool last = (t == nt - 2);
;             const char* a1 = cA + (size_t)(t + 1) * kstep;
;             const char* a2 = last ? nA : cA + (size_t)(t + 2) * kstep; const char* b2 = last ? nB : cB + (size_t)(t + 2) * kstep;
;             const char* a3 = a2 + kstep; const char* b3 = b2 + kstep;
;             if (last && has_next) S.a_ready(nxt);
;             if constexpr (SP2) {
;             PG8_LDB(B0, 0, 0); PG8_LDB(B1, 0, 1); PG8_SCHED; PG8_LDA(At, 0, 0); PG8_STAGE(PG8_SA(1, 1), a1 + hstep, voffA);
;             PG8_WAIT_V(8); PG8_WAIT_L(0); PG8_BAR; PG8_MMA(0, 0, At, B0); PG8_MMA(0, 1, At, B1); PG8_BAR; PG8_SCHED;
;             PG8_LDA(At, 0, 1); PG8_STAGE(PG8_SB(0, 0), b2, voffB); PG8_STAGE(PG8_SB(0, 1), b2 + hstep, voffB); PG8_STAGE(PG8_SA(0, 0), a2, voffA);
.LBB0_494:
	ds_read_b128 v[152:155], v149
	ds_read_b128 v[156:159], v235
	ds_read_b128 v[160:163], v149 offset:2048
	ds_read_b128 v[164:167], v235 offset:2048
	ds_read_b128 v[168:171], v150
	ds_read_b128 v[172:175], v236
	ds_read_b128 v[176:179], v150 offset:2048
	ds_read_b128 v[190:193], v236 offset:2048
	s_add_u32 s0, s30, 0xfffc0080
	s_addc_u32 s1, s31, -1
	s_cmp_eq_u32 s67, 12
	s_cselect_b32 s37, s21, s1
	s_cselect_b32 s36, s27, s0
	s_cselect_b32 s35, s19, s66
	s_cselect_b32 s34, s29, s65
	v_lshl_add_u64 v[144:145], s[30:31], 0, v[136:137]
	s_add_i32 m0, s43, 0xc000
	ds_read_b128 v[194:197], v151
	ds_read_b128 v[198:201], v233
	ds_read_b128 v[202:205], v151 offset:2048
	ds_read_b128 v[206:209], v233 offset:2048
	ds_read_b128 v[210:213], v151 offset:4096
	ds_read_b128 v[214:217], v233 offset:4096
	ds_read_b128 v[218:221], v151 offset:6144
	ds_read_b128 v[222:225], v233 offset:6144
	global_load_lds_dwordx4 v[144:145], off
	v_lshl_add_u64 v[144:145], s[30:31], 0, v[138:139]
	s_add_i32 m0, s43, 0xe000
	s_nop 0
	global_load_lds_dwordx4 v[144:145], off
	s_waitcnt vmcnt(8)
	s_waitcnt lgkmcnt(0)
	s_barrier
	s_setprio 1
	v_mfma_f32_16x16x32_bf16 v[124:127], v[152:155], v[194:197], v[124:127]
	v_mfma_f32_16x16x32_bf16 v[120:123], v[160:163], v[194:197], v[120:123]
	v_mfma_f32_16x16x32_bf16 v[116:119], v[152:155], v[202:205], v[116:119]
	v_mfma_f32_16x16x32_bf16 v[112:115], v[160:163], v[202:205], v[112:115]
	v_mfma_f32_16x16x32_bf16 v[108:111], v[152:155], v[210:213], v[108:111]
	v_mfma_f32_16x16x32_bf16 v[104:107], v[160:163], v[210:213], v[104:107]
	v_mfma_f32_16x16x32_bf16 v[100:103], v[152:155], v[218:221], v[100:103]
	v_mfma_f32_16x16x32_bf16 v[96:99], v[160:163], v[218:221], v[96:99]
	v_mfma_f32_16x16x32_bf16 v[124:127], v[156:159], v[198:201], v[124:127]
	v_mfma_f32_16x16x32_bf16 v[120:123], v[164:167], v[198:201], v[120:123]
	v_mfma_f32_16x16x32_bf16 v[116:119], v[156:159], v[206:209], v[116:119]
	v_mfma_f32_16x16x32_bf16 v[112:115], v[164:167], v[206:209], v[112:115]
	v_mfma_f32_16x16x32_bf16 v[108:111], v[156:159], v[214:217], v[108:111]
	v_mfma_f32_16x16x32_bf16 v[104:107], v[164:167], v[214:217], v[104:107]
	v_mfma_f32_16x16x32_bf16 v[100:103], v[156:159], v[222:225], v[100:103]
	v_mfma_f32_16x16x32_bf16 v[96:99], v[164:167], v[222:225], v[96:99]
	s_setprio 0
	s_setprio 1
	v_mfma_f32_16x16x32_bf16 v[60:63], v[168:171], v[194:197], v[60:63]
	v_mfma_f32_16x16x32_bf16 v[56:59], v[176:179], v[194:197], v[56:59]
	v_mfma_f32_16x16x32_bf16 v[52:55], v[168:171], v[202:205], v[52:55]
	v_mfma_f32_16x16x32_bf16 v[48:51], v[176:179], v[202:205], v[48:51]
	v_mfma_f32_16x16x32_bf16 v[44:47], v[168:171], v[210:213], v[44:47]
	v_mfma_f32_16x16x32_bf16 v[40:43], v[176:179], v[210:213], v[40:43]
	v_mfma_f32_16x16x32_bf16 v[36:39], v[168:171], v[218:221], v[36:39]
	v_mfma_f32_16x16x32_bf16 v[32:35], v[176:179], v[218:221], v[32:35]
	v_mfma_f32_16x16x32_bf16 v[60:63], v[172:175], v[198:201], v[60:63]
	v_mfma_f32_16x16x32_bf16 v[56:59], v[190:193], v[198:201], v[56:59]
	v_mfma_f32_16x16x32_bf16 v[52:55], v[172:175], v[206:209], v[52:55]
	v_mfma_f32_16x16x32_bf16 v[48:51], v[190:193], v[206:209], v[48:51]
	v_mfma_f32_16x16x32_bf16 v[44:47], v[172:175], v[214:217], v[44:47]
	v_mfma_f32_16x16x32_bf16 v[40:43], v[190:193], v[214:217], v[40:43]
	v_mfma_f32_16x16x32_bf16 v[36:39], v[172:175], v[222:225], v[36:39]
	v_mfma_f32_16x16x32_bf16 v[32:35], v[190:193], v[222:225], v[32:35]
	s_setprio 0
	s_barrier
	s_add_i32 s0, s62, s42
	v_lshl_add_u64 v[144:145], s[34:35], 0, v[130:131]
	s_mov_b32 m0, s0
	ds_read_b128 v[194:197], v151 offset:16384
	ds_read_b128 v[198:201], v233 offset:16384
	ds_read_b128 v[202:205], v151 offset:18432
	ds_read_b128 v[206:209], v233 offset:18432
	ds_read_b128 v[210:213], v151 offset:20480
	ds_read_b128 v[214:217], v233 offset:20480
	ds_read_b128 v[218:221], v151 offset:22528
	ds_read_b128 v[222:225], v233 offset:22528
	global_load_lds_dwordx4 v[144:145], off
	s_add_i32 m0, s0, 0x2000
	s_add_u32 s0, s34, 0x40000
	v_lshl_add_u64 v[180:181], s[34:35], 0, v[134:135]
	s_addc_u32 s1, s35, 0
	s_add_i32 s3, s63, s42
	global_load_lds_dwordx4 v[180:181], off
	v_lshl_add_u64 v[226:227], s[0:1], 0, v[130:131]
	s_mov_b32 m0, s3
	v_lshl_add_u64 v[228:229], s[36:37], 0, v[132:133]
	global_load_lds_dwordx4 v[226:227], off
	v_lshl_add_u64 v[226:227], s[0:1], 0, v[134:135]
	s_add_i32 m0, s3, 0x2000
	s_nop 0
	global_load_lds_dwordx4 v[226:227], off
	v_lshl_add_u64 v[226:227], s[36:37], 0, v[128:129]
	s_mov_b32 m0, s43
	s_nop 0
	global_load_lds_dwordx4 v[226:227], off
	s_mov_b32 m0, s47
	s_nop 0
	global_load_lds_dwordx4 v[228:229], off
	s_waitcnt vmcnt(8)
	s_waitcnt lgkmcnt(0)
	s_barrier
; #define PG8_STAGE(bufoff, gbase, voff) do { _Pragma("unroll") for (int _i = 0; _i < 2; ++_i) \
;         __builtin_amdgcn_global_load_lds((const unsigned*)((const char*)(gbase) + (voff)[_i]), (PG8_LAS unsigned*)(lds + (bufoff) + ldsw + _i * 8192), 16, 0, 0); } while (0)
; #define PG8_LDA(dst, b, h) do { _Pragma("unroll") for (int m = 0; m < 4; ++m) _Pragma("unroll") for (int k = 0; k < 2; ++k) dst[m][k] = *(const PG8_LAS bf16x8*)(lds + PG8_SA(b, h) + aoff + m * 2048 + k * 1024); } while (0)
; #define PG8_LDB(dst, b, h) do { _Pragma("unroll") for (int n = 0; n < 2; ++n) _Pragma("unroll") for (int k = 0; k < 2; ++k) dst[n][k] = *(const PG8_LAS bf16x8*)(lds + PG8_SB(b, h) + boff + n * 2048 + k * 1024); } while (0)
; #define PG8_MMA(ai, bj, At, Bt) do { __builtin_amdgcn_s_setprio(1); _Pragma("unroll") for (int m = 0; m < 4; ++m) _Pragma("unroll") for (int n = 0; n < 2; ++n) _Pragma("unroll") for (int k = 0; k < 2; ++k) \
;         acc[ai][bj][m][n] = __builtin_amdgcn_mfma_f32_16x16x32_bf16(Bt[n][k], At[m][k], acc[ai][bj][m][n], 0, 0, 0); __builtin_amdgcn_s_setprio(0); } while (0)
; #define PG8_WAIT_V(n) asm volatile("s_waitcnt vmcnt(" #n ")" ::: "memory")
; #define PG8_WAIT_L(n) asm volatile("s_waitcnt lgkmcnt(" #n ")" ::: "memory")
; #define PG8_BAR __builtin_amdgcn_s_barrier()
; #define PG8_SCHED __builtin_amdgcn_sched_barrier(0)
; template <class Epi, class Sched, bool ALIGN_EPI = false, bool SP2 = false>
; __device__ __forceinline__ void gemm_phase(PG8_LAS unsigned char* lds, const Gemm g, const Sched& S, const Epi& E) {
;     ...
;             PG8_WAIT_V(8); PG8_WAIT_L(0); PG8_BAR; PG8_MMA(1, 0, At, B0); PG8_MMA(1, 1, At, B1); PG8_BAR; PG8_SCHED;
;             PG8_LDB(B0, 1, 0); PG8_LDB(B1, 1, 1); PG8_SCHED; PG8_LDA(At, 1, 0); PG8_STAGE(PG8_SA(0, 1), a2 + hstep, voffA);
;             PG8_WAIT_V(8); PG8_WAIT_L(0); PG8_BAR; PG8_MMA(0, 0, At, B0); PG8_MMA(0, 1, At, B1); PG8_BAR; PG8_SCHED;
	s_setprio 1
	v_mfma_f32_16x16x32_bf16 v[92:95], v[152:155], v[194:197], v[92:95]
	v_mfma_f32_16x16x32_bf16 v[88:91], v[160:163], v[194:197], v[88:91]
	v_mfma_f32_16x16x32_bf16 v[84:87], v[152:155], v[202:205], v[84:87]
	v_mfma_f32_16x16x32_bf16 v[80:83], v[160:163], v[202:205], v[80:83]
	v_mfma_f32_16x16x32_bf16 v[76:79], v[152:155], v[210:213], v[76:79]
	v_mfma_f32_16x16x32_bf16 v[72:75], v[160:163], v[210:213], v[72:75]
	v_mfma_f32_16x16x32_bf16 v[68:71], v[152:155], v[218:221], v[68:71]
	v_mfma_f32_16x16x32_bf16 v[64:67], v[160:163], v[218:221], v[64:67]
	v_mfma_f32_16x16x32_bf16 v[92:95], v[156:159], v[198:201], v[92:95]
	v_mfma_f32_16x16x32_bf16 v[88:91], v[164:167], v[198:201], v[88:91]
	v_mfma_f32_16x16x32_bf16 v[84:87], v[156:159], v[206:209], v[84:87]
	v_mfma_f32_16x16x32_bf16 v[80:83], v[164:167], v[206:209], v[80:83]
	v_mfma_f32_16x16x32_bf16 v[76:79], v[156:159], v[214:217], v[76:79]
	v_mfma_f32_16x16x32_bf16 v[72:75], v[164:167], v[214:217], v[72:75]
	v_mfma_f32_16x16x32_bf16 v[68:71], v[156:159], v[222:225], v[68:71]
	v_mfma_f32_16x16x32_bf16 v[64:67], v[164:167], v[222:225], v[64:67]
	s_setprio 0
	s_setprio 1
	v_mfma_f32_16x16x32_bf16 v[28:31], v[168:171], v[194:197], v[28:31]
	v_mfma_f32_16x16x32_bf16 v[24:27], v[176:179], v[194:197], v[24:27]
	v_mfma_f32_16x16x32_bf16 v[20:23], v[168:171], v[202:205], v[20:23]
	v_mfma_f32_16x16x32_bf16 v[16:19], v[176:179], v[202:205], v[16:19]
	v_mfma_f32_16x16x32_bf16 v[12:15], v[168:171], v[210:213], v[12:15]
	v_mfma_f32_16x16x32_bf16 v[8:11], v[176:179], v[210:213], v[8:11]
	v_mfma_f32_16x16x32_bf16 v[4:7], v[168:171], v[218:221], v[4:7]
	v_mfma_f32_16x16x32_bf16 v[0:3], v[176:179], v[218:221], v[0:3]
	v_mfma_f32_16x16x32_bf16 v[28:31], v[172:175], v[198:201], v[28:31]
	v_mfma_f32_16x16x32_bf16 v[24:27], v[190:193], v[198:201], v[24:27]
	v_mfma_f32_16x16x32_bf16 v[20:23], v[172:175], v[206:209], v[20:23]
	v_mfma_f32_16x16x32_bf16 v[16:19], v[190:193], v[206:209], v[16:19]
	v_mfma_f32_16x16x32_bf16 v[12:15], v[172:175], v[214:217], v[12:15]
	v_mfma_f32_16x16x32_bf16 v[8:11], v[190:193], v[214:217], v[8:11]
	v_mfma_f32_16x16x32_bf16 v[4:7], v[172:175], v[222:225], v[4:7]
	v_mfma_f32_16x16x32_bf16 v[0:3], v[190:193], v[222:225], v[0:3]
	s_setprio 0
	s_barrier
	s_add_i32 s3, 0, 0x18000
	s_add_i32 s45, 0, 0x1c000
	v_add_u32_e32 v164, s3, v147
	v_add_u32_e32 v237, s3, v234
	v_add_u32_e32 v189, s45, v147
	v_add_u32_e32 v238, s45, v234
	ds_read_b128 v[152:155], v164
	ds_read_b128 v[156:159], v237
	ds_read_b128 v[160:163], v164 offset:2048
	ds_read_b128 v[164:167], v237 offset:2048
	ds_read_b128 v[168:171], v189
	ds_read_b128 v[172:175], v238
	ds_read_b128 v[176:179], v189 offset:2048
	ds_read_b128 v[190:193], v238 offset:2048
	s_add_u32 s0, s36, 0x40000
	s_addc_u32 s1, s37, 0
	s_mov_b32 m0, s52
	v_lshl_add_u64 v[230:231], s[0:1], 0, v[128:129]
	ds_read_b128 v[194:197], v151 offset:32768
	ds_read_b128 v[198:201], v233 offset:32768
	ds_read_b128 v[202:205], v151 offset:34816
	ds_read_b128 v[206:209], v233 offset:34816
	ds_read_b128 v[210:213], v151 offset:36864
	ds_read_b128 v[214:217], v233 offset:36864
	ds_read_b128 v[218:221], v151 offset:38912
	ds_read_b128 v[222:225], v233 offset:38912
	global_load_lds_dwordx4 v[230:231], off
	v_lshl_add_u64 v[230:231], s[0:1], 0, v[132:133]
	s_mov_b32 m0, s53
	s_nop 0
	global_load_lds_dwordx4 v[230:231], off
	s_waitcnt vmcnt(8)
	s_waitcnt lgkmcnt(0)
	s_barrier
	s_setprio 1
	v_mfma_f32_16x16x32_bf16 v[124:127], v[152:155], v[194:197], v[124:127]
	v_mfma_f32_16x16x32_bf16 v[120:123], v[160:163], v[194:197], v[120:123]
	v_mfma_f32_16x16x32_bf16 v[116:119], v[152:155], v[202:205], v[116:119]
	v_mfma_f32_16x16x32_bf16 v[112:115], v[160:163], v[202:205], v[112:115]
	v_mfma_f32_16x16x32_bf16 v[108:111], v[152:155], v[210:213], v[108:111]
	v_mfma_f32_16x16x32_bf16 v[104:107], v[160:163], v[210:213], v[104:107]
	v_mfma_f32_16x16x32_bf16 v[100:103], v[152:155], v[218:221], v[100:103]
	v_mfma_f32_16x16x32_bf16 v[96:99], v[160:163], v[218:221], v[96:99]
	v_mfma_f32_16x16x32_bf16 v[124:127], v[156:159], v[198:201], v[124:127]
	v_mfma_f32_16x16x32_bf16 v[120:123], v[164:167], v[198:201], v[120:123]
	v_mfma_f32_16x16x32_bf16 v[116:119], v[156:159], v[206:209], v[116:119]
	v_mfma_f32_16x16x32_bf16 v[112:115], v[164:167], v[206:209], v[112:115]
	v_mfma_f32_16x16x32_bf16 v[108:111], v[156:159], v[214:217], v[108:111]
	v_mfma_f32_16x16x32_bf16 v[104:107], v[164:167], v[214:217], v[104:107]
	v_mfma_f32_16x16x32_bf16 v[100:103], v[156:159], v[222:225], v[100:103]
	v_mfma_f32_16x16x32_bf16 v[96:99], v[164:167], v[222:225], v[96:99]
	s_setprio 0
	s_setprio 1
	v_mfma_f32_16x16x32_bf16 v[60:63], v[168:171], v[194:197], v[60:63]
	v_mfma_f32_16x16x32_bf16 v[56:59], v[176:179], v[194:197], v[56:59]
	v_mfma_f32_16x16x32_bf16 v[52:55], v[168:171], v[202:205], v[52:55]
	v_mfma_f32_16x16x32_bf16 v[48:51], v[176:179], v[202:205], v[48:51]
	v_mfma_f32_16x16x32_bf16 v[44:47], v[168:171], v[210:213], v[44:47]
	v_mfma_f32_16x16x32_bf16 v[40:43], v[176:179], v[210:213], v[40:43]
	v_mfma_f32_16x16x32_bf16 v[36:39], v[168:171], v[218:221], v[36:39]
	v_mfma_f32_16x16x32_bf16 v[32:35], v[176:179], v[218:221], v[32:35]
	v_mfma_f32_16x16x32_bf16 v[60:63], v[172:175], v[198:201], v[60:63]
	v_mfma_f32_16x16x32_bf16 v[56:59], v[190:193], v[198:201], v[56:59]
	v_mfma_f32_16x16x32_bf16 v[52:55], v[172:175], v[206:209], v[52:55]
	v_mfma_f32_16x16x32_bf16 v[48:51], v[190:193], v[206:209], v[48:51]
	v_mfma_f32_16x16x32_bf16 v[44:47], v[172:175], v[214:217], v[44:47]
	v_mfma_f32_16x16x32_bf16 v[40:43], v[190:193], v[214:217], v[40:43]
	v_mfma_f32_16x16x32_bf16 v[36:39], v[172:175], v[222:225], v[36:39]
	v_mfma_f32_16x16x32_bf16 v[32:35], v[190:193], v[222:225], v[32:35]
	s_setprio 0
	s_barrier
; #define PG8_STAGE(bufoff, gbase, voff) do { _Pragma("unroll") for (int _i = 0; _i < 2; ++_i) \
;         __builtin_amdgcn_global_load_lds((const unsigned*)((const char*)(gbase) + (voff)[_i]), (PG8_LAS unsigned*)(lds + (bufoff) + ldsw + _i * 8192), 16, 0, 0); } while (0)
; #define PG8_LDA(dst, b, h) do { _Pragma("unroll") for (int m = 0; m < 4; ++m) _Pragma("unroll") for (int k = 0; k < 2; ++k) dst[m][k] = *(const PG8_LAS bf16x8*)(lds + PG8_SA(b, h) + aoff + m * 2048 + k * 1024); } while (0)
; #define PG8_MMA(ai, bj, At, Bt) do { __builtin_amdgcn_s_setprio(1); _Pragma("unroll") for (int m = 0; m < 4; ++m) _Pragma("unroll") for (int n = 0; n < 2; ++n) _Pragma("unroll") for (int k = 0; k < 2; ++k) \
;         acc[ai][bj][m][n] = __builtin_amdgcn_mfma_f32_16x16x32_bf16(Bt[n][k], At[m][k], acc[ai][bj][m][n], 0, 0, 0); __builtin_amdgcn_s_setprio(0); } while (0)
; #define PG8_WAIT_V(n) asm volatile("s_waitcnt vmcnt(" #n ")" ::: "memory")
; #define PG8_WAIT_L(n) asm volatile("s_waitcnt lgkmcnt(" #n ")" ::: "memory")
; #define PG8_BAR __builtin_amdgcn_s_barrier()
; #define PG8_SCHED __builtin_amdgcn_sched_barrier(0)
; template <class Epi, class Sched, bool ALIGN_EPI = false, bool SP2 = false>
; __device__ __forceinline__ void gemm_phase(PG8_LAS unsigned char* lds, const Gemm g, const Sched& S, const Epi& E) {
;     ...
;             PG8_LDA(At, 1, 1); PG8_STAGE(PG8_SB(1, 0), b3, voffB); PG8_STAGE(PG8_SB(1, 1), b3 + hstep, voffB); PG8_STAGE(PG8_SA(1, 0), a3, voffA);
;             PG8_WAIT_V(8); PG8_WAIT_L(0); PG8_BAR; PG8_MMA(1, 0, At, B0); PG8_MMA(1, 1, At, B1); PG8_BAR; PG8_SCHED;
;     ...
;         if constexpr (ALIGN_EPI) { if (wr == 0) PG8_BAR; }
	s_add_i32 s0, s3, s42
	v_lshl_add_u64 v[144:145], v[144:145], 0, s[14:15]
	s_mov_b32 m0, s0
	ds_read_b128 v[194:197], v151 offset:49152
	ds_read_b128 v[198:201], v233 offset:49152
	ds_read_b128 v[202:205], v151 offset:51200
	ds_read_b128 v[206:209], v233 offset:51200
	ds_read_b128 v[210:213], v151 offset:53248
	ds_read_b128 v[214:217], v233 offset:53248
	ds_read_b128 v[218:221], v151 offset:55296
	ds_read_b128 v[222:225], v233 offset:55296
	global_load_lds_dwordx4 v[144:145], off
	s_add_i32 m0, s0, 0x2000
	s_add_u32 s0, s34, 0x40080
	v_lshl_add_u64 v[144:145], v[180:181], 0, s[14:15]
	s_addc_u32 s1, s35, 0
	s_add_i32 s3, s45, s42
	global_load_lds_dwordx4 v[144:145], off
	v_lshl_add_u64 v[144:145], s[0:1], 0, v[130:131]
	s_mov_b32 m0, s3
	s_nop 0
	global_load_lds_dwordx4 v[144:145], off
	v_lshl_add_u64 v[144:145], s[0:1], 0, v[134:135]
	s_add_i32 m0, s3, 0x2000
	s_nop 0
	global_load_lds_dwordx4 v[144:145], off
	v_lshl_add_u64 v[144:145], v[226:227], 0, s[14:15]
	s_mov_b32 m0, s56
	s_nop 0
	global_load_lds_dwordx4 v[144:145], off
	v_lshl_add_u64 v[144:145], v[228:229], 0, s[14:15]
	s_mov_b32 m0, s57
	s_nop 0
	global_load_lds_dwordx4 v[144:145], off
	s_waitcnt vmcnt(8)
	s_waitcnt lgkmcnt(0)
	s_barrier
	s_setprio 1
	v_mfma_f32_16x16x32_bf16 v[92:95], v[152:155], v[194:197], v[92:95]
	v_mfma_f32_16x16x32_bf16 v[88:91], v[160:163], v[194:197], v[88:91]
	v_mfma_f32_16x16x32_bf16 v[84:87], v[152:155], v[202:205], v[84:87]
	v_mfma_f32_16x16x32_bf16 v[80:83], v[160:163], v[202:205], v[80:83]
	v_mfma_f32_16x16x32_bf16 v[76:79], v[152:155], v[210:213], v[76:79]
	v_mfma_f32_16x16x32_bf16 v[72:75], v[160:163], v[210:213], v[72:75]
	v_mfma_f32_16x16x32_bf16 v[68:71], v[152:155], v[218:221], v[68:71]
	v_mfma_f32_16x16x32_bf16 v[64:67], v[160:163], v[218:221], v[64:67]
	v_mfma_f32_16x16x32_bf16 v[92:95], v[156:159], v[198:201], v[92:95]
	v_mfma_f32_16x16x32_bf16 v[88:91], v[164:167], v[198:201], v[88:91]
	v_mfma_f32_16x16x32_bf16 v[84:87], v[156:159], v[206:209], v[84:87]
	v_mfma_f32_16x16x32_bf16 v[80:83], v[164:167], v[206:209], v[80:83]
	v_mfma_f32_16x16x32_bf16 v[76:79], v[156:159], v[214:217], v[76:79]
	v_mfma_f32_16x16x32_bf16 v[72:75], v[164:167], v[214:217], v[72:75]
	v_mfma_f32_16x16x32_bf16 v[68:71], v[156:159], v[222:225], v[68:71]
	v_mfma_f32_16x16x32_bf16 v[64:67], v[164:167], v[222:225], v[64:67]
	s_setprio 0
	s_setprio 1
	v_mfma_f32_16x16x32_bf16 v[28:31], v[168:171], v[194:197], v[28:31]
	v_mfma_f32_16x16x32_bf16 v[24:27], v[176:179], v[194:197], v[24:27]
	v_mfma_f32_16x16x32_bf16 v[20:23], v[168:171], v[202:205], v[20:23]
	v_mfma_f32_16x16x32_bf16 v[16:19], v[176:179], v[202:205], v[16:19]
	v_mfma_f32_16x16x32_bf16 v[12:15], v[168:171], v[210:213], v[12:15]
	v_mfma_f32_16x16x32_bf16 v[8:11], v[176:179], v[210:213], v[8:11]
	v_mfma_f32_16x16x32_bf16 v[4:7], v[168:171], v[218:221], v[4:7]
	v_mfma_f32_16x16x32_bf16 v[0:3], v[176:179], v[218:221], v[0:3]
	v_mfma_f32_16x16x32_bf16 v[28:31], v[172:175], v[198:201], v[28:31]
	v_mfma_f32_16x16x32_bf16 v[24:27], v[190:193], v[198:201], v[24:27]
	v_mfma_f32_16x16x32_bf16 v[20:23], v[172:175], v[206:209], v[20:23]
	v_mfma_f32_16x16x32_bf16 v[16:19], v[190:193], v[206:209], v[16:19]
	v_mfma_f32_16x16x32_bf16 v[12:15], v[172:175], v[214:217], v[12:15]
	v_mfma_f32_16x16x32_bf16 v[8:11], v[190:193], v[214:217], v[8:11]
	v_mfma_f32_16x16x32_bf16 v[4:7], v[172:175], v[222:225], v[4:7]
	v_mfma_f32_16x16x32_bf16 v[0:3], v[190:193], v[222:225], v[0:3]
	s_setprio 0
	s_barrier
	s_add_i32 s67, s67, 2
	s_add_u32 s30, s30, 0x100
	s_addc_u32 s31, s31, 0
	s_add_u32 s65, s65, 0x100
	s_addc_u32 s66, s66, 0
	s_cmp_gt_u32 s67, 13
	s_cbranch_scc0 .LBB0_494
	s_and_b64 vcc, exec, s[16:17]
	s_cbranch_vccz .LBB0_497
	s_barrier

; #define PG8_STAGE(bufoff, gbase, voff) do { _Pragma("unroll") for (int _i = 0; _i < 2; ++_i) \
;         __builtin_amdgcn_global_load_lds((const unsigned*)((const char*)(gbase) + (voff)[_i]), (PG8_LAS unsigned*)(lds + (bufoff) + ldsw + _i * 8192), 16, 0, 0); } while (0)
; #define PG8_LDA(dst, b, h) do { _Pragma("unroll") for (int m = 0; m < 4; ++m) _Pragma("unroll") for (int k = 0; k < 2; ++k) dst[m][k] = *(const PG8_LAS bf16x8*)(lds + PG8_SA(b, h) + aoff + m * 2048 + k * 1024); } while (0)
; #define PG8_LDB(dst, b, h) do { _Pragma("unroll") for (int n = 0; n < 2; ++n) _Pragma("unroll") for (int k = 0; k < 2; ++k) dst[n][k] = *(const PG8_LAS bf16x8*)(lds + PG8_SB(b, h) + boff + n * 2048 + k * 1024); } while (0)
; #define PG8_MMA(ai, bj, At, Bt) do { __builtin_amdgcn_s_setprio(1); _Pragma("unroll") for (int m = 0; m < 4; ++m) _Pragma("unroll") for (int n = 0; n < 2; ++n) _Pragma("unroll") for (int k = 0; k < 2; ++k) \
;         acc[ai][bj][m][n] = __builtin_amdgcn_mfma_f32_16x16x32_bf16(Bt[n][k], At[m][k], acc[ai][bj][m][n], 0, 0, 0); __builtin_amdgcn_s_setprio(0); } while (0)
; #define PG8_WAIT_V(n) asm volatile("s_waitcnt vmcnt(" #n ")" ::: "memory")
; template <class Epi, class Sched, bool ALIGN_EPI = false, bool SP2 = false>
; __device__ __forceinline__ void gemm_phase(PG8_LAS unsigned char* lds, const Gemm g, const Sched& S, const Epi& E) {
;     ...
;         const char* nA = has_next ? (const char*)g.A + (size_t)nxt.pm * tstep : cA; const char* nB = has_next ? (const char*)g.Bt + (size_t)nxt.pn * tstep : cB;
;         for (int t = 0; t < nt; t += 2) {
;             const bool last = (t == nt - 2);
;             const char* a1 = cA + (size_t)(t + 1) * kstep;
;             const char* a2 = last ? nA : cA + (size_t)(t + 2) * kstep; const char* b2 = last ? nB : cB + (size_t)(t + 2) * kstep;
;             const char* a3 = a2 + kstep; const char* b3 = b2 + kstep;
;             if (last && has_next) S.a_ready(nxt);
;             if constexpr (SP2) {
;             PG8_LDB(B0, 0, 0); PG8_LDB(B1, 0, 1); PG8_SCHED; PG8_LDA(At, 0, 0); PG8_STAGE(PG8_SA(1, 1), a1 + hstep, voffA);
;             PG8_WAIT_V(8); PG8_WAIT_L(0); PG8_BAR; PG8_MMA(0, 0, At, B0); PG8_MMA(0, 1, At, B1); PG8_BAR; PG8_SCHED;
;             PG8_LDA(At, 0, 1); PG8_STAGE(PG8_SB(0, 0), b2, voffB); PG8_STAGE(PG8_SB(0, 1), b2 + hstep, voffB); PG8_STAGE(PG8_SA(0, 0), a2, voffA);
.LBB0_760:
	ds_read_b128 v[112:115], v167
	ds_read_b128 v[116:119], v167 offset:1024
	ds_read_b128 v[152:155], v167 offset:2048
	ds_read_b128 v[156:159], v167 offset:3072
	ds_read_b128 v[160:163], v168
	ds_read_b128 v[170:173], v168 offset:1024
	ds_read_b128 v[174:177], v168 offset:2048
	ds_read_b128 v[178:181], v168 offset:3072
	s_add_u32 s0, s34, 0xfffe0080
	s_addc_u32 s1, s35, -1
	s_cmp_eq_u32 s68, 4
	s_cselect_b32 s39, s25, s1
	s_cselect_b32 s38, s64, s0
	s_cselect_b32 s37, s23, s67
	s_cselect_b32 s36, s65, s66
	v_lshl_add_u64 v[222:223], s[34:35], 0, v[144:145]
	s_add_i32 m0, s31, 0xc000
	ds_read_b128 v[190:193], v169
	ds_read_b128 v[194:197], v169 offset:1024
	ds_read_b128 v[198:201], v169 offset:2048
	ds_read_b128 v[202:205], v169 offset:3072
	ds_read_b128 v[206:209], v169 offset:4096
	ds_read_b128 v[210:213], v169 offset:5120
	ds_read_b128 v[214:217], v169 offset:6144
	ds_read_b128 v[218:221], v169 offset:7168
	global_load_lds_dwordx4 v[222:223], off
	v_lshl_add_u64 v[222:223], s[34:35], 0, v[146:147]
	s_add_i32 m0, s31, 0xe000
	s_nop 0
	global_load_lds_dwordx4 v[222:223], off
	s_waitcnt vmcnt(8)
	s_waitcnt lgkmcnt(0)
	s_barrier
	s_setprio 1
	v_mfma_f32_16x16x32_bf16 v[132:135], v[112:115], v[190:193], v[132:135]
	v_mfma_f32_16x16x32_bf16 v[128:131], v[152:155], v[190:193], v[128:131]
	v_mfma_f32_16x16x32_bf16 v[124:127], v[112:115], v[198:201], v[124:127]
	v_mfma_f32_16x16x32_bf16 v[120:123], v[152:155], v[198:201], v[120:123]
	v_mfma_f32_16x16x32_bf16 v[108:111], v[112:115], v[206:209], v[108:111]
	v_mfma_f32_16x16x32_bf16 v[104:107], v[152:155], v[206:209], v[104:107]
	v_mfma_f32_16x16x32_bf16 v[100:103], v[112:115], v[214:217], v[100:103]
	v_mfma_f32_16x16x32_bf16 v[96:99], v[152:155], v[214:217], v[96:99]
	v_mfma_f32_16x16x32_bf16 v[132:135], v[116:119], v[194:197], v[132:135]
	v_mfma_f32_16x16x32_bf16 v[128:131], v[156:159], v[194:197], v[128:131]
	v_mfma_f32_16x16x32_bf16 v[124:127], v[116:119], v[202:205], v[124:127]
	v_mfma_f32_16x16x32_bf16 v[120:123], v[156:159], v[202:205], v[120:123]
	v_mfma_f32_16x16x32_bf16 v[108:111], v[116:119], v[210:213], v[108:111]
	v_mfma_f32_16x16x32_bf16 v[104:107], v[156:159], v[210:213], v[104:107]
	v_mfma_f32_16x16x32_bf16 v[100:103], v[116:119], v[218:221], v[100:103]
	v_mfma_f32_16x16x32_bf16 v[96:99], v[156:159], v[218:221], v[96:99]
	s_setprio 0
	s_setprio 1
	v_mfma_f32_16x16x32_bf16 v[60:63], v[160:163], v[190:193], v[60:63]
	v_mfma_f32_16x16x32_bf16 v[56:59], v[174:177], v[190:193], v[56:59]
	v_mfma_f32_16x16x32_bf16 v[52:55], v[160:163], v[198:201], v[52:55]
	v_mfma_f32_16x16x32_bf16 v[48:51], v[174:177], v[198:201], v[48:51]
	v_mfma_f32_16x16x32_bf16 v[44:47], v[160:163], v[206:209], v[44:47]
	v_mfma_f32_16x16x32_bf16 v[40:43], v[174:177], v[206:209], v[40:43]
	v_mfma_f32_16x16x32_bf16 v[36:39], v[160:163], v[214:217], v[36:39]
	v_mfma_f32_16x16x32_bf16 v[32:35], v[174:177], v[214:217], v[32:35]
	v_mfma_f32_16x16x32_bf16 v[60:63], v[170:173], v[194:197], v[60:63]
	v_mfma_f32_16x16x32_bf16 v[56:59], v[178:181], v[194:197], v[56:59]
	v_mfma_f32_16x16x32_bf16 v[52:55], v[170:173], v[202:205], v[52:55]
	v_mfma_f32_16x16x32_bf16 v[48:51], v[178:181], v[202:205], v[48:51]
	v_mfma_f32_16x16x32_bf16 v[44:47], v[170:173], v[210:213], v[44:47]
	v_mfma_f32_16x16x32_bf16 v[40:43], v[178:181], v[210:213], v[40:43]
	v_mfma_f32_16x16x32_bf16 v[36:39], v[170:173], v[218:221], v[36:39]
	v_mfma_f32_16x16x32_bf16 v[32:35], v[178:181], v[218:221], v[32:35]
	s_setprio 0
	s_barrier
	s_add_i32 s0, s61, s52
	v_lshl_add_u64 v[222:223], s[36:37], 0, v[138:139]
	s_mov_b32 m0, s0
	ds_read_b128 v[190:193], v169 offset:16384
	ds_read_b128 v[194:197], v169 offset:17408
	ds_read_b128 v[198:201], v169 offset:18432
	ds_read_b128 v[202:205], v169 offset:19456
	ds_read_b128 v[206:209], v169 offset:20480
	ds_read_b128 v[210:213], v169 offset:21504
	ds_read_b128 v[214:217], v169 offset:22528
	ds_read_b128 v[218:221], v169 offset:23552
	global_load_lds_dwordx4 v[222:223], off
	s_add_i32 m0, s0, 0x2000
	s_add_u32 s0, s36, 0x20000
	v_lshl_add_u64 v[224:225], s[36:37], 0, v[142:143]
	s_addc_u32 s1, s37, 0
	s_add_i32 s3, s62, s52
	global_load_lds_dwordx4 v[224:225], off
	v_lshl_add_u64 v[226:227], s[0:1], 0, v[138:139]
	s_mov_b32 m0, s3
	v_lshl_add_u64 v[228:229], s[38:39], 0, v[140:141]
	global_load_lds_dwordx4 v[226:227], off
	v_lshl_add_u64 v[226:227], s[0:1], 0, v[142:143]
	s_add_i32 m0, s3, 0x2000
	s_nop 0
	global_load_lds_dwordx4 v[226:227], off
	v_lshl_add_u64 v[226:227], s[38:39], 0, v[136:137]
	s_mov_b32 m0, s31
	s_nop 0
	global_load_lds_dwordx4 v[226:227], off
	s_mov_b32 m0, s53
	s_nop 0
	global_load_lds_dwordx4 v[228:229], off
	s_waitcnt vmcnt(8)
	s_waitcnt lgkmcnt(0)
	s_barrier
; #define PG8_STAGE(bufoff, gbase, voff) do { _Pragma("unroll") for (int _i = 0; _i < 2; ++_i) \
;         __builtin_amdgcn_global_load_lds((const unsigned*)((const char*)(gbase) + (voff)[_i]), (PG8_LAS unsigned*)(lds + (bufoff) + ldsw + _i * 8192), 16, 0, 0); } while (0)
; #define PG8_LDA(dst, b, h) do { _Pragma("unroll") for (int m = 0; m < 4; ++m) _Pragma("unroll") for (int k = 0; k < 2; ++k) dst[m][k] = *(const PG8_LAS bf16x8*)(lds + PG8_SA(b, h) + aoff + m * 2048 + k * 1024); } while (0)
; #define PG8_LDB(dst, b, h) do { _Pragma("unroll") for (int n = 0; n < 2; ++n) _Pragma("unroll") for (int k = 0; k < 2; ++k) dst[n][k] = *(const PG8_LAS bf16x8*)(lds + PG8_SB(b, h) + boff + n * 2048 + k * 1024); } while (0)
; #define PG8_MMA(ai, bj, At, Bt) do { __builtin_amdgcn_s_setprio(1); _Pragma("unroll") for (int m = 0; m < 4; ++m) _Pragma("unroll") for (int n = 0; n < 2; ++n) _Pragma("unroll") for (int k = 0; k < 2; ++k) \
;         acc[ai][bj][m][n] = __builtin_amdgcn_mfma_f32_16x16x32_bf16(Bt[n][k], At[m][k], acc[ai][bj][m][n], 0, 0, 0); __builtin_amdgcn_s_setprio(0); } while (0)
; #define PG8_WAIT_V(n) asm volatile("s_waitcnt vmcnt(" #n ")" ::: "memory")
; #define PG8_WAIT_L(n) asm volatile("s_waitcnt lgkmcnt(" #n ")" ::: "memory")
; #define PG8_BAR __builtin_amdgcn_s_barrier()
; #define PG8_SCHED __builtin_amdgcn_sched_barrier(0)
; template <class Epi, class Sched, bool ALIGN_EPI = false, bool SP2 = false>
; __device__ __forceinline__ void gemm_phase(PG8_LAS unsigned char* lds, const Gemm g, const Sched& S, const Epi& E) {
;     ...
;             PG8_WAIT_V(8); PG8_WAIT_L(0); PG8_BAR; PG8_MMA(1, 0, At, B0); PG8_MMA(1, 1, At, B1); PG8_BAR; PG8_SCHED;
;             PG8_LDB(B0, 1, 0); PG8_LDB(B1, 1, 1); PG8_SCHED; PG8_LDA(At, 1, 0); PG8_STAGE(PG8_SA(0, 1), a2 + hstep, voffA);
;             PG8_WAIT_V(8); PG8_WAIT_L(0); PG8_BAR; PG8_MMA(0, 0, At, B0); PG8_MMA(0, 1, At, B1); PG8_BAR; PG8_SCHED;
	s_setprio 1
	v_mfma_f32_16x16x32_bf16 v[92:95], v[112:115], v[190:193], v[92:95]
	v_mfma_f32_16x16x32_bf16 v[88:91], v[152:155], v[190:193], v[88:91]
	v_mfma_f32_16x16x32_bf16 v[84:87], v[112:115], v[198:201], v[84:87]
	v_mfma_f32_16x16x32_bf16 v[80:83], v[152:155], v[198:201], v[80:83]
	v_mfma_f32_16x16x32_bf16 v[76:79], v[112:115], v[206:209], v[76:79]
	v_mfma_f32_16x16x32_bf16 v[72:75], v[152:155], v[206:209], v[72:75]
	v_mfma_f32_16x16x32_bf16 v[68:71], v[112:115], v[214:217], v[68:71]
	v_mfma_f32_16x16x32_bf16 v[64:67], v[152:155], v[214:217], v[64:67]
	v_mfma_f32_16x16x32_bf16 v[92:95], v[116:119], v[194:197], v[92:95]
	v_mfma_f32_16x16x32_bf16 v[88:91], v[156:159], v[194:197], v[88:91]
	v_mfma_f32_16x16x32_bf16 v[84:87], v[116:119], v[202:205], v[84:87]
	v_mfma_f32_16x16x32_bf16 v[80:83], v[156:159], v[202:205], v[80:83]
	v_mfma_f32_16x16x32_bf16 v[76:79], v[116:119], v[210:213], v[76:79]
	v_mfma_f32_16x16x32_bf16 v[72:75], v[156:159], v[210:213], v[72:75]
	v_mfma_f32_16x16x32_bf16 v[68:71], v[116:119], v[218:221], v[68:71]
	v_mfma_f32_16x16x32_bf16 v[64:67], v[156:159], v[218:221], v[64:67]
	s_setprio 0
	s_setprio 1
	v_mfma_f32_16x16x32_bf16 v[28:31], v[160:163], v[190:193], v[28:31]
	v_mfma_f32_16x16x32_bf16 v[24:27], v[174:177], v[190:193], v[24:27]
	v_mfma_f32_16x16x32_bf16 v[20:23], v[160:163], v[198:201], v[20:23]
	v_mfma_f32_16x16x32_bf16 v[16:19], v[174:177], v[198:201], v[16:19]
	v_mfma_f32_16x16x32_bf16 v[12:15], v[160:163], v[206:209], v[12:15]
	v_mfma_f32_16x16x32_bf16 v[8:11], v[174:177], v[206:209], v[8:11]
	v_mfma_f32_16x16x32_bf16 v[4:7], v[160:163], v[214:217], v[4:7]
	v_mfma_f32_16x16x32_bf16 v[0:3], v[174:177], v[214:217], v[0:3]
	v_mfma_f32_16x16x32_bf16 v[28:31], v[170:173], v[194:197], v[28:31]
	v_mfma_f32_16x16x32_bf16 v[24:27], v[178:181], v[194:197], v[24:27]
	v_mfma_f32_16x16x32_bf16 v[20:23], v[170:173], v[202:205], v[20:23]
	v_mfma_f32_16x16x32_bf16 v[16:19], v[178:181], v[202:205], v[16:19]
	v_mfma_f32_16x16x32_bf16 v[12:15], v[170:173], v[210:213], v[12:15]
	v_mfma_f32_16x16x32_bf16 v[8:11], v[178:181], v[210:213], v[8:11]
	v_mfma_f32_16x16x32_bf16 v[4:7], v[170:173], v[218:221], v[4:7]
	v_mfma_f32_16x16x32_bf16 v[0:3], v[178:181], v[218:221], v[0:3]
	s_setprio 0
	s_barrier
	s_add_i32 s3, 0, 0x18000
	s_add_i32 s45, 0, 0x1c000
	v_add_u32_e32 v156, s3, v165
	v_add_u32_e32 v178, s45, v165
	ds_read_b128 v[112:115], v156
	ds_read_b128 v[116:119], v156 offset:1024
	ds_read_b128 v[152:155], v156 offset:2048
	ds_read_b128 v[156:159], v156 offset:3072
	ds_read_b128 v[160:163], v178
	ds_read_b128 v[170:173], v178 offset:1024
	ds_read_b128 v[174:177], v178 offset:2048
	ds_read_b128 v[178:181], v178 offset:3072
	s_add_u32 s0, s38, 0x20000
	s_addc_u32 s1, s39, 0
	s_mov_b32 m0, s54
	v_lshl_add_u64 v[230:231], s[0:1], 0, v[136:137]
	ds_read_b128 v[190:193], v169 offset:32768
	ds_read_b128 v[194:197], v169 offset:33792
	ds_read_b128 v[198:201], v169 offset:34816
	ds_read_b128 v[202:205], v169 offset:35840
	ds_read_b128 v[206:209], v169 offset:36864
	ds_read_b128 v[210:213], v169 offset:37888
	ds_read_b128 v[214:217], v169 offset:38912
	ds_read_b128 v[218:221], v169 offset:39936
	global_load_lds_dwordx4 v[230:231], off
	v_lshl_add_u64 v[230:231], s[0:1], 0, v[140:141]
	s_mov_b32 m0, s55
	s_nop 0
	global_load_lds_dwordx4 v[230:231], off
	s_waitcnt vmcnt(8)
	s_waitcnt lgkmcnt(0)
	s_barrier
	s_setprio 1
	v_mfma_f32_16x16x32_bf16 v[132:135], v[112:115], v[190:193], v[132:135]
	v_mfma_f32_16x16x32_bf16 v[128:131], v[152:155], v[190:193], v[128:131]
	v_mfma_f32_16x16x32_bf16 v[124:127], v[112:115], v[198:201], v[124:127]
	v_mfma_f32_16x16x32_bf16 v[120:123], v[152:155], v[198:201], v[120:123]
	v_mfma_f32_16x16x32_bf16 v[108:111], v[112:115], v[206:209], v[108:111]
	v_mfma_f32_16x16x32_bf16 v[104:107], v[152:155], v[206:209], v[104:107]
	v_mfma_f32_16x16x32_bf16 v[100:103], v[112:115], v[214:217], v[100:103]
	v_mfma_f32_16x16x32_bf16 v[96:99], v[152:155], v[214:217], v[96:99]
	v_mfma_f32_16x16x32_bf16 v[132:135], v[116:119], v[194:197], v[132:135]
	v_mfma_f32_16x16x32_bf16 v[128:131], v[156:159], v[194:197], v[128:131]
	v_mfma_f32_16x16x32_bf16 v[124:127], v[116:119], v[202:205], v[124:127]
	v_mfma_f32_16x16x32_bf16 v[120:123], v[156:159], v[202:205], v[120:123]
	v_mfma_f32_16x16x32_bf16 v[108:111], v[116:119], v[210:213], v[108:111]
	v_mfma_f32_16x16x32_bf16 v[104:107], v[156:159], v[210:213], v[104:107]
	v_mfma_f32_16x16x32_bf16 v[100:103], v[116:119], v[218:221], v[100:103]
	v_mfma_f32_16x16x32_bf16 v[96:99], v[156:159], v[218:221], v[96:99]
	s_setprio 0
	s_setprio 1
	v_mfma_f32_16x16x32_bf16 v[60:63], v[160:163], v[190:193], v[60:63]
	v_mfma_f32_16x16x32_bf16 v[56:59], v[174:177], v[190:193], v[56:59]
	v_mfma_f32_16x16x32_bf16 v[52:55], v[160:163], v[198:201], v[52:55]
	v_mfma_f32_16x16x32_bf16 v[48:51], v[174:177], v[198:201], v[48:51]
	v_mfma_f32_16x16x32_bf16 v[44:47], v[160:163], v[206:209], v[44:47]
	v_mfma_f32_16x16x32_bf16 v[40:43], v[174:177], v[206:209], v[40:43]
	v_mfma_f32_16x16x32_bf16 v[36:39], v[160:163], v[214:217], v[36:39]
	v_mfma_f32_16x16x32_bf16 v[32:35], v[174:177], v[214:217], v[32:35]
	v_mfma_f32_16x16x32_bf16 v[60:63], v[170:173], v[194:197], v[60:63]
	v_mfma_f32_16x16x32_bf16 v[56:59], v[178:181], v[194:197], v[56:59]
	v_mfma_f32_16x16x32_bf16 v[52:55], v[170:173], v[202:205], v[52:55]
	v_mfma_f32_16x16x32_bf16 v[48:51], v[178:181], v[202:205], v[48:51]
	v_mfma_f32_16x16x32_bf16 v[44:47], v[170:173], v[210:213], v[44:47]
	v_mfma_f32_16x16x32_bf16 v[40:43], v[178:181], v[210:213], v[40:43]
	v_mfma_f32_16x16x32_bf16 v[36:39], v[170:173], v[218:221], v[36:39]
	v_mfma_f32_16x16x32_bf16 v[32:35], v[178:181], v[218:221], v[32:35]
	s_setprio 0
	s_barrier
; #define PG8_STAGE(bufoff, gbase, voff) do { _Pragma("unroll") for (int _i = 0; _i < 2; ++_i) \
;         __builtin_amdgcn_global_load_lds((const unsigned*)((const char*)(gbase) + (voff)[_i]), (PG8_LAS unsigned*)(lds + (bufoff) + ldsw + _i * 8192), 16, 0, 0); } while (0)
; #define PG8_LDA(dst, b, h) do { _Pragma("unroll") for (int m = 0; m < 4; ++m) _Pragma("unroll") for (int k = 0; k < 2; ++k) dst[m][k] = *(const PG8_LAS bf16x8*)(lds + PG8_SA(b, h) + aoff + m * 2048 + k * 1024); } while (0)
; #define PG8_MMA(ai, bj, At, Bt) do { __builtin_amdgcn_s_setprio(1); _Pragma("unroll") for (int m = 0; m < 4; ++m) _Pragma("unroll") for (int n = 0; n < 2; ++n) _Pragma("unroll") for (int k = 0; k < 2; ++k) \
;         acc[ai][bj][m][n] = __builtin_amdgcn_mfma_f32_16x16x32_bf16(Bt[n][k], At[m][k], acc[ai][bj][m][n], 0, 0, 0); __builtin_amdgcn_s_setprio(0); } while (0)
; #define PG8_WAIT_V(n) asm volatile("s_waitcnt vmcnt(" #n ")" ::: "memory")
; #define PG8_WAIT_L(n) asm volatile("s_waitcnt lgkmcnt(" #n ")" ::: "memory")
; #define PG8_BAR __builtin_amdgcn_s_barrier()
; #define PG8_SCHED __builtin_amdgcn_sched_barrier(0)
; template <class Epi, class Sched, bool ALIGN_EPI = false, bool SP2 = false>
; __device__ __forceinline__ void gemm_phase(PG8_LAS unsigned char* lds, const Gemm g, const Sched& S, const Epi& E) {
;     ...
;             PG8_LDA(At, 1, 1); PG8_STAGE(PG8_SB(1, 0), b3, voffB); PG8_STAGE(PG8_SB(1, 1), b3 + hstep, voffB); PG8_STAGE(PG8_SA(1, 0), a3, voffA);
;             PG8_WAIT_V(8); PG8_WAIT_L(0); PG8_BAR; PG8_MMA(1, 0, At, B0); PG8_MMA(1, 1, At, B1); PG8_BAR; PG8_SCHED;
;     ...
;         if constexpr (ALIGN_EPI) { if (wr == 0) PG8_BAR; }
	s_add_i32 s0, s3, s52
	v_lshl_add_u64 v[222:223], v[222:223], 0, s[18:19]
	s_mov_b32 m0, s0
	ds_read_b128 v[190:193], v169 offset:49152
	ds_read_b128 v[194:197], v169 offset:50176
	ds_read_b128 v[198:201], v169 offset:51200
	ds_read_b128 v[202:205], v169 offset:52224
	ds_read_b128 v[206:209], v169 offset:53248
	ds_read_b128 v[210:213], v169 offset:54272
	ds_read_b128 v[214:217], v169 offset:55296
	ds_read_b128 v[218:221], v169 offset:56320
	global_load_lds_dwordx4 v[222:223], off
	s_add_i32 m0, s0, 0x2000
	s_add_u32 s0, s36, 0x20080
	v_lshl_add_u64 v[222:223], v[224:225], 0, s[18:19]
	s_addc_u32 s1, s37, 0
	s_add_i32 s3, s45, s52
	global_load_lds_dwordx4 v[222:223], off
	v_lshl_add_u64 v[222:223], s[0:1], 0, v[138:139]
	s_mov_b32 m0, s3
	s_nop 0
	global_load_lds_dwordx4 v[222:223], off
	v_lshl_add_u64 v[222:223], s[0:1], 0, v[142:143]
	s_add_i32 m0, s3, 0x2000
	s_nop 0
	global_load_lds_dwordx4 v[222:223], off
	v_lshl_add_u64 v[222:223], v[226:227], 0, s[18:19]
	s_mov_b32 m0, s57
	s_nop 0
	global_load_lds_dwordx4 v[222:223], off
	v_lshl_add_u64 v[222:223], v[228:229], 0, s[18:19]
	s_mov_b32 m0, s58
	s_nop 0
	global_load_lds_dwordx4 v[222:223], off
	s_waitcnt vmcnt(8)
	s_waitcnt lgkmcnt(0)
	s_barrier
	s_setprio 1
	v_mfma_f32_16x16x32_bf16 v[92:95], v[112:115], v[190:193], v[92:95]
	v_mfma_f32_16x16x32_bf16 v[88:91], v[152:155], v[190:193], v[88:91]
	v_mfma_f32_16x16x32_bf16 v[84:87], v[112:115], v[198:201], v[84:87]
	v_mfma_f32_16x16x32_bf16 v[80:83], v[152:155], v[198:201], v[80:83]
	v_mfma_f32_16x16x32_bf16 v[76:79], v[112:115], v[206:209], v[76:79]
	v_mfma_f32_16x16x32_bf16 v[72:75], v[152:155], v[206:209], v[72:75]
	v_mfma_f32_16x16x32_bf16 v[68:71], v[112:115], v[214:217], v[68:71]
	v_mfma_f32_16x16x32_bf16 v[64:67], v[152:155], v[214:217], v[64:67]
	v_mfma_f32_16x16x32_bf16 v[92:95], v[116:119], v[194:197], v[92:95]
	v_mfma_f32_16x16x32_bf16 v[88:91], v[156:159], v[194:197], v[88:91]
	v_mfma_f32_16x16x32_bf16 v[84:87], v[116:119], v[202:205], v[84:87]
	v_mfma_f32_16x16x32_bf16 v[80:83], v[156:159], v[202:205], v[80:83]
	v_mfma_f32_16x16x32_bf16 v[76:79], v[116:119], v[210:213], v[76:79]
	v_mfma_f32_16x16x32_bf16 v[72:75], v[156:159], v[210:213], v[72:75]
	v_mfma_f32_16x16x32_bf16 v[68:71], v[116:119], v[218:221], v[68:71]
	v_mfma_f32_16x16x32_bf16 v[64:67], v[156:159], v[218:221], v[64:67]
	s_setprio 0
	s_setprio 1
	v_mfma_f32_16x16x32_bf16 v[28:31], v[160:163], v[190:193], v[28:31]
	v_mfma_f32_16x16x32_bf16 v[24:27], v[174:177], v[190:193], v[24:27]
	v_mfma_f32_16x16x32_bf16 v[20:23], v[160:163], v[198:201], v[20:23]
	v_mfma_f32_16x16x32_bf16 v[16:19], v[174:177], v[198:201], v[16:19]
	v_mfma_f32_16x16x32_bf16 v[12:15], v[160:163], v[206:209], v[12:15]
	v_mfma_f32_16x16x32_bf16 v[8:11], v[174:177], v[206:209], v[8:11]
	v_mfma_f32_16x16x32_bf16 v[4:7], v[160:163], v[214:217], v[4:7]
	v_mfma_f32_16x16x32_bf16 v[0:3], v[174:177], v[214:217], v[0:3]
	v_mfma_f32_16x16x32_bf16 v[28:31], v[170:173], v[194:197], v[28:31]
	v_mfma_f32_16x16x32_bf16 v[24:27], v[178:181], v[194:197], v[24:27]
	v_mfma_f32_16x16x32_bf16 v[20:23], v[170:173], v[202:205], v[20:23]
	v_mfma_f32_16x16x32_bf16 v[16:19], v[178:181], v[202:205], v[16:19]
	v_mfma_f32_16x16x32_bf16 v[12:15], v[170:173], v[210:213], v[12:15]
	v_mfma_f32_16x16x32_bf16 v[8:11], v[178:181], v[210:213], v[8:11]
	v_mfma_f32_16x16x32_bf16 v[4:7], v[170:173], v[218:221], v[4:7]
	v_mfma_f32_16x16x32_bf16 v[0:3], v[178:181], v[218:221], v[0:3]
	s_setprio 0
	s_barrier
	s_add_i32 s68, s68, 2
	s_add_u32 s34, s34, 0x100
	s_addc_u32 s35, s35, 0
	s_add_u32 s66, s66, 0x100
	s_addc_u32 s67, s67, 0
	s_cmp_gt_u32 s68, 5
	s_cbranch_scc0 .LBB0_760
	s_and_b64 vcc, exec, s[20:21]
	s_cbranch_vccz .LBB0_763
	s_barrier

; #define PG8_STAGE(bufoff, gbase, voff) do { _Pragma("unroll") for (int _i = 0; _i < 2; ++_i) \
;         __builtin_amdgcn_global_load_lds((const unsigned*)((const char*)(gbase) + (voff)[_i]), (PG8_LAS unsigned*)(lds + (bufoff) + ldsw + _i * 8192), 16, 0, 0); } while (0)
; #define PG8_LDA(dst, b, h) do { _Pragma("unroll") for (int m = 0; m < 4; ++m) _Pragma("unroll") for (int k = 0; k < 2; ++k) dst[m][k] = *(const PG8_LAS bf16x8*)(lds + PG8_SA(b, h) + aoff + m * 2048 + k * 1024); } while (0)
; #define PG8_LDB(dst, b, h) do { _Pragma("unroll") for (int n = 0; n < 2; ++n) _Pragma("unroll") for (int k = 0; k < 2; ++k) dst[n][k] = *(const PG8_LAS bf16x8*)(lds + PG8_SB(b, h) + boff + n * 2048 + k * 1024); } while (0)
; #define PG8_MMA(ai, bj, At, Bt) do { __builtin_amdgcn_s_setprio(1); _Pragma("unroll") for (int m = 0; m < 4; ++m) _Pragma("unroll") for (int n = 0; n < 2; ++n) _Pragma("unroll") for (int k = 0; k < 2; ++k) \
;         acc[ai][bj][m][n] = __builtin_amdgcn_mfma_f32_16x16x32_bf16(Bt[n][k], At[m][k], acc[ai][bj][m][n], 0, 0, 0); __builtin_amdgcn_s_setprio(0); } while (0)
; #define PG8_WAIT_V(n) asm volatile("s_waitcnt vmcnt(" #n ")" ::: "memory")
; template <class Epi, class Sched, bool ALIGN_EPI = false, bool SP2 = false>
; __device__ __forceinline__ void gemm_phase(PG8_LAS unsigned char* lds, const Gemm g, const Sched& S, const Epi& E) {
;     ...
;         const char* nA = has_next ? (const char*)g.A + (size_t)nxt.pm * tstep : cA; const char* nB = has_next ? (const char*)g.Bt + (size_t)nxt.pn * tstep : cB;
;         for (int t = 0; t < nt; t += 2) {
;             const bool last = (t == nt - 2);
;             const char* a1 = cA + (size_t)(t + 1) * kstep;
;             const char* a2 = last ? nA : cA + (size_t)(t + 2) * kstep; const char* b2 = last ? nB : cB + (size_t)(t + 2) * kstep;
;             const char* a3 = a2 + kstep; const char* b3 = b2 + kstep;
;             if (last && has_next) S.a_ready(nxt);
;             if constexpr (SP2) {
;             PG8_LDB(B0, 0, 0); PG8_LDB(B1, 0, 1); PG8_SCHED; PG8_LDA(At, 0, 0); PG8_STAGE(PG8_SA(1, 1), a1 + hstep, voffA);
;             PG8_WAIT_V(8); PG8_WAIT_L(0); PG8_BAR; PG8_MMA(0, 0, At, B0); PG8_MMA(0, 1, At, B1); PG8_BAR; PG8_SCHED;
;             PG8_LDA(At, 0, 1); PG8_STAGE(PG8_SB(0, 0), b2, voffB); PG8_STAGE(PG8_SB(0, 1), b2 + hstep, voffB); PG8_STAGE(PG8_SA(0, 0), a2, voffA);
.LBB0_929:
	ds_read_b128 v[150:153], v147
	ds_read_b128 v[154:157], v235
	ds_read_b128 v[158:161], v147 offset:2048
	ds_read_b128 v[162:165], v235 offset:2048
	ds_read_b128 v[166:169], v148
	ds_read_b128 v[170:173], v236
	ds_read_b128 v[174:177], v148 offset:2048
	ds_read_b128 v[178:181], v236 offset:2048
	s_add_u32 s3, s40, 0xfffc0080
	s_addc_u32 s45, s41, -1
	s_cmp_eq_u32 s76, 12
	s_cselect_b32 s53, s31, s45
	s_cselect_b32 s52, s72, s3
	s_cselect_b32 s51, s29, s75
	s_cselect_b32 s50, s73, s74
	v_lshl_add_u64 v[222:223], s[40:41], 0, v[136:137]
	s_add_i32 m0, s39, 0xc000
	ds_read_b128 v[190:193], v149
	ds_read_b128 v[194:197], v233
	ds_read_b128 v[198:201], v149 offset:2048
	ds_read_b128 v[202:205], v233 offset:2048
	ds_read_b128 v[206:209], v149 offset:4096
	ds_read_b128 v[210:213], v233 offset:4096
	ds_read_b128 v[214:217], v149 offset:6144
	ds_read_b128 v[218:221], v233 offset:6144
	global_load_lds_dwordx4 v[222:223], off
	v_lshl_add_u64 v[222:223], s[40:41], 0, v[138:139]
	s_add_i32 m0, s39, 0xe000
	s_nop 0
	global_load_lds_dwordx4 v[222:223], off
	s_waitcnt vmcnt(8)
	s_waitcnt lgkmcnt(0)
	s_barrier
	s_setprio 1
	v_mfma_f32_16x16x32_bf16 v[124:127], v[150:153], v[190:193], v[124:127]
	v_mfma_f32_16x16x32_bf16 v[120:123], v[158:161], v[190:193], v[120:123]
	v_mfma_f32_16x16x32_bf16 v[116:119], v[150:153], v[198:201], v[116:119]
	v_mfma_f32_16x16x32_bf16 v[112:115], v[158:161], v[198:201], v[112:115]
	v_mfma_f32_16x16x32_bf16 v[108:111], v[150:153], v[206:209], v[108:111]
	v_mfma_f32_16x16x32_bf16 v[104:107], v[158:161], v[206:209], v[104:107]
	v_mfma_f32_16x16x32_bf16 v[100:103], v[150:153], v[214:217], v[100:103]
	v_mfma_f32_16x16x32_bf16 v[96:99], v[158:161], v[214:217], v[96:99]
	v_mfma_f32_16x16x32_bf16 v[124:127], v[154:157], v[194:197], v[124:127]
	v_mfma_f32_16x16x32_bf16 v[120:123], v[162:165], v[194:197], v[120:123]
	v_mfma_f32_16x16x32_bf16 v[116:119], v[154:157], v[202:205], v[116:119]
	v_mfma_f32_16x16x32_bf16 v[112:115], v[162:165], v[202:205], v[112:115]
	v_mfma_f32_16x16x32_bf16 v[108:111], v[154:157], v[210:213], v[108:111]
	v_mfma_f32_16x16x32_bf16 v[104:107], v[162:165], v[210:213], v[104:107]
	v_mfma_f32_16x16x32_bf16 v[100:103], v[154:157], v[218:221], v[100:103]
	v_mfma_f32_16x16x32_bf16 v[96:99], v[162:165], v[218:221], v[96:99]
	s_setprio 0
	s_setprio 1
	v_mfma_f32_16x16x32_bf16 v[76:79], v[166:169], v[190:193], v[76:79]
	v_mfma_f32_16x16x32_bf16 v[68:71], v[174:177], v[190:193], v[68:71]
	v_mfma_f32_16x16x32_bf16 v[60:63], v[166:169], v[198:201], v[60:63]
	v_mfma_f32_16x16x32_bf16 v[52:55], v[174:177], v[198:201], v[52:55]
	v_mfma_f32_16x16x32_bf16 v[44:47], v[166:169], v[206:209], v[44:47]
	v_mfma_f32_16x16x32_bf16 v[40:43], v[174:177], v[206:209], v[40:43]
	v_mfma_f32_16x16x32_bf16 v[36:39], v[166:169], v[214:217], v[36:39]
	v_mfma_f32_16x16x32_bf16 v[32:35], v[174:177], v[214:217], v[32:35]
	v_mfma_f32_16x16x32_bf16 v[76:79], v[170:173], v[194:197], v[76:79]
	v_mfma_f32_16x16x32_bf16 v[68:71], v[178:181], v[194:197], v[68:71]
	v_mfma_f32_16x16x32_bf16 v[60:63], v[170:173], v[202:205], v[60:63]
	v_mfma_f32_16x16x32_bf16 v[52:55], v[178:181], v[202:205], v[52:55]
	v_mfma_f32_16x16x32_bf16 v[44:47], v[170:173], v[210:213], v[44:47]
	v_mfma_f32_16x16x32_bf16 v[40:43], v[178:181], v[210:213], v[40:43]
	v_mfma_f32_16x16x32_bf16 v[36:39], v[170:173], v[218:221], v[36:39]
	v_mfma_f32_16x16x32_bf16 v[32:35], v[178:181], v[218:221], v[32:35]
	s_setprio 0
	s_barrier
	s_add_i32 s3, s65, s56
	v_lshl_add_u64 v[222:223], s[50:51], 0, v[130:131]
	s_mov_b32 m0, s3
	ds_read_b128 v[190:193], v149 offset:16384
	ds_read_b128 v[194:197], v233 offset:16384
	ds_read_b128 v[198:201], v149 offset:18432
	ds_read_b128 v[202:205], v233 offset:18432
	ds_read_b128 v[206:209], v149 offset:20480
	ds_read_b128 v[210:213], v233 offset:20480
	ds_read_b128 v[214:217], v149 offset:22528
	ds_read_b128 v[218:221], v233 offset:22528
	global_load_lds_dwordx4 v[222:223], off
	s_add_i32 m0, s3, 0x2000
	s_add_u32 s70, s50, 0x40000
	v_lshl_add_u64 v[224:225], s[50:51], 0, v[134:135]
	s_addc_u32 s71, s51, 0
	s_add_i32 s3, s66, s56
	global_load_lds_dwordx4 v[224:225], off
	v_lshl_add_u64 v[226:227], s[70:71], 0, v[130:131]
	s_mov_b32 m0, s3
	v_lshl_add_u64 v[228:229], s[52:53], 0, v[132:133]
	global_load_lds_dwordx4 v[226:227], off
	v_lshl_add_u64 v[226:227], s[70:71], 0, v[134:135]
	s_add_i32 m0, s3, 0x2000
	s_nop 0
	global_load_lds_dwordx4 v[226:227], off
	v_lshl_add_u64 v[226:227], s[52:53], 0, v[128:129]
	s_mov_b32 m0, s39
	s_nop 0
	global_load_lds_dwordx4 v[226:227], off
	s_mov_b32 m0, s57
	s_nop 0
	global_load_lds_dwordx4 v[228:229], off
	s_waitcnt vmcnt(8)
	s_waitcnt lgkmcnt(0)
	s_barrier
; #define PG8_STAGE(bufoff, gbase, voff) do { _Pragma("unroll") for (int _i = 0; _i < 2; ++_i) \
;         __builtin_amdgcn_global_load_lds((const unsigned*)((const char*)(gbase) + (voff)[_i]), (PG8_LAS unsigned*)(lds + (bufoff) + ldsw + _i * 8192), 16, 0, 0); } while (0)
; #define PG8_LDA(dst, b, h) do { _Pragma("unroll") for (int m = 0; m < 4; ++m) _Pragma("unroll") for (int k = 0; k < 2; ++k) dst[m][k] = *(const PG8_LAS bf16x8*)(lds + PG8_SA(b, h) + aoff + m * 2048 + k * 1024); } while (0)
; #define PG8_LDB(dst, b, h) do { _Pragma("unroll") for (int n = 0; n < 2; ++n) _Pragma("unroll") for (int k = 0; k < 2; ++k) dst[n][k] = *(const PG8_LAS bf16x8*)(lds + PG8_SB(b, h) + boff + n * 2048 + k * 1024); } while (0)
; #define PG8_MMA(ai, bj, At, Bt) do { __builtin_amdgcn_s_setprio(1); _Pragma("unroll") for (int m = 0; m < 4; ++m) _Pragma("unroll") for (int n = 0; n < 2; ++n) _Pragma("unroll") for (int k = 0; k < 2; ++k) \
;         acc[ai][bj][m][n] = __builtin_amdgcn_mfma_f32_16x16x32_bf16(Bt[n][k], At[m][k], acc[ai][bj][m][n], 0, 0, 0); __builtin_amdgcn_s_setprio(0); } while (0)
; #define PG8_WAIT_V(n) asm volatile("s_waitcnt vmcnt(" #n ")" ::: "memory")
; #define PG8_WAIT_L(n) asm volatile("s_waitcnt lgkmcnt(" #n ")" ::: "memory")
; #define PG8_BAR __builtin_amdgcn_s_barrier()
; #define PG8_SCHED __builtin_amdgcn_sched_barrier(0)
; template <class Epi, class Sched, bool ALIGN_EPI = false, bool SP2 = false>
; __device__ __forceinline__ void gemm_phase(PG8_LAS unsigned char* lds, const Gemm g, const Sched& S, const Epi& E) {
;     ...
;             PG8_WAIT_V(8); PG8_WAIT_L(0); PG8_BAR; PG8_MMA(1, 0, At, B0); PG8_MMA(1, 1, At, B1); PG8_BAR; PG8_SCHED;
;             PG8_LDB(B0, 1, 0); PG8_LDB(B1, 1, 1); PG8_SCHED; PG8_LDA(At, 1, 0); PG8_STAGE(PG8_SA(0, 1), a2 + hstep, voffA);
;             PG8_WAIT_V(8); PG8_WAIT_L(0); PG8_BAR; PG8_MMA(0, 0, At, B0); PG8_MMA(0, 1, At, B1); PG8_BAR; PG8_SCHED;
	s_setprio 1
	v_mfma_f32_16x16x32_bf16 v[92:95], v[150:153], v[190:193], v[92:95]
	v_mfma_f32_16x16x32_bf16 v[88:91], v[158:161], v[190:193], v[88:91]
	v_mfma_f32_16x16x32_bf16 v[84:87], v[150:153], v[198:201], v[84:87]
	v_mfma_f32_16x16x32_bf16 v[80:83], v[158:161], v[198:201], v[80:83]
	v_mfma_f32_16x16x32_bf16 v[72:75], v[150:153], v[206:209], v[72:75]
	v_mfma_f32_16x16x32_bf16 v[64:67], v[158:161], v[206:209], v[64:67]
	v_mfma_f32_16x16x32_bf16 v[56:59], v[150:153], v[214:217], v[56:59]
	v_mfma_f32_16x16x32_bf16 v[48:51], v[158:161], v[214:217], v[48:51]
	v_mfma_f32_16x16x32_bf16 v[92:95], v[154:157], v[194:197], v[92:95]
	v_mfma_f32_16x16x32_bf16 v[88:91], v[162:165], v[194:197], v[88:91]
	v_mfma_f32_16x16x32_bf16 v[84:87], v[154:157], v[202:205], v[84:87]
	v_mfma_f32_16x16x32_bf16 v[80:83], v[162:165], v[202:205], v[80:83]
	v_mfma_f32_16x16x32_bf16 v[72:75], v[154:157], v[210:213], v[72:75]
	v_mfma_f32_16x16x32_bf16 v[64:67], v[162:165], v[210:213], v[64:67]
	v_mfma_f32_16x16x32_bf16 v[56:59], v[154:157], v[218:221], v[56:59]
	v_mfma_f32_16x16x32_bf16 v[48:51], v[162:165], v[218:221], v[48:51]
	s_setprio 0
	s_setprio 1
	v_mfma_f32_16x16x32_bf16 v[28:31], v[166:169], v[190:193], v[28:31]
	v_mfma_f32_16x16x32_bf16 v[24:27], v[174:177], v[190:193], v[24:27]
	v_mfma_f32_16x16x32_bf16 v[20:23], v[166:169], v[198:201], v[20:23]
	v_mfma_f32_16x16x32_bf16 v[16:19], v[174:177], v[198:201], v[16:19]
	v_mfma_f32_16x16x32_bf16 v[12:15], v[166:169], v[206:209], v[12:15]
	v_mfma_f32_16x16x32_bf16 v[8:11], v[174:177], v[206:209], v[8:11]
	v_mfma_f32_16x16x32_bf16 v[4:7], v[166:169], v[214:217], v[4:7]
	v_mfma_f32_16x16x32_bf16 v[0:3], v[174:177], v[214:217], v[0:3]
	v_mfma_f32_16x16x32_bf16 v[28:31], v[170:173], v[194:197], v[28:31]
	v_mfma_f32_16x16x32_bf16 v[24:27], v[178:181], v[194:197], v[24:27]
	v_mfma_f32_16x16x32_bf16 v[20:23], v[170:173], v[202:205], v[20:23]
	v_mfma_f32_16x16x32_bf16 v[16:19], v[178:181], v[202:205], v[16:19]
	v_mfma_f32_16x16x32_bf16 v[12:15], v[170:173], v[210:213], v[12:15]
	v_mfma_f32_16x16x32_bf16 v[8:11], v[178:181], v[210:213], v[8:11]
	v_mfma_f32_16x16x32_bf16 v[4:7], v[170:173], v[218:221], v[4:7]
	v_mfma_f32_16x16x32_bf16 v[0:3], v[178:181], v[218:221], v[0:3]
	s_setprio 0
	s_barrier
	s_add_i32 s3, 0, 0x18000
	s_add_i32 s45, 0, 0x1c000
	v_add_u32_e32 v162, s3, v145
	v_add_u32_e32 v237, s3, v234
	v_add_u32_e32 v178, s45, v145
	v_add_u32_e32 v238, s45, v234
	ds_read_b128 v[150:153], v162
	ds_read_b128 v[154:157], v237
	ds_read_b128 v[158:161], v162 offset:2048
	ds_read_b128 v[162:165], v237 offset:2048
	ds_read_b128 v[166:169], v178
	ds_read_b128 v[170:173], v238
	ds_read_b128 v[174:177], v178 offset:2048
	ds_read_b128 v[178:181], v238 offset:2048
	s_add_u32 s52, s52, 0x40000
	s_addc_u32 s53, s53, 0
	s_mov_b32 m0, s58
	v_lshl_add_u64 v[230:231], s[52:53], 0, v[128:129]
	ds_read_b128 v[190:193], v149 offset:32768
	ds_read_b128 v[194:197], v233 offset:32768
	ds_read_b128 v[198:201], v149 offset:34816
	ds_read_b128 v[202:205], v233 offset:34816
	ds_read_b128 v[206:209], v149 offset:36864
	ds_read_b128 v[210:213], v233 offset:36864
	ds_read_b128 v[214:217], v149 offset:38912
	ds_read_b128 v[218:221], v233 offset:38912
	global_load_lds_dwordx4 v[230:231], off
	v_lshl_add_u64 v[230:231], s[52:53], 0, v[132:133]
	s_mov_b32 m0, s59
	s_nop 0
	global_load_lds_dwordx4 v[230:231], off
	s_waitcnt vmcnt(8)
	s_waitcnt lgkmcnt(0)
	s_barrier
	s_setprio 1
	v_mfma_f32_16x16x32_bf16 v[124:127], v[150:153], v[190:193], v[124:127]
	v_mfma_f32_16x16x32_bf16 v[120:123], v[158:161], v[190:193], v[120:123]
	v_mfma_f32_16x16x32_bf16 v[116:119], v[150:153], v[198:201], v[116:119]
	v_mfma_f32_16x16x32_bf16 v[112:115], v[158:161], v[198:201], v[112:115]
	v_mfma_f32_16x16x32_bf16 v[108:111], v[150:153], v[206:209], v[108:111]
	v_mfma_f32_16x16x32_bf16 v[104:107], v[158:161], v[206:209], v[104:107]
	v_mfma_f32_16x16x32_bf16 v[100:103], v[150:153], v[214:217], v[100:103]
	v_mfma_f32_16x16x32_bf16 v[96:99], v[158:161], v[214:217], v[96:99]
	v_mfma_f32_16x16x32_bf16 v[124:127], v[154:157], v[194:197], v[124:127]
	v_mfma_f32_16x16x32_bf16 v[120:123], v[162:165], v[194:197], v[120:123]
	v_mfma_f32_16x16x32_bf16 v[116:119], v[154:157], v[202:205], v[116:119]
	v_mfma_f32_16x16x32_bf16 v[112:115], v[162:165], v[202:205], v[112:115]
	v_mfma_f32_16x16x32_bf16 v[108:111], v[154:157], v[210:213], v[108:111]
	v_mfma_f32_16x16x32_bf16 v[104:107], v[162:165], v[210:213], v[104:107]
	v_mfma_f32_16x16x32_bf16 v[100:103], v[154:157], v[218:221], v[100:103]
	v_mfma_f32_16x16x32_bf16 v[96:99], v[162:165], v[218:221], v[96:99]
	s_setprio 0
	s_setprio 1
	v_mfma_f32_16x16x32_bf16 v[76:79], v[166:169], v[190:193], v[76:79]
	v_mfma_f32_16x16x32_bf16 v[68:71], v[174:177], v[190:193], v[68:71]
	v_mfma_f32_16x16x32_bf16 v[60:63], v[166:169], v[198:201], v[60:63]
	v_mfma_f32_16x16x32_bf16 v[52:55], v[174:177], v[198:201], v[52:55]
	v_mfma_f32_16x16x32_bf16 v[44:47], v[166:169], v[206:209], v[44:47]
	v_mfma_f32_16x16x32_bf16 v[40:43], v[174:177], v[206:209], v[40:43]
	v_mfma_f32_16x16x32_bf16 v[36:39], v[166:169], v[214:217], v[36:39]
	v_mfma_f32_16x16x32_bf16 v[32:35], v[174:177], v[214:217], v[32:35]
	v_mfma_f32_16x16x32_bf16 v[76:79], v[170:173], v[194:197], v[76:79]
	v_mfma_f32_16x16x32_bf16 v[68:71], v[178:181], v[194:197], v[68:71]
	v_mfma_f32_16x16x32_bf16 v[60:63], v[170:173], v[202:205], v[60:63]
	v_mfma_f32_16x16x32_bf16 v[52:55], v[178:181], v[202:205], v[52:55]
	v_mfma_f32_16x16x32_bf16 v[44:47], v[170:173], v[210:213], v[44:47]
	v_mfma_f32_16x16x32_bf16 v[40:43], v[178:181], v[210:213], v[40:43]
	v_mfma_f32_16x16x32_bf16 v[36:39], v[170:173], v[218:221], v[36:39]
	v_mfma_f32_16x16x32_bf16 v[32:35], v[178:181], v[218:221], v[32:35]
	s_setprio 0
	s_barrier
; #define PG8_STAGE(bufoff, gbase, voff) do { _Pragma("unroll") for (int _i = 0; _i < 2; ++_i) \
;         __builtin_amdgcn_global_load_lds((const unsigned*)((const char*)(gbase) + (voff)[_i]), (PG8_LAS unsigned*)(lds + (bufoff) + ldsw + _i * 8192), 16, 0, 0); } while (0)
; #define PG8_LDA(dst, b, h) do { _Pragma("unroll") for (int m = 0; m < 4; ++m) _Pragma("unroll") for (int k = 0; k < 2; ++k) dst[m][k] = *(const PG8_LAS bf16x8*)(lds + PG8_SA(b, h) + aoff + m * 2048 + k * 1024); } while (0)
; #define PG8_MMA(ai, bj, At, Bt) do { __builtin_amdgcn_s_setprio(1); _Pragma("unroll") for (int m = 0; m < 4; ++m) _Pragma("unroll") for (int n = 0; n < 2; ++n) _Pragma("unroll") for (int k = 0; k < 2; ++k) \
;         acc[ai][bj][m][n] = __builtin_amdgcn_mfma_f32_16x16x32_bf16(Bt[n][k], At[m][k], acc[ai][bj][m][n], 0, 0, 0); __builtin_amdgcn_s_setprio(0); } while (0)
; #define PG8_WAIT_V(n) asm volatile("s_waitcnt vmcnt(" #n ")" ::: "memory")
; #define PG8_WAIT_L(n) asm volatile("s_waitcnt lgkmcnt(" #n ")" ::: "memory")
; #define PG8_BAR __builtin_amdgcn_s_barrier()
; #define PG8_SCHED __builtin_amdgcn_sched_barrier(0)
; template <class Epi, class Sched, bool ALIGN_EPI = false, bool SP2 = false>
; __device__ __forceinline__ void gemm_phase(PG8_LAS unsigned char* lds, const Gemm g, const Sched& S, const Epi& E) {
;     ...
;             PG8_LDA(At, 1, 1); PG8_STAGE(PG8_SB(1, 0), b3, voffB); PG8_STAGE(PG8_SB(1, 1), b3 + hstep, voffB); PG8_STAGE(PG8_SA(1, 0), a3, voffA);
;             PG8_WAIT_V(8); PG8_WAIT_L(0); PG8_BAR; PG8_MMA(1, 0, At, B0); PG8_MMA(1, 1, At, B1); PG8_BAR; PG8_SCHED;
;     ...
;         if constexpr (ALIGN_EPI) { if (wr == 0) PG8_BAR; }
	s_add_i32 s3, s3, s56
	v_lshl_add_u64 v[222:223], v[222:223], 0, s[18:19]
	s_mov_b32 m0, s3
	ds_read_b128 v[190:193], v149 offset:49152
	ds_read_b128 v[194:197], v233 offset:49152
	ds_read_b128 v[198:201], v149 offset:51200
	ds_read_b128 v[202:205], v233 offset:51200
	ds_read_b128 v[206:209], v149 offset:53248
	ds_read_b128 v[210:213], v233 offset:53248
	ds_read_b128 v[214:217], v149 offset:55296
	ds_read_b128 v[218:221], v233 offset:55296
	global_load_lds_dwordx4 v[222:223], off
	s_add_i32 m0, s3, 0x2000
	s_add_u32 s50, s50, 0x40080
	v_lshl_add_u64 v[222:223], v[224:225], 0, s[18:19]
	s_addc_u32 s51, s51, 0
	s_add_i32 s3, s45, s56
	global_load_lds_dwordx4 v[222:223], off
	v_lshl_add_u64 v[222:223], s[50:51], 0, v[130:131]
	s_mov_b32 m0, s3
	s_nop 0
	global_load_lds_dwordx4 v[222:223], off
	v_lshl_add_u64 v[222:223], s[50:51], 0, v[134:135]
	s_add_i32 m0, s3, 0x2000
	s_nop 0
	global_load_lds_dwordx4 v[222:223], off
	v_lshl_add_u64 v[222:223], v[226:227], 0, s[18:19]
	s_mov_b32 m0, s61
	s_nop 0
	global_load_lds_dwordx4 v[222:223], off
	v_lshl_add_u64 v[222:223], v[228:229], 0, s[18:19]
	s_mov_b32 m0, s62
	s_nop 0
	global_load_lds_dwordx4 v[222:223], off
	s_waitcnt vmcnt(8)
	s_waitcnt lgkmcnt(0)
	s_barrier
	s_setprio 1
	v_mfma_f32_16x16x32_bf16 v[92:95], v[150:153], v[190:193], v[92:95]
	v_mfma_f32_16x16x32_bf16 v[88:91], v[158:161], v[190:193], v[88:91]
	v_mfma_f32_16x16x32_bf16 v[84:87], v[150:153], v[198:201], v[84:87]
	v_mfma_f32_16x16x32_bf16 v[80:83], v[158:161], v[198:201], v[80:83]
	v_mfma_f32_16x16x32_bf16 v[72:75], v[150:153], v[206:209], v[72:75]
	v_mfma_f32_16x16x32_bf16 v[64:67], v[158:161], v[206:209], v[64:67]
	v_mfma_f32_16x16x32_bf16 v[56:59], v[150:153], v[214:217], v[56:59]
	v_mfma_f32_16x16x32_bf16 v[48:51], v[158:161], v[214:217], v[48:51]
	v_mfma_f32_16x16x32_bf16 v[92:95], v[154:157], v[194:197], v[92:95]
	v_mfma_f32_16x16x32_bf16 v[88:91], v[162:165], v[194:197], v[88:91]
	v_mfma_f32_16x16x32_bf16 v[84:87], v[154:157], v[202:205], v[84:87]
	v_mfma_f32_16x16x32_bf16 v[80:83], v[162:165], v[202:205], v[80:83]
	v_mfma_f32_16x16x32_bf16 v[72:75], v[154:157], v[210:213], v[72:75]
	v_mfma_f32_16x16x32_bf16 v[64:67], v[162:165], v[210:213], v[64:67]
	v_mfma_f32_16x16x32_bf16 v[56:59], v[154:157], v[218:221], v[56:59]
	v_mfma_f32_16x16x32_bf16 v[48:51], v[162:165], v[218:221], v[48:51]
	s_setprio 0
	s_setprio 1
	v_mfma_f32_16x16x32_bf16 v[28:31], v[166:169], v[190:193], v[28:31]
	v_mfma_f32_16x16x32_bf16 v[24:27], v[174:177], v[190:193], v[24:27]
	v_mfma_f32_16x16x32_bf16 v[20:23], v[166:169], v[198:201], v[20:23]
	v_mfma_f32_16x16x32_bf16 v[16:19], v[174:177], v[198:201], v[16:19]
	v_mfma_f32_16x16x32_bf16 v[12:15], v[166:169], v[206:209], v[12:15]
	v_mfma_f32_16x16x32_bf16 v[8:11], v[174:177], v[206:209], v[8:11]
	v_mfma_f32_16x16x32_bf16 v[4:7], v[166:169], v[214:217], v[4:7]
	v_mfma_f32_16x16x32_bf16 v[0:3], v[174:177], v[214:217], v[0:3]
	v_mfma_f32_16x16x32_bf16 v[28:31], v[170:173], v[194:197], v[28:31]
	v_mfma_f32_16x16x32_bf16 v[24:27], v[178:181], v[194:197], v[24:27]
	v_mfma_f32_16x16x32_bf16 v[20:23], v[170:173], v[202:205], v[20:23]
	v_mfma_f32_16x16x32_bf16 v[16:19], v[178:181], v[202:205], v[16:19]
	v_mfma_f32_16x16x32_bf16 v[12:15], v[170:173], v[210:213], v[12:15]
	v_mfma_f32_16x16x32_bf16 v[8:11], v[178:181], v[210:213], v[8:11]
	v_mfma_f32_16x16x32_bf16 v[4:7], v[170:173], v[218:221], v[4:7]
	v_mfma_f32_16x16x32_bf16 v[0:3], v[178:181], v[218:221], v[0:3]
	s_setprio 0
	s_barrier
	s_add_i32 s76, s76, 2
	s_add_u32 s40, s40, 0x100
	s_addc_u32 s41, s41, 0
	s_add_u32 s74, s74, 0x100
	s_addc_u32 s75, s75, 0
	s_cmp_gt_u32 s76, 13
	s_cbranch_scc0 .LBB0_929
	s_and_b64 vcc, exec, s[20:21]
	s_cbranch_vccz .LBB0_932
	s_barrier

; #define PG8_STAGE(bufoff, gbase, voff) do { _Pragma("unroll") for (int _i = 0; _i < 2; ++_i) \
;         __builtin_amdgcn_global_load_lds((const unsigned*)((const char*)(gbase) + (voff)[_i]), (PG8_LAS unsigned*)(lds + (bufoff) + ldsw + _i * 8192), 16, 0, 0); } while (0)
; #define PG8_LDA(dst, b, h) do { _Pragma("unroll") for (int m = 0; m < 4; ++m) _Pragma("unroll") for (int k = 0; k < 2; ++k) dst[m][k] = *(const PG8_LAS bf16x8*)(lds + PG8_SA(b, h) + aoff + m * 2048 + k * 1024); } while (0)
; #define PG8_LDB(dst, b, h) do { _Pragma("unroll") for (int n = 0; n < 2; ++n) _Pragma("unroll") for (int k = 0; k < 2; ++k) dst[n][k] = *(const PG8_LAS bf16x8*)(lds + PG8_SB(b, h) + boff + n * 2048 + k * 1024); } while (0)
; #define PG8_MMA(ai, bj, At, Bt) do { __builtin_amdgcn_s_setprio(1); _Pragma("unroll") for (int m = 0; m < 4; ++m) _Pragma("unroll") for (int n = 0; n < 2; ++n) _Pragma("unroll") for (int k = 0; k < 2; ++k) \
;         acc[ai][bj][m][n] = __builtin_amdgcn_mfma_f32_16x16x32_bf16(Bt[n][k], At[m][k], acc[ai][bj][m][n], 0, 0, 0); __builtin_amdgcn_s_setprio(0); } while (0)
; #define PG8_WAIT_V(n) asm volatile("s_waitcnt vmcnt(" #n ")" ::: "memory")
; template <class Epi, class Sched, bool ALIGN_EPI = false, bool SP2 = false>
; __device__ __forceinline__ void gemm_phase(PG8_LAS unsigned char* lds, const Gemm g, const Sched& S, const Epi& E) {
;     ...
;         const char* nA = has_next ? (const char*)g.A + (size_t)nxt.pm * tstep : cA; const char* nB = has_next ? (const char*)g.Bt + (size_t)nxt.pn * tstep : cB;
;         for (int t = 0; t < nt; t += 2) {
;             const bool last = (t == nt - 2);
;             const char* a1 = cA + (size_t)(t + 1) * kstep;
;             const char* a2 = last ? nA : cA + (size_t)(t + 2) * kstep; const char* b2 = last ? nB : cB + (size_t)(t + 2) * kstep;
;             const char* a3 = a2 + kstep; const char* b3 = b2 + kstep;
;             if (last && has_next) S.a_ready(nxt);
;             if constexpr (SP2) {
;             PG8_LDB(B0, 0, 0); PG8_LDB(B1, 0, 1); PG8_SCHED; PG8_LDA(At, 0, 0); PG8_STAGE(PG8_SA(1, 1), a1 + hstep, voffA);
;             PG8_WAIT_V(8); PG8_WAIT_L(0); PG8_BAR; PG8_MMA(0, 0, At, B0); PG8_MMA(0, 1, At, B1); PG8_BAR; PG8_SCHED;
;             PG8_LDA(At, 0, 1); PG8_STAGE(PG8_SB(0, 0), b2, voffB); PG8_STAGE(PG8_SB(0, 1), b2 + hstep, voffB); PG8_STAGE(PG8_SA(0, 0), a2, voffA);
.LBB0_1118:
	ds_read_b128 v[144:147], v151
	ds_read_b128 v[154:157], v235
	ds_read_b128 v[158:161], v151 offset:2048
	ds_read_b128 v[162:165], v235 offset:2048
	ds_read_b128 v[166:169], v152
	ds_read_b128 v[170:173], v236
	ds_read_b128 v[174:177], v152 offset:2048
	ds_read_b128 v[178:181], v236 offset:2048
	s_add_u32 s0, s30, 0xfffc0080
	s_addc_u32 s1, s31, -1
	s_cmp_eq_u32 s64, 12
	s_cselect_b32 s37, s23, s1
	s_cselect_b32 s36, s60, s0
	s_cselect_b32 s35, s21, s63
	s_cselect_b32 s34, s61, s62
	v_lshl_add_u64 v[222:223], s[30:31], 0, v[136:137]
	s_add_i32 m0, s29, 0xc000
	ds_read_b128 v[190:193], v153
	ds_read_b128 v[194:197], v233
	ds_read_b128 v[198:201], v153 offset:2048
	ds_read_b128 v[202:205], v233 offset:2048
	ds_read_b128 v[206:209], v153 offset:4096
	ds_read_b128 v[210:213], v233 offset:4096
	ds_read_b128 v[214:217], v153 offset:6144
	ds_read_b128 v[218:221], v233 offset:6144
	global_load_lds_dwordx4 v[222:223], off
	v_lshl_add_u64 v[222:223], s[30:31], 0, v[138:139]
	s_add_i32 m0, s29, 0xe000
	s_nop 0
	global_load_lds_dwordx4 v[222:223], off
	s_waitcnt vmcnt(8)
	s_waitcnt lgkmcnt(0)
	s_barrier
	s_setprio 1
	v_mfma_f32_16x16x32_bf16 v[124:127], v[144:147], v[190:193], v[124:127]
	v_mfma_f32_16x16x32_bf16 v[120:123], v[158:161], v[190:193], v[120:123]
	v_mfma_f32_16x16x32_bf16 v[108:111], v[144:147], v[198:201], v[108:111]
	v_mfma_f32_16x16x32_bf16 v[104:107], v[158:161], v[198:201], v[104:107]
	v_mfma_f32_16x16x32_bf16 v[92:95], v[144:147], v[206:209], v[92:95]
	v_mfma_f32_16x16x32_bf16 v[88:91], v[158:161], v[206:209], v[88:91]
	v_mfma_f32_16x16x32_bf16 v[76:79], v[144:147], v[214:217], v[76:79]
	v_mfma_f32_16x16x32_bf16 v[72:75], v[158:161], v[214:217], v[72:75]
	v_mfma_f32_16x16x32_bf16 v[124:127], v[154:157], v[194:197], v[124:127]
	v_mfma_f32_16x16x32_bf16 v[120:123], v[162:165], v[194:197], v[120:123]
	v_mfma_f32_16x16x32_bf16 v[108:111], v[154:157], v[202:205], v[108:111]
	v_mfma_f32_16x16x32_bf16 v[104:107], v[162:165], v[202:205], v[104:107]
	v_mfma_f32_16x16x32_bf16 v[92:95], v[154:157], v[210:213], v[92:95]
	v_mfma_f32_16x16x32_bf16 v[88:91], v[162:165], v[210:213], v[88:91]
	v_mfma_f32_16x16x32_bf16 v[76:79], v[154:157], v[218:221], v[76:79]
	v_mfma_f32_16x16x32_bf16 v[72:75], v[162:165], v[218:221], v[72:75]
	s_setprio 0
	s_setprio 1
	v_mfma_f32_16x16x32_bf16 v[116:119], v[166:169], v[190:193], v[116:119]
	v_mfma_f32_16x16x32_bf16 v[112:115], v[174:177], v[190:193], v[112:115]
	v_mfma_f32_16x16x32_bf16 v[100:103], v[166:169], v[198:201], v[100:103]
	v_mfma_f32_16x16x32_bf16 v[96:99], v[174:177], v[198:201], v[96:99]
	v_mfma_f32_16x16x32_bf16 v[84:87], v[166:169], v[206:209], v[84:87]
	v_mfma_f32_16x16x32_bf16 v[80:83], v[174:177], v[206:209], v[80:83]
	v_mfma_f32_16x16x32_bf16 v[68:71], v[166:169], v[214:217], v[68:71]
	v_mfma_f32_16x16x32_bf16 v[64:67], v[174:177], v[214:217], v[64:67]
	v_mfma_f32_16x16x32_bf16 v[116:119], v[170:173], v[194:197], v[116:119]
	v_mfma_f32_16x16x32_bf16 v[112:115], v[178:181], v[194:197], v[112:115]
	v_mfma_f32_16x16x32_bf16 v[100:103], v[170:173], v[202:205], v[100:103]
	v_mfma_f32_16x16x32_bf16 v[96:99], v[178:181], v[202:205], v[96:99]
	v_mfma_f32_16x16x32_bf16 v[84:87], v[170:173], v[210:213], v[84:87]
	v_mfma_f32_16x16x32_bf16 v[80:83], v[178:181], v[210:213], v[80:83]
	v_mfma_f32_16x16x32_bf16 v[68:71], v[170:173], v[218:221], v[68:71]
	v_mfma_f32_16x16x32_bf16 v[64:67], v[178:181], v[218:221], v[64:67]
	s_setprio 0
	s_barrier
	s_add_i32 s0, s56, s42
	v_lshl_add_u64 v[222:223], s[34:35], 0, v[132:133]
	s_mov_b32 m0, s0
	ds_read_b128 v[190:193], v153 offset:16384
	ds_read_b128 v[194:197], v233 offset:16384
	ds_read_b128 v[198:201], v153 offset:18432
	ds_read_b128 v[202:205], v233 offset:18432
	ds_read_b128 v[206:209], v153 offset:20480
	ds_read_b128 v[210:213], v233 offset:20480
	ds_read_b128 v[214:217], v153 offset:22528
	ds_read_b128 v[218:221], v233 offset:22528
	global_load_lds_dwordx4 v[222:223], off
	s_add_i32 m0, s0, 0x2000
	s_add_u32 s0, s34, 0x40000
	v_lshl_add_u64 v[224:225], s[34:35], 0, v[128:129]
	s_addc_u32 s1, s35, 0
	s_add_i32 s3, s57, s42
	global_load_lds_dwordx4 v[224:225], off
	v_lshl_add_u64 v[226:227], s[0:1], 0, v[132:133]
	s_mov_b32 m0, s3
	v_lshl_add_u64 v[228:229], s[36:37], 0, v[130:131]
	global_load_lds_dwordx4 v[226:227], off
	v_lshl_add_u64 v[226:227], s[0:1], 0, v[128:129]
	s_add_i32 m0, s3, 0x2000
	s_nop 0
	global_load_lds_dwordx4 v[226:227], off
	v_lshl_add_u64 v[226:227], s[36:37], 0, v[134:135]
	s_mov_b32 m0, s29
	s_nop 0
	global_load_lds_dwordx4 v[226:227], off
	s_mov_b32 m0, s48
	s_nop 0
	global_load_lds_dwordx4 v[228:229], off
	s_waitcnt vmcnt(8)
	s_waitcnt lgkmcnt(0)
	s_barrier
; #define PG8_STAGE(bufoff, gbase, voff) do { _Pragma("unroll") for (int _i = 0; _i < 2; ++_i) \
;         __builtin_amdgcn_global_load_lds((const unsigned*)((const char*)(gbase) + (voff)[_i]), (PG8_LAS unsigned*)(lds + (bufoff) + ldsw + _i * 8192), 16, 0, 0); } while (0)
; #define PG8_LDA(dst, b, h) do { _Pragma("unroll") for (int m = 0; m < 4; ++m) _Pragma("unroll") for (int k = 0; k < 2; ++k) dst[m][k] = *(const PG8_LAS bf16x8*)(lds + PG8_SA(b, h) + aoff + m * 2048 + k * 1024); } while (0)
; #define PG8_LDB(dst, b, h) do { _Pragma("unroll") for (int n = 0; n < 2; ++n) _Pragma("unroll") for (int k = 0; k < 2; ++k) dst[n][k] = *(const PG8_LAS bf16x8*)(lds + PG8_SB(b, h) + boff + n * 2048 + k * 1024); } while (0)
; #define PG8_MMA(ai, bj, At, Bt) do { __builtin_amdgcn_s_setprio(1); _Pragma("unroll") for (int m = 0; m < 4; ++m) _Pragma("unroll") for (int n = 0; n < 2; ++n) _Pragma("unroll") for (int k = 0; k < 2; ++k) \
;         acc[ai][bj][m][n] = __builtin_amdgcn_mfma_f32_16x16x32_bf16(Bt[n][k], At[m][k], acc[ai][bj][m][n], 0, 0, 0); __builtin_amdgcn_s_setprio(0); } while (0)
; #define PG8_WAIT_V(n) asm volatile("s_waitcnt vmcnt(" #n ")" ::: "memory")
; #define PG8_WAIT_L(n) asm volatile("s_waitcnt lgkmcnt(" #n ")" ::: "memory")
; #define PG8_BAR __builtin_amdgcn_s_barrier()
; #define PG8_SCHED __builtin_amdgcn_sched_barrier(0)
; template <class Epi, class Sched, bool ALIGN_EPI = false, bool SP2 = false>
; __device__ __forceinline__ void gemm_phase(PG8_LAS unsigned char* lds, const Gemm g, const Sched& S, const Epi& E) {
;     ...
;             PG8_WAIT_V(8); PG8_WAIT_L(0); PG8_BAR; PG8_MMA(1, 0, At, B0); PG8_MMA(1, 1, At, B1); PG8_BAR; PG8_SCHED;
;             PG8_LDB(B0, 1, 0); PG8_LDB(B1, 1, 1); PG8_SCHED; PG8_LDA(At, 1, 0); PG8_STAGE(PG8_SA(0, 1), a2 + hstep, voffA);
;             PG8_WAIT_V(8); PG8_WAIT_L(0); PG8_BAR; PG8_MMA(0, 0, At, B0); PG8_MMA(0, 1, At, B1); PG8_BAR; PG8_SCHED;
	s_setprio 1
	v_mfma_f32_16x16x32_bf16 v[60:63], v[144:147], v[190:193], v[60:63]
	v_mfma_f32_16x16x32_bf16 v[56:59], v[158:161], v[190:193], v[56:59]
	v_mfma_f32_16x16x32_bf16 v[44:47], v[144:147], v[198:201], v[44:47]
	v_mfma_f32_16x16x32_bf16 v[40:43], v[158:161], v[198:201], v[40:43]
	v_mfma_f32_16x16x32_bf16 v[28:31], v[144:147], v[206:209], v[28:31]
	v_mfma_f32_16x16x32_bf16 v[24:27], v[158:161], v[206:209], v[24:27]
	v_mfma_f32_16x16x32_bf16 v[12:15], v[144:147], v[214:217], v[12:15]
	v_mfma_f32_16x16x32_bf16 v[8:11], v[158:161], v[214:217], v[8:11]
	v_mfma_f32_16x16x32_bf16 v[60:63], v[154:157], v[194:197], v[60:63]
	v_mfma_f32_16x16x32_bf16 v[56:59], v[162:165], v[194:197], v[56:59]
	v_mfma_f32_16x16x32_bf16 v[44:47], v[154:157], v[202:205], v[44:47]
	v_mfma_f32_16x16x32_bf16 v[40:43], v[162:165], v[202:205], v[40:43]
	v_mfma_f32_16x16x32_bf16 v[28:31], v[154:157], v[210:213], v[28:31]
	v_mfma_f32_16x16x32_bf16 v[24:27], v[162:165], v[210:213], v[24:27]
	v_mfma_f32_16x16x32_bf16 v[12:15], v[154:157], v[218:221], v[12:15]
	v_mfma_f32_16x16x32_bf16 v[8:11], v[162:165], v[218:221], v[8:11]
	s_setprio 0
	s_setprio 1
	v_mfma_f32_16x16x32_bf16 v[52:55], v[166:169], v[190:193], v[52:55]
	v_mfma_f32_16x16x32_bf16 v[48:51], v[174:177], v[190:193], v[48:51]
	v_mfma_f32_16x16x32_bf16 v[36:39], v[166:169], v[198:201], v[36:39]
	v_mfma_f32_16x16x32_bf16 v[32:35], v[174:177], v[198:201], v[32:35]
	v_mfma_f32_16x16x32_bf16 v[20:23], v[166:169], v[206:209], v[20:23]
	v_mfma_f32_16x16x32_bf16 v[16:19], v[174:177], v[206:209], v[16:19]
	v_mfma_f32_16x16x32_bf16 v[4:7], v[166:169], v[214:217], v[4:7]
	v_mfma_f32_16x16x32_bf16 v[0:3], v[174:177], v[214:217], v[0:3]
	v_mfma_f32_16x16x32_bf16 v[52:55], v[170:173], v[194:197], v[52:55]
	v_mfma_f32_16x16x32_bf16 v[48:51], v[178:181], v[194:197], v[48:51]
	v_mfma_f32_16x16x32_bf16 v[36:39], v[170:173], v[202:205], v[36:39]
	v_mfma_f32_16x16x32_bf16 v[32:35], v[178:181], v[202:205], v[32:35]
	v_mfma_f32_16x16x32_bf16 v[20:23], v[170:173], v[210:213], v[20:23]
	v_mfma_f32_16x16x32_bf16 v[16:19], v[178:181], v[210:213], v[16:19]
	v_mfma_f32_16x16x32_bf16 v[4:7], v[170:173], v[218:221], v[4:7]
	v_mfma_f32_16x16x32_bf16 v[0:3], v[178:181], v[218:221], v[0:3]
	s_setprio 0
	s_barrier
	s_add_i32 s3, 0, 0x18000
	s_add_i32 s45, 0, 0x1c000
	v_add_u32_e32 v162, s3, v149
	v_add_u32_e32 v237, s3, v234
	v_add_u32_e32 v178, s45, v149
	v_add_u32_e32 v238, s45, v234
	ds_read_b128 v[144:147], v162
	ds_read_b128 v[154:157], v237
	ds_read_b128 v[158:161], v162 offset:2048
	ds_read_b128 v[162:165], v237 offset:2048
	ds_read_b128 v[166:169], v178
	ds_read_b128 v[170:173], v238
	ds_read_b128 v[174:177], v178 offset:2048
	ds_read_b128 v[178:181], v238 offset:2048
	s_add_u32 s0, s36, 0x40000
	s_addc_u32 s1, s37, 0
	s_mov_b32 m0, s49
	v_lshl_add_u64 v[230:231], s[0:1], 0, v[134:135]
	ds_read_b128 v[190:193], v153 offset:32768
	ds_read_b128 v[194:197], v233 offset:32768
	ds_read_b128 v[198:201], v153 offset:34816
	ds_read_b128 v[202:205], v233 offset:34816
	ds_read_b128 v[206:209], v153 offset:36864
	ds_read_b128 v[210:213], v233 offset:36864
	ds_read_b128 v[214:217], v153 offset:38912
	ds_read_b128 v[218:221], v233 offset:38912
	global_load_lds_dwordx4 v[230:231], off
	v_lshl_add_u64 v[230:231], s[0:1], 0, v[130:131]
	s_mov_b32 m0, s50
	s_nop 0
	global_load_lds_dwordx4 v[230:231], off
	s_waitcnt vmcnt(8)
	s_waitcnt lgkmcnt(0)
	s_barrier
	s_setprio 1
	v_mfma_f32_16x16x32_bf16 v[124:127], v[144:147], v[190:193], v[124:127]
	v_mfma_f32_16x16x32_bf16 v[120:123], v[158:161], v[190:193], v[120:123]
	v_mfma_f32_16x16x32_bf16 v[108:111], v[144:147], v[198:201], v[108:111]
	v_mfma_f32_16x16x32_bf16 v[104:107], v[158:161], v[198:201], v[104:107]
	v_mfma_f32_16x16x32_bf16 v[92:95], v[144:147], v[206:209], v[92:95]
	v_mfma_f32_16x16x32_bf16 v[88:91], v[158:161], v[206:209], v[88:91]
	v_mfma_f32_16x16x32_bf16 v[76:79], v[144:147], v[214:217], v[76:79]
	v_mfma_f32_16x16x32_bf16 v[72:75], v[158:161], v[214:217], v[72:75]
	v_mfma_f32_16x16x32_bf16 v[124:127], v[154:157], v[194:197], v[124:127]
	v_mfma_f32_16x16x32_bf16 v[120:123], v[162:165], v[194:197], v[120:123]
	v_mfma_f32_16x16x32_bf16 v[108:111], v[154:157], v[202:205], v[108:111]
	v_mfma_f32_16x16x32_bf16 v[104:107], v[162:165], v[202:205], v[104:107]
	v_mfma_f32_16x16x32_bf16 v[92:95], v[154:157], v[210:213], v[92:95]
	v_mfma_f32_16x16x32_bf16 v[88:91], v[162:165], v[210:213], v[88:91]
	v_mfma_f32_16x16x32_bf16 v[76:79], v[154:157], v[218:221], v[76:79]
	v_mfma_f32_16x16x32_bf16 v[72:75], v[162:165], v[218:221], v[72:75]
	s_setprio 0
	s_setprio 1
	v_mfma_f32_16x16x32_bf16 v[116:119], v[166:169], v[190:193], v[116:119]
	v_mfma_f32_16x16x32_bf16 v[112:115], v[174:177], v[190:193], v[112:115]
	v_mfma_f32_16x16x32_bf16 v[100:103], v[166:169], v[198:201], v[100:103]
	v_mfma_f32_16x16x32_bf16 v[96:99], v[174:177], v[198:201], v[96:99]
	v_mfma_f32_16x16x32_bf16 v[84:87], v[166:169], v[206:209], v[84:87]
	v_mfma_f32_16x16x32_bf16 v[80:83], v[174:177], v[206:209], v[80:83]
	v_mfma_f32_16x16x32_bf16 v[68:71], v[166:169], v[214:217], v[68:71]
	v_mfma_f32_16x16x32_bf16 v[64:67], v[174:177], v[214:217], v[64:67]
	v_mfma_f32_16x16x32_bf16 v[116:119], v[170:173], v[194:197], v[116:119]
	v_mfma_f32_16x16x32_bf16 v[112:115], v[178:181], v[194:197], v[112:115]
	v_mfma_f32_16x16x32_bf16 v[100:103], v[170:173], v[202:205], v[100:103]
	v_mfma_f32_16x16x32_bf16 v[96:99], v[178:181], v[202:205], v[96:99]
	v_mfma_f32_16x16x32_bf16 v[84:87], v[170:173], v[210:213], v[84:87]
	v_mfma_f32_16x16x32_bf16 v[80:83], v[178:181], v[210:213], v[80:83]
	v_mfma_f32_16x16x32_bf16 v[68:71], v[170:173], v[218:221], v[68:71]
	v_mfma_f32_16x16x32_bf16 v[64:67], v[178:181], v[218:221], v[64:67]
	s_setprio 0
	s_barrier
; #define PG8_STAGE(bufoff, gbase, voff) do { _Pragma("unroll") for (int _i = 0; _i < 2; ++_i) \
;         __builtin_amdgcn_global_load_lds((const unsigned*)((const char*)(gbase) + (voff)[_i]), (PG8_LAS unsigned*)(lds + (bufoff) + ldsw + _i * 8192), 16, 0, 0); } while (0)
; #define PG8_LDA(dst, b, h) do { _Pragma("unroll") for (int m = 0; m < 4; ++m) _Pragma("unroll") for (int k = 0; k < 2; ++k) dst[m][k] = *(const PG8_LAS bf16x8*)(lds + PG8_SA(b, h) + aoff + m * 2048 + k * 1024); } while (0)
; #define PG8_MMA(ai, bj, At, Bt) do { __builtin_amdgcn_s_setprio(1); _Pragma("unroll") for (int m = 0; m < 4; ++m) _Pragma("unroll") for (int n = 0; n < 2; ++n) _Pragma("unroll") for (int k = 0; k < 2; ++k) \
;         acc[ai][bj][m][n] = __builtin_amdgcn_mfma_f32_16x16x32_bf16(Bt[n][k], At[m][k], acc[ai][bj][m][n], 0, 0, 0); __builtin_amdgcn_s_setprio(0); } while (0)
; #define PG8_WAIT_V(n) asm volatile("s_waitcnt vmcnt(" #n ")" ::: "memory")
; #define PG8_WAIT_L(n) asm volatile("s_waitcnt lgkmcnt(" #n ")" ::: "memory")
; #define PG8_BAR __builtin_amdgcn_s_barrier()
; #define PG8_SCHED __builtin_amdgcn_sched_barrier(0)
; template <class Epi, class Sched, bool ALIGN_EPI = false, bool SP2 = false>
; __device__ __forceinline__ void gemm_phase(PG8_LAS unsigned char* lds, const Gemm g, const Sched& S, const Epi& E) {
;     ...
;             PG8_LDA(At, 1, 1); PG8_STAGE(PG8_SB(1, 0), b3, voffB); PG8_STAGE(PG8_SB(1, 1), b3 + hstep, voffB); PG8_STAGE(PG8_SA(1, 0), a3, voffA);
;             PG8_WAIT_V(8); PG8_WAIT_L(0); PG8_BAR; PG8_MMA(1, 0, At, B0); PG8_MMA(1, 1, At, B1); PG8_BAR; PG8_SCHED;
;     ...
;         if constexpr (ALIGN_EPI) { if (wr == 0) PG8_BAR; }
	s_add_i32 s0, s3, s42
	v_lshl_add_u64 v[222:223], v[222:223], 0, s[16:17]
	s_mov_b32 m0, s0
	ds_read_b128 v[190:193], v153 offset:49152
	ds_read_b128 v[194:197], v233 offset:49152
	ds_read_b128 v[198:201], v153 offset:51200
	ds_read_b128 v[202:205], v233 offset:51200
	ds_read_b128 v[206:209], v153 offset:53248
	ds_read_b128 v[210:213], v233 offset:53248
	ds_read_b128 v[214:217], v153 offset:55296
	ds_read_b128 v[218:221], v233 offset:55296
	global_load_lds_dwordx4 v[222:223], off
	s_add_i32 m0, s0, 0x2000
	s_add_u32 s0, s34, 0x40080
	v_lshl_add_u64 v[222:223], v[224:225], 0, s[16:17]
	s_addc_u32 s1, s35, 0
	s_add_i32 s3, s45, s42
	global_load_lds_dwordx4 v[222:223], off
	v_lshl_add_u64 v[222:223], s[0:1], 0, v[132:133]
	s_mov_b32 m0, s3
	s_nop 0
	global_load_lds_dwordx4 v[222:223], off
	v_lshl_add_u64 v[222:223], s[0:1], 0, v[128:129]
	s_add_i32 m0, s3, 0x2000
	s_nop 0
	global_load_lds_dwordx4 v[222:223], off
	v_lshl_add_u64 v[222:223], v[226:227], 0, s[16:17]
	s_mov_b32 m0, s52
	s_nop 0
	global_load_lds_dwordx4 v[222:223], off
	v_lshl_add_u64 v[222:223], v[228:229], 0, s[16:17]
	s_mov_b32 m0, s53
	s_nop 0
	global_load_lds_dwordx4 v[222:223], off
	s_waitcnt vmcnt(8)
	s_waitcnt lgkmcnt(0)
	s_barrier
	s_setprio 1
	v_mfma_f32_16x16x32_bf16 v[60:63], v[144:147], v[190:193], v[60:63]
	v_mfma_f32_16x16x32_bf16 v[56:59], v[158:161], v[190:193], v[56:59]
	v_mfma_f32_16x16x32_bf16 v[44:47], v[144:147], v[198:201], v[44:47]
	v_mfma_f32_16x16x32_bf16 v[40:43], v[158:161], v[198:201], v[40:43]
	v_mfma_f32_16x16x32_bf16 v[28:31], v[144:147], v[206:209], v[28:31]
	v_mfma_f32_16x16x32_bf16 v[24:27], v[158:161], v[206:209], v[24:27]
	v_mfma_f32_16x16x32_bf16 v[12:15], v[144:147], v[214:217], v[12:15]
	v_mfma_f32_16x16x32_bf16 v[8:11], v[158:161], v[214:217], v[8:11]
	v_mfma_f32_16x16x32_bf16 v[60:63], v[154:157], v[194:197], v[60:63]
	v_mfma_f32_16x16x32_bf16 v[56:59], v[162:165], v[194:197], v[56:59]
	v_mfma_f32_16x16x32_bf16 v[44:47], v[154:157], v[202:205], v[44:47]
	v_mfma_f32_16x16x32_bf16 v[40:43], v[162:165], v[202:205], v[40:43]
	v_mfma_f32_16x16x32_bf16 v[28:31], v[154:157], v[210:213], v[28:31]
	v_mfma_f32_16x16x32_bf16 v[24:27], v[162:165], v[210:213], v[24:27]
	v_mfma_f32_16x16x32_bf16 v[12:15], v[154:157], v[218:221], v[12:15]
	v_mfma_f32_16x16x32_bf16 v[8:11], v[162:165], v[218:221], v[8:11]
	s_setprio 0
	s_setprio 1
	v_mfma_f32_16x16x32_bf16 v[52:55], v[166:169], v[190:193], v[52:55]
	v_mfma_f32_16x16x32_bf16 v[48:51], v[174:177], v[190:193], v[48:51]
	v_mfma_f32_16x16x32_bf16 v[36:39], v[166:169], v[198:201], v[36:39]
	v_mfma_f32_16x16x32_bf16 v[32:35], v[174:177], v[198:201], v[32:35]
	v_mfma_f32_16x16x32_bf16 v[20:23], v[166:169], v[206:209], v[20:23]
	v_mfma_f32_16x16x32_bf16 v[16:19], v[174:177], v[206:209], v[16:19]
	v_mfma_f32_16x16x32_bf16 v[4:7], v[166:169], v[214:217], v[4:7]
	v_mfma_f32_16x16x32_bf16 v[0:3], v[174:177], v[214:217], v[0:3]
	v_mfma_f32_16x16x32_bf16 v[52:55], v[170:173], v[194:197], v[52:55]
	v_mfma_f32_16x16x32_bf16 v[48:51], v[178:181], v[194:197], v[48:51]
	v_mfma_f32_16x16x32_bf16 v[36:39], v[170:173], v[202:205], v[36:39]
	v_mfma_f32_16x16x32_bf16 v[32:35], v[178:181], v[202:205], v[32:35]
	v_mfma_f32_16x16x32_bf16 v[20:23], v[170:173], v[210:213], v[20:23]
	v_mfma_f32_16x16x32_bf16 v[16:19], v[178:181], v[210:213], v[16:19]
	v_mfma_f32_16x16x32_bf16 v[4:7], v[170:173], v[218:221], v[4:7]
	v_mfma_f32_16x16x32_bf16 v[0:3], v[178:181], v[218:221], v[0:3]
	s_setprio 0
	s_barrier
	s_add_i32 s64, s64, 2
	s_add_u32 s30, s30, 0x100
	s_addc_u32 s31, s31, 0
	s_add_u32 s62, s62, 0x100
	s_addc_u32 s63, s63, 0
	s_cmp_gt_u32 s64, 13
	s_cbranch_scc0 .LBB0_1118
	s_and_b64 vcc, exec, s[18:19]
	s_cbranch_vccz .LBB0_1121
	s_barrier

; #define PG8_STAGE(bufoff, gbase, voff) do { _Pragma("unroll") for (int _i = 0; _i < 2; ++_i) \
;         __builtin_amdgcn_global_load_lds((const unsigned*)((const char*)(gbase) + (voff)[_i]), (PG8_LAS unsigned*)(lds + (bufoff) + ldsw + _i * 8192), 16, 0, 0); } while (0)
; #define PG8_LDA(dst, b, h) do { _Pragma("unroll") for (int m = 0; m < 4; ++m) _Pragma("unroll") for (int k = 0; k < 2; ++k) dst[m][k] = *(const PG8_LAS bf16x8*)(lds + PG8_SA(b, h) + aoff + m * 2048 + k * 1024); } while (0)
; #define PG8_LDB(dst, b, h) do { _Pragma("unroll") for (int n = 0; n < 2; ++n) _Pragma("unroll") for (int k = 0; k < 2; ++k) dst[n][k] = *(const PG8_LAS bf16x8*)(lds + PG8_SB(b, h) + boff + n * 2048 + k * 1024); } while (0)
; #define PG8_MMA(ai, bj, At, Bt) do { __builtin_amdgcn_s_setprio(1); _Pragma("unroll") for (int m = 0; m < 4; ++m) _Pragma("unroll") for (int n = 0; n < 2; ++n) _Pragma("unroll") for (int k = 0; k < 2; ++k) \
;         acc[ai][bj][m][n] = __builtin_amdgcn_mfma_f32_16x16x32_bf16(Bt[n][k], At[m][k], acc[ai][bj][m][n], 0, 0, 0); __builtin_amdgcn_s_setprio(0); } while (0)
; #define PG8_WAIT_V(n) asm volatile("s_waitcnt vmcnt(" #n ")" ::: "memory")
; template <class Epi, class Sched, bool ALIGN_EPI = false, bool SP2 = false>
; __device__ __forceinline__ void gemm_phase(PG8_LAS unsigned char* lds, const Gemm g, const Sched& S, const Epi& E) {
;     ...
;         const char* nA = has_next ? (const char*)g.A + (size_t)nxt.pm * tstep : cA; const char* nB = has_next ? (const char*)g.Bt + (size_t)nxt.pn * tstep : cB;
;         for (int t = 0; t < nt; t += 2) {
;             const bool last = (t == nt - 2);
;             const char* a1 = cA + (size_t)(t + 1) * kstep;
;             const char* a2 = last ? nA : cA + (size_t)(t + 2) * kstep; const char* b2 = last ? nB : cB + (size_t)(t + 2) * kstep;
;             const char* a3 = a2 + kstep; const char* b3 = b2 + kstep;
;             if (last && has_next) S.a_ready(nxt);
;             if constexpr (SP2) {
;             PG8_LDB(B0, 0, 0); PG8_LDB(B1, 0, 1); PG8_SCHED; PG8_LDA(At, 0, 0); PG8_STAGE(PG8_SA(1, 1), a1 + hstep, voffA);
;             PG8_WAIT_V(8); PG8_WAIT_L(0); PG8_BAR; PG8_MMA(0, 0, At, B0); PG8_MMA(0, 1, At, B1); PG8_BAR; PG8_SCHED;
;             PG8_LDA(At, 0, 1); PG8_STAGE(PG8_SB(0, 0), b2, voffB); PG8_STAGE(PG8_SB(0, 1), b2 + hstep, voffB); PG8_STAGE(PG8_SA(0, 0), a2, voffA);
.LBB0_1209:
	ds_read_b128 v[150:153], v147
	ds_read_b128 v[154:157], v235
	ds_read_b128 v[158:161], v147 offset:2048
	ds_read_b128 v[162:165], v235 offset:2048
	ds_read_b128 v[166:169], v148
	ds_read_b128 v[170:173], v236
	ds_read_b128 v[174:177], v148 offset:2048
	ds_read_b128 v[178:181], v236 offset:2048
	s_add_u32 s30, s28, 0x100
	s_addc_u32 s31, s29, 0
	s_cmp_eq_u32 s68, 40
	s_cselect_b32 s37, s9, s31
	s_cselect_b32 s36, s8, s30
	s_cselect_b32 s35, s27, s67
	s_cselect_b32 s34, s26, s66
	v_lshl_add_u64 v[222:223], s[28:29], 0, v[136:137]
	s_add_i32 m0, s47, 0xc000
	ds_read_b128 v[190:193], v149
	ds_read_b128 v[194:197], v233
	ds_read_b128 v[198:201], v149 offset:2048
	ds_read_b128 v[202:205], v233 offset:2048
	ds_read_b128 v[206:209], v149 offset:4096
	ds_read_b128 v[210:213], v233 offset:4096
	ds_read_b128 v[214:217], v149 offset:6144
	ds_read_b128 v[218:221], v233 offset:6144
	global_load_lds_dwordx4 v[222:223], off
	v_lshl_add_u64 v[222:223], s[28:29], 0, v[138:139]
	s_add_i32 m0, s47, 0xe000
	s_nop 0
	global_load_lds_dwordx4 v[222:223], off
	s_waitcnt vmcnt(8)
	s_waitcnt lgkmcnt(0)
	s_barrier
	s_setprio 1
	v_mfma_f32_16x16x32_bf16 v[124:127], v[150:153], v[190:193], v[124:127]
	v_mfma_f32_16x16x32_bf16 v[120:123], v[158:161], v[190:193], v[120:123]
	v_mfma_f32_16x16x32_bf16 v[116:119], v[150:153], v[198:201], v[116:119]
	v_mfma_f32_16x16x32_bf16 v[112:115], v[158:161], v[198:201], v[112:115]
	v_mfma_f32_16x16x32_bf16 v[108:111], v[150:153], v[206:209], v[108:111]
	v_mfma_f32_16x16x32_bf16 v[104:107], v[158:161], v[206:209], v[104:107]
	v_mfma_f32_16x16x32_bf16 v[100:103], v[150:153], v[214:217], v[100:103]
	v_mfma_f32_16x16x32_bf16 v[96:99], v[158:161], v[214:217], v[96:99]
	v_mfma_f32_16x16x32_bf16 v[124:127], v[154:157], v[194:197], v[124:127]
	v_mfma_f32_16x16x32_bf16 v[120:123], v[162:165], v[194:197], v[120:123]
	v_mfma_f32_16x16x32_bf16 v[116:119], v[154:157], v[202:205], v[116:119]
	v_mfma_f32_16x16x32_bf16 v[112:115], v[162:165], v[202:205], v[112:115]
	v_mfma_f32_16x16x32_bf16 v[108:111], v[154:157], v[210:213], v[108:111]
	v_mfma_f32_16x16x32_bf16 v[104:107], v[162:165], v[210:213], v[104:107]
	v_mfma_f32_16x16x32_bf16 v[100:103], v[154:157], v[218:221], v[100:103]
	v_mfma_f32_16x16x32_bf16 v[96:99], v[162:165], v[218:221], v[96:99]
	s_setprio 0
	s_setprio 1
	v_mfma_f32_16x16x32_bf16 v[76:79], v[166:169], v[190:193], v[76:79]
	v_mfma_f32_16x16x32_bf16 v[68:71], v[174:177], v[190:193], v[68:71]
	v_mfma_f32_16x16x32_bf16 v[60:63], v[166:169], v[198:201], v[60:63]
	v_mfma_f32_16x16x32_bf16 v[52:55], v[174:177], v[198:201], v[52:55]
	v_mfma_f32_16x16x32_bf16 v[44:47], v[166:169], v[206:209], v[44:47]
	v_mfma_f32_16x16x32_bf16 v[40:43], v[174:177], v[206:209], v[40:43]
	v_mfma_f32_16x16x32_bf16 v[36:39], v[166:169], v[214:217], v[36:39]
	v_mfma_f32_16x16x32_bf16 v[32:35], v[174:177], v[214:217], v[32:35]
	v_mfma_f32_16x16x32_bf16 v[76:79], v[170:173], v[194:197], v[76:79]
	v_mfma_f32_16x16x32_bf16 v[68:71], v[178:181], v[194:197], v[68:71]
	v_mfma_f32_16x16x32_bf16 v[60:63], v[170:173], v[202:205], v[60:63]
	v_mfma_f32_16x16x32_bf16 v[52:55], v[178:181], v[202:205], v[52:55]
	v_mfma_f32_16x16x32_bf16 v[44:47], v[170:173], v[210:213], v[44:47]
	v_mfma_f32_16x16x32_bf16 v[40:43], v[178:181], v[210:213], v[40:43]
	v_mfma_f32_16x16x32_bf16 v[36:39], v[170:173], v[218:221], v[36:39]
	v_mfma_f32_16x16x32_bf16 v[32:35], v[178:181], v[218:221], v[32:35]
	s_setprio 0
	s_barrier
	s_add_i32 s0, s56, s43
	v_lshl_add_u64 v[222:223], s[34:35], 0, v[130:131]
	s_mov_b32 m0, s0
	ds_read_b128 v[190:193], v149 offset:16384
	ds_read_b128 v[194:197], v233 offset:16384
	ds_read_b128 v[198:201], v149 offset:18432
	ds_read_b128 v[202:205], v233 offset:18432
	ds_read_b128 v[206:209], v149 offset:20480
	ds_read_b128 v[210:213], v233 offset:20480
	ds_read_b128 v[214:217], v149 offset:22528
	ds_read_b128 v[218:221], v233 offset:22528
	global_load_lds_dwordx4 v[222:223], off
	s_add_i32 m0, s0, 0x2000
	s_add_u32 s0, s34, 0xb0000
	v_lshl_add_u64 v[224:225], s[34:35], 0, v[134:135]
	s_addc_u32 s1, s35, 0
	s_add_i32 s3, s57, s43
	global_load_lds_dwordx4 v[224:225], off
	v_lshl_add_u64 v[226:227], s[0:1], 0, v[130:131]
	s_mov_b32 m0, s3
	v_lshl_add_u64 v[228:229], s[36:37], 0, v[132:133]
	global_load_lds_dwordx4 v[226:227], off
	v_lshl_add_u64 v[226:227], s[0:1], 0, v[134:135]
	s_add_i32 m0, s3, 0x2000
	s_nop 0
	global_load_lds_dwordx4 v[226:227], off
	v_lshl_add_u64 v[226:227], s[36:37], 0, v[128:129]
	s_mov_b32 m0, s47
	s_nop 0
	global_load_lds_dwordx4 v[226:227], off
	s_mov_b32 m0, s48
	s_nop 0
	global_load_lds_dwordx4 v[228:229], off
	s_waitcnt vmcnt(8)
	s_waitcnt lgkmcnt(0)
	s_barrier
; #define PG8_STAGE(bufoff, gbase, voff) do { _Pragma("unroll") for (int _i = 0; _i < 2; ++_i) \
;         __builtin_amdgcn_global_load_lds((const unsigned*)((const char*)(gbase) + (voff)[_i]), (PG8_LAS unsigned*)(lds + (bufoff) + ldsw + _i * 8192), 16, 0, 0); } while (0)
; #define PG8_LDA(dst, b, h) do { _Pragma("unroll") for (int m = 0; m < 4; ++m) _Pragma("unroll") for (int k = 0; k < 2; ++k) dst[m][k] = *(const PG8_LAS bf16x8*)(lds + PG8_SA(b, h) + aoff + m * 2048 + k * 1024); } while (0)
; #define PG8_LDB(dst, b, h) do { _Pragma("unroll") for (int n = 0; n < 2; ++n) _Pragma("unroll") for (int k = 0; k < 2; ++k) dst[n][k] = *(const PG8_LAS bf16x8*)(lds + PG8_SB(b, h) + boff + n * 2048 + k * 1024); } while (0)
; #define PG8_MMA(ai, bj, At, Bt) do { __builtin_amdgcn_s_setprio(1); _Pragma("unroll") for (int m = 0; m < 4; ++m) _Pragma("unroll") for (int n = 0; n < 2; ++n) _Pragma("unroll") for (int k = 0; k < 2; ++k) \
;         acc[ai][bj][m][n] = __builtin_amdgcn_mfma_f32_16x16x32_bf16(Bt[n][k], At[m][k], acc[ai][bj][m][n], 0, 0, 0); __builtin_amdgcn_s_setprio(0); } while (0)
; #define PG8_WAIT_V(n) asm volatile("s_waitcnt vmcnt(" #n ")" ::: "memory")
; #define PG8_WAIT_L(n) asm volatile("s_waitcnt lgkmcnt(" #n ")" ::: "memory")
; #define PG8_BAR __builtin_amdgcn_s_barrier()
; #define PG8_SCHED __builtin_amdgcn_sched_barrier(0)
; template <class Epi, class Sched, bool ALIGN_EPI = false, bool SP2 = false>
; __device__ __forceinline__ void gemm_phase(PG8_LAS unsigned char* lds, const Gemm g, const Sched& S, const Epi& E) {
;     ...
;             PG8_WAIT_V(8); PG8_WAIT_L(0); PG8_BAR; PG8_MMA(1, 0, At, B0); PG8_MMA(1, 1, At, B1); PG8_BAR; PG8_SCHED;
;             PG8_LDB(B0, 1, 0); PG8_LDB(B1, 1, 1); PG8_SCHED; PG8_LDA(At, 1, 0); PG8_STAGE(PG8_SA(0, 1), a2 + hstep, voffA);
;             PG8_WAIT_V(8); PG8_WAIT_L(0); PG8_BAR; PG8_MMA(0, 0, At, B0); PG8_MMA(0, 1, At, B1); PG8_BAR; PG8_SCHED;
	s_setprio 1
	v_mfma_f32_16x16x32_bf16 v[92:95], v[150:153], v[190:193], v[92:95]
	v_mfma_f32_16x16x32_bf16 v[88:91], v[158:161], v[190:193], v[88:91]
	v_mfma_f32_16x16x32_bf16 v[84:87], v[150:153], v[198:201], v[84:87]
	v_mfma_f32_16x16x32_bf16 v[80:83], v[158:161], v[198:201], v[80:83]
	v_mfma_f32_16x16x32_bf16 v[72:75], v[150:153], v[206:209], v[72:75]
	v_mfma_f32_16x16x32_bf16 v[64:67], v[158:161], v[206:209], v[64:67]
	v_mfma_f32_16x16x32_bf16 v[56:59], v[150:153], v[214:217], v[56:59]
	v_mfma_f32_16x16x32_bf16 v[48:51], v[158:161], v[214:217], v[48:51]
	v_mfma_f32_16x16x32_bf16 v[92:95], v[154:157], v[194:197], v[92:95]
	v_mfma_f32_16x16x32_bf16 v[88:91], v[162:165], v[194:197], v[88:91]
	v_mfma_f32_16x16x32_bf16 v[84:87], v[154:157], v[202:205], v[84:87]
	v_mfma_f32_16x16x32_bf16 v[80:83], v[162:165], v[202:205], v[80:83]
	v_mfma_f32_16x16x32_bf16 v[72:75], v[154:157], v[210:213], v[72:75]
	v_mfma_f32_16x16x32_bf16 v[64:67], v[162:165], v[210:213], v[64:67]
	v_mfma_f32_16x16x32_bf16 v[56:59], v[154:157], v[218:221], v[56:59]
	v_mfma_f32_16x16x32_bf16 v[48:51], v[162:165], v[218:221], v[48:51]
	s_setprio 0
	s_setprio 1
	v_mfma_f32_16x16x32_bf16 v[28:31], v[166:169], v[190:193], v[28:31]
	v_mfma_f32_16x16x32_bf16 v[24:27], v[174:177], v[190:193], v[24:27]
	v_mfma_f32_16x16x32_bf16 v[20:23], v[166:169], v[198:201], v[20:23]
	v_mfma_f32_16x16x32_bf16 v[16:19], v[174:177], v[198:201], v[16:19]
	v_mfma_f32_16x16x32_bf16 v[12:15], v[166:169], v[206:209], v[12:15]
	v_mfma_f32_16x16x32_bf16 v[8:11], v[174:177], v[206:209], v[8:11]
	v_mfma_f32_16x16x32_bf16 v[4:7], v[166:169], v[214:217], v[4:7]
	v_mfma_f32_16x16x32_bf16 v[0:3], v[174:177], v[214:217], v[0:3]
	v_mfma_f32_16x16x32_bf16 v[28:31], v[170:173], v[194:197], v[28:31]
	v_mfma_f32_16x16x32_bf16 v[24:27], v[178:181], v[194:197], v[24:27]
	v_mfma_f32_16x16x32_bf16 v[20:23], v[170:173], v[202:205], v[20:23]
	v_mfma_f32_16x16x32_bf16 v[16:19], v[178:181], v[202:205], v[16:19]
	v_mfma_f32_16x16x32_bf16 v[12:15], v[170:173], v[210:213], v[12:15]
	v_mfma_f32_16x16x32_bf16 v[8:11], v[178:181], v[210:213], v[8:11]
	v_mfma_f32_16x16x32_bf16 v[4:7], v[170:173], v[218:221], v[4:7]
	v_mfma_f32_16x16x32_bf16 v[0:3], v[178:181], v[218:221], v[0:3]
	s_setprio 0
	s_barrier
	s_add_i32 s3, 0, 0x18000
	s_add_i32 s28, 0, 0x1c000
	v_add_u32_e32 v162, s3, v145
	v_add_u32_e32 v237, s3, v234
	v_add_u32_e32 v178, s28, v145
	v_add_u32_e32 v238, s28, v234
	ds_read_b128 v[150:153], v162
	ds_read_b128 v[154:157], v237
	ds_read_b128 v[158:161], v162 offset:2048
	ds_read_b128 v[162:165], v237 offset:2048
	ds_read_b128 v[166:169], v178
	ds_read_b128 v[170:173], v238
	ds_read_b128 v[174:177], v178 offset:2048
	ds_read_b128 v[178:181], v238 offset:2048
	s_add_u32 s0, s36, 0xb0000
	s_addc_u32 s1, s37, 0
	s_mov_b32 m0, s49
	v_lshl_add_u64 v[230:231], s[0:1], 0, v[128:129]
	ds_read_b128 v[190:193], v149 offset:32768
	ds_read_b128 v[194:197], v233 offset:32768
	ds_read_b128 v[198:201], v149 offset:34816
	ds_read_b128 v[202:205], v233 offset:34816
	ds_read_b128 v[206:209], v149 offset:36864
	ds_read_b128 v[210:213], v233 offset:36864
	ds_read_b128 v[214:217], v149 offset:38912
	ds_read_b128 v[218:221], v233 offset:38912
	global_load_lds_dwordx4 v[230:231], off
	v_lshl_add_u64 v[230:231], s[0:1], 0, v[132:133]
	s_mov_b32 m0, s50
	s_nop 0
	global_load_lds_dwordx4 v[230:231], off
	s_waitcnt vmcnt(8)
	s_waitcnt lgkmcnt(0)
	s_barrier
	s_setprio 1
	v_mfma_f32_16x16x32_bf16 v[124:127], v[150:153], v[190:193], v[124:127]
	v_mfma_f32_16x16x32_bf16 v[120:123], v[158:161], v[190:193], v[120:123]
	v_mfma_f32_16x16x32_bf16 v[116:119], v[150:153], v[198:201], v[116:119]
	v_mfma_f32_16x16x32_bf16 v[112:115], v[158:161], v[198:201], v[112:115]
	v_mfma_f32_16x16x32_bf16 v[108:111], v[150:153], v[206:209], v[108:111]
	v_mfma_f32_16x16x32_bf16 v[104:107], v[158:161], v[206:209], v[104:107]
	v_mfma_f32_16x16x32_bf16 v[100:103], v[150:153], v[214:217], v[100:103]
	v_mfma_f32_16x16x32_bf16 v[96:99], v[158:161], v[214:217], v[96:99]
	v_mfma_f32_16x16x32_bf16 v[124:127], v[154:157], v[194:197], v[124:127]
	v_mfma_f32_16x16x32_bf16 v[120:123], v[162:165], v[194:197], v[120:123]
	v_mfma_f32_16x16x32_bf16 v[116:119], v[154:157], v[202:205], v[116:119]
	v_mfma_f32_16x16x32_bf16 v[112:115], v[162:165], v[202:205], v[112:115]
	v_mfma_f32_16x16x32_bf16 v[108:111], v[154:157], v[210:213], v[108:111]
	v_mfma_f32_16x16x32_bf16 v[104:107], v[162:165], v[210:213], v[104:107]
	v_mfma_f32_16x16x32_bf16 v[100:103], v[154:157], v[218:221], v[100:103]
	v_mfma_f32_16x16x32_bf16 v[96:99], v[162:165], v[218:221], v[96:99]
	s_setprio 0
	s_setprio 1
	v_mfma_f32_16x16x32_bf16 v[76:79], v[166:169], v[190:193], v[76:79]
	v_mfma_f32_16x16x32_bf16 v[68:71], v[174:177], v[190:193], v[68:71]
	v_mfma_f32_16x16x32_bf16 v[60:63], v[166:169], v[198:201], v[60:63]
	v_mfma_f32_16x16x32_bf16 v[52:55], v[174:177], v[198:201], v[52:55]
	v_mfma_f32_16x16x32_bf16 v[44:47], v[166:169], v[206:209], v[44:47]
	v_mfma_f32_16x16x32_bf16 v[40:43], v[174:177], v[206:209], v[40:43]
	v_mfma_f32_16x16x32_bf16 v[36:39], v[166:169], v[214:217], v[36:39]
	v_mfma_f32_16x16x32_bf16 v[32:35], v[174:177], v[214:217], v[32:35]
	v_mfma_f32_16x16x32_bf16 v[76:79], v[170:173], v[194:197], v[76:79]
	v_mfma_f32_16x16x32_bf16 v[68:71], v[178:181], v[194:197], v[68:71]
	v_mfma_f32_16x16x32_bf16 v[60:63], v[170:173], v[202:205], v[60:63]
	v_mfma_f32_16x16x32_bf16 v[52:55], v[178:181], v[202:205], v[52:55]
	v_mfma_f32_16x16x32_bf16 v[44:47], v[170:173], v[210:213], v[44:47]
	v_mfma_f32_16x16x32_bf16 v[40:43], v[178:181], v[210:213], v[40:43]
	v_mfma_f32_16x16x32_bf16 v[36:39], v[170:173], v[218:221], v[36:39]
	v_mfma_f32_16x16x32_bf16 v[32:35], v[178:181], v[218:221], v[32:35]
	s_setprio 0
	s_barrier
; #define PG8_STAGE(bufoff, gbase, voff) do { _Pragma("unroll") for (int _i = 0; _i < 2; ++_i) \
;         __builtin_amdgcn_global_load_lds((const unsigned*)((const char*)(gbase) + (voff)[_i]), (PG8_LAS unsigned*)(lds + (bufoff) + ldsw + _i * 8192), 16, 0, 0); } while (0)
; #define PG8_LDA(dst, b, h) do { _Pragma("unroll") for (int m = 0; m < 4; ++m) _Pragma("unroll") for (int k = 0; k < 2; ++k) dst[m][k] = *(const PG8_LAS bf16x8*)(lds + PG8_SA(b, h) + aoff + m * 2048 + k * 1024); } while (0)
; #define PG8_MMA(ai, bj, At, Bt) do { __builtin_amdgcn_s_setprio(1); _Pragma("unroll") for (int m = 0; m < 4; ++m) _Pragma("unroll") for (int n = 0; n < 2; ++n) _Pragma("unroll") for (int k = 0; k < 2; ++k) \
;         acc[ai][bj][m][n] = __builtin_amdgcn_mfma_f32_16x16x32_bf16(Bt[n][k], At[m][k], acc[ai][bj][m][n], 0, 0, 0); __builtin_amdgcn_s_setprio(0); } while (0)
; #define PG8_WAIT_V(n) asm volatile("s_waitcnt vmcnt(" #n ")" ::: "memory")
; #define PG8_WAIT_L(n) asm volatile("s_waitcnt lgkmcnt(" #n ")" ::: "memory")
; #define PG8_BAR __builtin_amdgcn_s_barrier()
; #define PG8_SCHED __builtin_amdgcn_sched_barrier(0)
; template <class Epi, class Sched, bool ALIGN_EPI = false, bool SP2 = false>
; __device__ __forceinline__ void gemm_phase(PG8_LAS unsigned char* lds, const Gemm g, const Sched& S, const Epi& E) {
;     ...
;             PG8_LDA(At, 1, 1); PG8_STAGE(PG8_SB(1, 0), b3, voffB); PG8_STAGE(PG8_SB(1, 1), b3 + hstep, voffB); PG8_STAGE(PG8_SA(1, 0), a3, voffA);
;             PG8_WAIT_V(8); PG8_WAIT_L(0); PG8_BAR; PG8_MMA(1, 0, At, B0); PG8_MMA(1, 1, At, B1); PG8_BAR; PG8_SCHED;
;     ...
;         if constexpr (ALIGN_EPI) { if (wr == 0) PG8_BAR; }
	s_add_i32 s0, s3, s43
	v_lshl_add_u64 v[222:223], v[222:223], 0, s[14:15]
	s_mov_b32 m0, s0
	ds_read_b128 v[190:193], v149 offset:49152
	ds_read_b128 v[194:197], v233 offset:49152
	ds_read_b128 v[198:201], v149 offset:51200
	ds_read_b128 v[202:205], v233 offset:51200
	ds_read_b128 v[206:209], v149 offset:53248
	ds_read_b128 v[210:213], v233 offset:53248
	ds_read_b128 v[214:217], v149 offset:55296
	ds_read_b128 v[218:221], v233 offset:55296
	global_load_lds_dwordx4 v[222:223], off
	s_add_i32 m0, s0, 0x2000
	s_add_u32 s0, s34, 0xb0080
	v_lshl_add_u64 v[222:223], v[224:225], 0, s[14:15]
	s_addc_u32 s1, s35, 0
	s_add_i32 s3, s28, s43
	global_load_lds_dwordx4 v[222:223], off
	v_lshl_add_u64 v[222:223], s[0:1], 0, v[130:131]
	s_mov_b32 m0, s3
	s_nop 0
	global_load_lds_dwordx4 v[222:223], off
	v_lshl_add_u64 v[222:223], s[0:1], 0, v[134:135]
	s_add_i32 m0, s3, 0x2000
	s_nop 0
	global_load_lds_dwordx4 v[222:223], off
	v_lshl_add_u64 v[222:223], v[226:227], 0, s[14:15]
	s_mov_b32 m0, s52
	s_nop 0
	global_load_lds_dwordx4 v[222:223], off
	v_lshl_add_u64 v[222:223], v[228:229], 0, s[14:15]
	s_mov_b32 m0, s53
	s_nop 0
	global_load_lds_dwordx4 v[222:223], off
	s_waitcnt vmcnt(8)
	s_waitcnt lgkmcnt(0)
	s_barrier
	s_setprio 1
	v_mfma_f32_16x16x32_bf16 v[92:95], v[150:153], v[190:193], v[92:95]
	v_mfma_f32_16x16x32_bf16 v[88:91], v[158:161], v[190:193], v[88:91]
	v_mfma_f32_16x16x32_bf16 v[84:87], v[150:153], v[198:201], v[84:87]
	v_mfma_f32_16x16x32_bf16 v[80:83], v[158:161], v[198:201], v[80:83]
	v_mfma_f32_16x16x32_bf16 v[72:75], v[150:153], v[206:209], v[72:75]
	v_mfma_f32_16x16x32_bf16 v[64:67], v[158:161], v[206:209], v[64:67]
	v_mfma_f32_16x16x32_bf16 v[56:59], v[150:153], v[214:217], v[56:59]
	v_mfma_f32_16x16x32_bf16 v[48:51], v[158:161], v[214:217], v[48:51]
	v_mfma_f32_16x16x32_bf16 v[92:95], v[154:157], v[194:197], v[92:95]
	v_mfma_f32_16x16x32_bf16 v[88:91], v[162:165], v[194:197], v[88:91]
	v_mfma_f32_16x16x32_bf16 v[84:87], v[154:157], v[202:205], v[84:87]
	v_mfma_f32_16x16x32_bf16 v[80:83], v[162:165], v[202:205], v[80:83]
	v_mfma_f32_16x16x32_bf16 v[72:75], v[154:157], v[210:213], v[72:75]
	v_mfma_f32_16x16x32_bf16 v[64:67], v[162:165], v[210:213], v[64:67]
	v_mfma_f32_16x16x32_bf16 v[56:59], v[154:157], v[218:221], v[56:59]
	v_mfma_f32_16x16x32_bf16 v[48:51], v[162:165], v[218:221], v[48:51]
	s_setprio 0
	s_setprio 1
	v_mfma_f32_16x16x32_bf16 v[28:31], v[166:169], v[190:193], v[28:31]
	v_mfma_f32_16x16x32_bf16 v[24:27], v[174:177], v[190:193], v[24:27]
	v_mfma_f32_16x16x32_bf16 v[20:23], v[166:169], v[198:201], v[20:23]
	v_mfma_f32_16x16x32_bf16 v[16:19], v[174:177], v[198:201], v[16:19]
	v_mfma_f32_16x16x32_bf16 v[12:15], v[166:169], v[206:209], v[12:15]
	v_mfma_f32_16x16x32_bf16 v[8:11], v[174:177], v[206:209], v[8:11]
	v_mfma_f32_16x16x32_bf16 v[4:7], v[166:169], v[214:217], v[4:7]
	v_mfma_f32_16x16x32_bf16 v[0:3], v[174:177], v[214:217], v[0:3]
	v_mfma_f32_16x16x32_bf16 v[28:31], v[170:173], v[194:197], v[28:31]
	v_mfma_f32_16x16x32_bf16 v[24:27], v[178:181], v[194:197], v[24:27]
	v_mfma_f32_16x16x32_bf16 v[20:23], v[170:173], v[202:205], v[20:23]
	v_mfma_f32_16x16x32_bf16 v[16:19], v[178:181], v[202:205], v[16:19]
	v_mfma_f32_16x16x32_bf16 v[12:15], v[170:173], v[210:213], v[12:15]
	v_mfma_f32_16x16x32_bf16 v[8:11], v[178:181], v[210:213], v[8:11]
	v_mfma_f32_16x16x32_bf16 v[4:7], v[170:173], v[218:221], v[4:7]
	v_mfma_f32_16x16x32_bf16 v[0:3], v[178:181], v[218:221], v[0:3]
	s_setprio 0
	s_barrier
	s_add_i32 s68, s68, 2
	s_add_u32 s66, s66, 0x100
	s_addc_u32 s67, s67, 0
	s_cmp_gt_u32 s68, 41
	s_mov_b64 s[28:29], s[30:31]
	s_cbranch_scc0 .LBB0_1209
	s_and_b64 vcc, exec, s[16:17]
	s_cbranch_vccz .LBB0_1212
	s_barrier
